# full stack + L1-bypass (sc1) on outproj, merge and NSA streaming operand loads
# speedup vs baseline: 1.0174x; 1.0001x over previous
;   __device__ __forceinline__ half_t* u() const { return (half_t*)(ws() + OFF_u); }
;   __device__ __forceinline__ half_t* kcmp() const { return (half_t*)(ws() + OFF_kcmp); }
;   __device__ __forceinline__ half_t* vcmpT() const { return (half_t*)(ws() + OFF_vcmpT); }
; __device__ __forceinline__ float sigmoidf_(float x) { return 1.f / (1.f + __expf(-x)); }
; template <bool HASV>
; __device__ __forceinline__ void load_stage(StageRegs& r, const half_t* __restrict__ Kb, int ldk,
;                                            const half_t* __restrict__ VT, int ldv, int key0, int tid) {
;   const int row = tid >> 3, c = tid & 7;
;   r.k0 = *(const u32x4*)(Kb + (size_t)(key0 + row) * ldk + c * 8);
;   r.k1 = *(const u32x4*)(Kb + (size_t)(key0 + row + 32) * ldk + c * 8);
; __device__ __forceinline__ void nsa_item(const KP& p, int b, int g, int tile, char* smem) {
;     ...
;   const half_t* ub = p.u() + (size_t)b * SEQ * NU;
;   const half_t* urow = ub + (size_t)tj * NU;
;   h8 qf[4];
; #pragma unroll
;   for (int ks = 0; ks < 4; ++ks) {
;     qf[ks] = *(const h8*)(urow + C_CQ + head * 64 + 16 * ks + 8 * h);
; #pragma unroll
;     for (int e = 0; e < 8; ++e) qf[ks][e] = (half_t)((float)qf[ks][e] * 0.18033688f);
;   }
;   float gate[3];
; #pragma unroll
;   for (int i = 0; i < 3; ++i) gate[i] = sigmoidf_((float)urow[C_CG + head * 3 + i]);
;   f32x16 res[2];
; #pragma unroll
;   for (int dt = 0; dt < 2; ++dt)
; #pragma unroll
;     for (int r = 0; r < 16; ++r) res[dt][r] = 0.f;
;   for (int i = lane; i < 2080; i += 64) impA[i] = 0.f;
;   DState st;
;   auto nopost = [&](int, f32x16*) __attribute__((always_inline)) {};
;   {
;     const int nmax_j = (tj >= 31) ? ((tj - 31) >> 4) : -1;
;     const int bhi = (t0 >> 4) >> 6;
;     const half_t* Kc = p.kcmp() + (size_t)(b * 2 + g) * 512 * 64;
;     const half_t* Vc = p.vcmpT() + (size_t)(b * 2 + g) * 64 * 512;
;     auto pre = [&](int) __attribute__((always_inline)) { return 1; };
;     const int nmax_w = (tw0 >= 31) ? ((tw0 - 31) >> 4) : -1;
;     auto fullc = [&](int blk) __attribute__((always_inline)) { return blk * 64 + 63 <= nmax_w; };
;     auto vfn = [&](int n, int) __attribute__((always_inline)) { return n <= nmax_j; };
;     ds_reset(st);
;     run_dense<true, false, false>(st, Kc, 64, (const half_t*)nullptr, 0, 0, bhi, qf, pre, fullc, vfn, 0.f, 0.f, nopost, smem, tid);
.LBB0_1602:
	s_lshl_b32 s2, s8, 3
	v_mov_b32_e32 v19, v224
	s_andn2_b32 s2, s2, 31
	s_sub_i32 s31, 0x1fe0, s2
	v_ashrrev_i32_e32 v102, 6, v19
	v_lshl_add_u32 v190, v102, 3, s31
	v_bfe_u32 v100, v19, 2, 3
	v_and_b32_e32 v43, 3, v19
	v_or_b32_e32 v181, v190, v100
	v_or_b32_e32 v24, s92, v43
	v_mov_b64_e32 v[2:3], s[16:17]
	v_bfe_u32 v18, v19, 5, 1
	v_mad_i64_i32 v[176:177], s[2:3], v181, s5, v[2:3]
	v_lshlrev_b32_e32 v0, 7, v24
	v_lshl_add_u64 v[2:3], v[176:177], 0, v[0:1]
	v_lshlrev_b32_e32 v0, 4, v18
	v_lshl_add_u64 v[2:3], v[2:3], 0, v[0:1]
	v_mul_u32_u24_e32 v0, 3, v24
	v_add_co_u32_e32 v10, vcc, 0x1000, v2
	v_lshlrev_b32_e32 v0, 1, v0
	v_lshl_add_u64 v[14:15], v[2:3], 0, s[94:95]
	v_addc_co_u32_e32 v11, vcc, 0, v3, vcc
	v_lshl_add_u64 v[20:21], v[176:177], 0, v[0:1]
	s_mov_b64 s[2:3], 0x3950
	global_load_dwordx4 v[6:9], v[14:15], off offset:32 sc1
	global_load_dwordx4 v[2:5], v[14:15], off offset:64 sc1
	s_nop 0
	global_load_dwordx4 v[10:13], v[10:11], off sc1
	s_nop 0
	global_load_dwordx4 v[14:17], v[14:15], off offset:96 sc1
	v_lshl_add_u64 v[22:23], v[20:21], 0, s[2:3]
	v_add_co_u32_e32 v20, vcc, 0x3000, v20
	v_and_b32_e32 v101, 63, v19
	s_nop 0
	v_addc_co_u32_e32 v21, vcc, 0, v21, vcc
	global_load_dword v180, v[20:21], off offset:2384
	global_load_ushort v179, v[22:23], off offset:4
	s_movk_i32 s2, 0x2080
	v_mul_lo_u32 v103, v102, s2
	v_lshlrev_b32_e32 v104, 2, v101
	v_lshrrev_b32_e32 v20, 2, v19
	v_lshlrev_b32_e32 v178, 6, v24
	v_lshlrev_b32_e32 v50, 3, v18
	v_add3_u32 v0, v103, v104, s69
	v_or_b32_e32 v21, 0xffffffc0, v101
	s_mov_b64 s[2:3], 0
.LBB0_1603:
	v_add_u32_e32 v21, 64, v21
	s_movk_i32 s8, 0x7df
	v_cmp_lt_u32_e32 vcc, s8, v21
	ds_write_b32 v0, v1
	s_or_b64 s[2:3], vcc, s[2:3]
	v_add_u32_e32 v0, 0x100, v0
	s_andn2_b64 exec, exec, s[2:3]
	s_cbranch_execnz .LBB0_1603
	s_or_b64 exec, exec, s[2:3]
	s_waitcnt vmcnt(2)
	v_cvt_f32_f16_sdwa v23, v14 dst_sel:DWORD dst_unused:UNUSED_PAD src0_sel:WORD_1
	v_cvt_f32_f16_e32 v22, v14
	v_cvt_f32_f16_sdwa v25, v15 dst_sel:DWORD dst_unused:UNUSED_PAD src0_sel:WORD_1
	v_cvt_f32_f16_e32 v24, v15
	v_cvt_f32_f16_sdwa v15, v16 dst_sel:DWORD dst_unused:UNUSED_PAD src0_sel:WORD_1
	v_cvt_f32_f16_e32 v14, v16
	v_cvt_f32_f16_sdwa v27, v17 dst_sel:DWORD dst_unused:UNUSED_PAD src0_sel:WORD_1
	v_cvt_f32_f16_e32 v26, v17
	v_cvt_f32_f16_sdwa v17, v10 dst_sel:DWORD dst_unused:UNUSED_PAD src0_sel:WORD_1
	v_cvt_f32_f16_e32 v16, v10
	v_cvt_f32_f16_sdwa v29, v11 dst_sel:DWORD dst_unused:UNUSED_PAD src0_sel:WORD_1
	v_cvt_f32_f16_e32 v28, v11
	v_cvt_f32_f16_sdwa v11, v12 dst_sel:DWORD dst_unused:UNUSED_PAD src0_sel:WORD_1
	v_cvt_f32_f16_e32 v10, v12
	v_cvt_f32_f16_sdwa v31, v13 dst_sel:DWORD dst_unused:UNUSED_PAD src0_sel:WORD_1
	v_cvt_f32_f16_e32 v30, v13
	v_cvt_f32_f16_sdwa v13, v6 dst_sel:DWORD dst_unused:UNUSED_PAD src0_sel:WORD_1
	v_cvt_f32_f16_e32 v12, v6
	v_cvt_f32_f16_sdwa v33, v7 dst_sel:DWORD dst_unused:UNUSED_PAD src0_sel:WORD_1
	v_cvt_f32_f16_e32 v32, v7
	v_cvt_f32_f16_sdwa v7, v8 dst_sel:DWORD dst_unused:UNUSED_PAD src0_sel:WORD_1
	v_cvt_f32_f16_e32 v6, v8
	v_cvt_f32_f16_sdwa v35, v9 dst_sel:DWORD dst_unused:UNUSED_PAD src0_sel:WORD_1
	v_cvt_f32_f16_e32 v34, v9
	v_cvt_f32_f16_sdwa v9, v2 dst_sel:DWORD dst_unused:UNUSED_PAD src0_sel:WORD_1
	v_cvt_f32_f16_e32 v8, v2
	v_cvt_f32_f16_sdwa v37, v3 dst_sel:DWORD dst_unused:UNUSED_PAD src0_sel:WORD_1
	v_cvt_f32_f16_e32 v36, v3
	v_cvt_f32_f16_sdwa v3, v4 dst_sel:DWORD dst_unused:UNUSED_PAD src0_sel:WORD_1
	v_cvt_f32_f16_e32 v2, v4
	v_cvt_f32_f16_sdwa v39, v5 dst_sel:DWORD dst_unused:UNUSED_PAD src0_sel:WORD_1
	v_cvt_f32_f16_e32 v38, v5
	v_pk_mul_f32 v[4:5], v[22:23], s[62:63] op_sel_hi:[1,0]
	v_subrev_u32_e32 v0, 31, v181
	v_cvt_pk_f16_f32 v144, v4, v5
	v_pk_mul_f32 v[4:5], v[16:17], s[62:63] op_sel_hi:[1,0]
	v_pk_mul_f32 v[2:3], v[2:3], s[62:63] op_sel_hi:[1,0]
	v_cvt_pk_f16_f32 v148, v4, v5
	v_pk_mul_f32 v[4:5], v[28:29], s[62:63] op_sel_hi:[1,0]
	v_cmp_lt_i32_e32 vcc, 30, v181
	v_cvt_pk_f16_f32 v149, v4, v5
	v_pk_mul_f32 v[4:5], v[10:11], s[62:63] op_sel_hi:[1,0]
	v_ashrrev_i32_e32 v0, 4, v0
	v_ashrrev_i32_e32 v188, 3, v19
	v_cvt_pk_f16_f32 v150, v4, v5
	v_pk_mul_f32 v[4:5], v[30:31], s[62:63] op_sel_hi:[1,0]
	v_cvt_pk_f16_f32 v158, v2, v3
	v_pk_mul_f32 v[2:3], v[38:39], s[62:63] op_sel_hi:[1,0]
	v_cndmask_b32_e32 v105, -1, v0, vcc
	v_subrev_u32_e32 v0, 31, v190
	v_ashrrev_i32_e32 v189, 31, v188
	v_lshlrev_b32_e32 v51, 3, v19
	v_cvt_pk_f16_f32 v151, v4, v5
	v_pk_mul_f32 v[4:5], v[12:13], s[62:63] op_sel_hi:[1,0]
	v_cvt_pk_f16_f32 v159, v2, v3
	v_cmp_lt_i32_e32 vcc, 30, v190
	v_ashrrev_i32_e32 v0, 4, v0
	v_lshlrev_b64 v[2:3], 7, v[188:189]
	v_and_b32_e32 v42, 56, v51
	v_add_u32_e32 v84, 32, v188
	v_cvt_pk_f16_f32 v152, v4, v5
	v_pk_mul_f32 v[4:5], v[32:33], s[62:63] op_sel_hi:[1,0]
	v_cndmask_b32_e32 v106, -1, v0, vcc
	v_lshl_add_u64 v[2:3], s[18:19], 0, v[2:3]
	v_lshlrev_b32_e32 v0, 1, v42
	v_ashrrev_i32_e32 v85, 31, v84
	v_cvt_pk_f16_f32 v153, v4, v5
	v_pk_mul_f32 v[4:5], v[6:7], s[62:63] op_sel_hi:[1,0]
	v_lshl_add_u64 v[44:45], v[2:3], 0, v[0:1]
	v_lshlrev_b64 v[2:3], 7, v[84:85]
	v_cvt_pk_f16_f32 v154, v4, v5
	v_pk_mul_f32 v[4:5], v[34:35], s[62:63] op_sel_hi:[1,0]
	v_lshl_add_u64 v[2:3], s[18:19], 0, v[2:3]
	v_cvt_pk_f16_f32 v155, v4, v5
	v_pk_mul_f32 v[4:5], v[8:9], s[62:63] op_sel_hi:[1,0]
	v_lshl_add_u64 v[46:47], v[2:3], 0, v[0:1]
	v_cvt_pk_f16_f32 v156, v4, v5
	v_pk_mul_f32 v[4:5], v[36:37], s[62:63] op_sel_hi:[1,0]
	global_load_dwordx4 v[34:37], v[44:45], off sc1
	global_load_dwordx4 v[38:41], v[46:47], off sc1
	v_mul_lo_u32 v52, v188, s36
	v_add_u32_e32 v199, v52, v0
	v_lshl_add_u64 v[86:87], s[18:19], 0, v[0:1]
	v_and_b32_e32 v0, 31, v19
	v_mul_u32_u24_e32 v54, 0x48, v0
	v_or_b32_e32 v0, 32, v101
	v_pk_mul_f32 v[22:23], v[24:25], s[62:63] op_sel_hi:[1,0]
	v_pk_mul_f32 v[14:15], v[14:15], s[62:63] op_sel_hi:[1,0]
	v_pk_mul_f32 v[24:25], v[26:27], s[62:63] op_sel_hi:[1,0]
	v_and_b32_e32 v53, 8, v20
	v_mul_u32_u24_e32 v55, 0x48, v0
	v_cvt_pk_f16_f32 v145, v22, v23
	v_cvt_pk_f16_f32 v146, v14, v15
	v_cvt_pk_f16_f32 v147, v24, v25
	v_cvt_pk_f16_f32 v157, v4, v5
	s_lshr_b32 s14, s31, 10
	v_add_lshl_u32 v200, v54, v53, 1
	v_add_lshl_u32 v201, v55, v53, 1
	v_add_lshl_u32 v202, v50, v54, 1
	v_add_lshl_u32 v203, v55, v50, 1
	v_lshlrev_b32_e32 v198, 2, v18
	s_mov_b32 s15, 0
	v_mov_b32_e32 v107, 0xc61c4000
	v_mov_b32_e32 v56, 0
	s_mov_b32 s8, 63
; template <bool ONLINE, bool HASV, bool FAST, class VF> ...
;   const int h = lane >> 5, c = lane & 31;
;   f32x16 s[2];
; #pragma unroll
;   for (int kt = 0; kt < 2; ++kt) {
; #pragma unroll
;     for (int r = 0; r < 16; ++r) s[kt][r] = 0.f;
; #pragma unroll
;     for (int ks = 0; ks < 4; ++ks) {
;       const h8 a = *(const h8*)&Ks[(32 * kt + c) * 72 + 16 * ks + 8 * h];
;       s[kt] = __builtin_amdgcn_mfma_f32_32x32x16_f16(a, qf[ks], s[kt], 0, 0, 0);
;     }
;   }
;   float cm = NEGF;
; #pragma unroll
;   for (int kt = 0; kt < 2; ++kt)
; #pragma unroll
;     for (int r = 0; r < 16; ++r) {
;       const int key = key0 + 32 * kt + (r & 3) + 8 * (r >> 2) + 4 * h;
;       const float v = (FAST ? (flag != 0) : valid(key, flag)) ? s[kt][r] : NEGF;
;       s[kt][r] = v;
;       cm = fmaxf(cm, v);
;     }
;   float mnew;
;   if (ONLINE) {
;     cm = fmaxf(cm, __shfl_xor(cm, 32));
;     mnew = st.m;
;     if (__ballot(cm > st.m + 8.0f) != 0ull) {
; template <bool ONLINE, bool HASV, bool WANTP, class PRE, class FU, class VF, class PO> ...
;     ...
;   for (int blk = blk_lo; blk <= blk_hi; ++blk) {
;     __syncthreads();
;     write_stage<HASV>(sr, Ks, Vs, tid);
;     __syncthreads();
;     const int nb = blk < blk_hi ? blk + 1 : blk;
;     load_stage<HASV>(sr, Kb, ldk, VT, ldv, nb * 64, tid);
;     const int flag = pre(blk);
;     if (__ballot(flag != 0) != 0ull) {
.LBB0_1605:
	s_add_i32 s42, s15, 1
	s_cmp_lt_u32 s15, s14
	s_cselect_b32 s2, s42, s15
	v_lshl_add_u32 v2, s2, 6, v188
	v_ashrrev_i32_e32 v3, 31, v2
	v_lshlrev_b64 v[2:3], 7, v[2:3]
	v_lshl_add_u64 v[2:3], v[86:87], 0, v[2:3]
	v_add_co_u32_e32 v4, vcc, 0x1000, v2
	s_waitcnt lgkmcnt(0)
	s_barrier
	s_waitcnt vmcnt(1)
	ds_write_b128 v199, v[34:37]
	s_waitcnt vmcnt(0)
	ds_write_b128 v199, v[38:41] offset:4608
	s_waitcnt lgkmcnt(0)
	s_barrier
	v_addc_co_u32_e32 v5, vcc, 0, v3, vcc
	global_load_dwordx4 v[34:37], v[2:3], off sc1
	global_load_dwordx4 v[38:41], v[4:5], off sc1
	s_cmp_eq_u64 exec, 0
	s_cbranch_scc1 .LBB0_1611
	v_cmp_le_i32_e32 vcc, s8, v106
	v_add_f32_e32 v0, 0x41000000, v107
	s_and_saveexec_b64 s[2:3], vcc
	s_xor_b64 s[2:3], exec, s[2:3]
	s_cbranch_execz .LBB0_1608
	ds_read_b128 v[2:5], v200
	ds_read_b128 v[18:21], v200 offset:32
	v_and_b32_e32 v57, 64, v237
	v_xor_b32_e32 v49, 32, v237
	v_add_u32_e32 v57, 64, v57
	s_waitcnt lgkmcnt(1)
	v_mfma_f32_32x32x16_f16 v[2:17], v[2:5], v[148:151], 0
	v_cmp_lt_i32_e32 vcc, v49, v57
	s_nop 1
	v_cndmask_b32_e32 v49, v237, v49, vcc
	v_lshlrev_b32_e32 v49, 2, v49
	s_waitcnt lgkmcnt(0)
	v_mfma_f32_32x32x16_f16 v[2:17], v[18:21], v[152:155], v[2:17]
	ds_read_b128 v[18:21], v200 offset:64
	s_waitcnt lgkmcnt(0)
	v_mfma_f32_32x32x16_f16 v[2:17], v[18:21], v[156:159], v[2:17]
	ds_read_b128 v[18:21], v200 offset:96
	s_waitcnt lgkmcnt(0)
	v_mfma_f32_32x32x16_f16 v[2:17], v[18:21], v[144:147], v[2:17]
	ds_read_b128 v[18:21], v201
	ds_read_b128 v[58:61], v201 offset:32
	s_waitcnt lgkmcnt(1)
	v_mfma_f32_32x32x16_f16 v[18:33], v[18:21], v[148:151], 0
	s_nop 7
	v_max3_f32 v48, v2, s74, v3
	v_max3_f32 v48, v48, v4, v5
	v_max3_f32 v48, v48, v6, v7
	v_max3_f32 v48, v48, v8, v9
	v_max3_f32 v48, v48, v10, v11
	v_max3_f32 v48, v48, v12, v13
	v_max3_f32 v48, v48, v14, v15
	s_waitcnt lgkmcnt(0)
	v_mfma_f32_32x32x16_f16 v[18:33], v[58:61], v[152:155], v[18:33]
	ds_read_b128 v[58:61], v201 offset:64
	v_max3_f32 v48, v48, v16, v17
	s_waitcnt lgkmcnt(0)
	v_mfma_f32_32x32x16_f16 v[18:33], v[58:61], v[156:159], v[18:33]
	ds_read_b128 v[58:61], v201 offset:96
	s_waitcnt lgkmcnt(0)
	v_mfma_f32_32x32x16_f16 v[18:33], v[58:61], v[144:147], v[18:33]
	s_nop 11
	v_max3_f32 v48, v48, v18, v19
	v_max3_f32 v48, v48, v20, v21
	v_max3_f32 v48, v48, v22, v23
	v_max3_f32 v48, v48, v24, v25
	v_max3_f32 v48, v48, v26, v27
	v_max3_f32 v48, v48, v28, v29
	v_max3_f32 v48, v48, v30, v31
	v_max3_f32 v48, v48, v32, v33
	ds_bpermute_b32 v49, v49, v48
	s_waitcnt lgkmcnt(0)
	v_max_f32_e32 v49, v49, v49
	v_max_f32_e32 v57, v48, v49
	v_cmp_gt_f32_e64 s[40:41], v57, v0

; __device__ __forceinline__ void nsa_item(const KP& p, int b, int g, int tile, char* smem) {
;     ...
;     float lt = st.l;
;     lt += __shfl_xor(lt, 32);
;     const float mfix = st.m;
;     const float invl = lt > 0.f ? 1.f / lt : 0.f;
;     ds_reset(st);
;     auto post = [&](int n0, f32x16* pp) __attribute__((always_inline)) {
; #pragma unroll
;       for (int kt = 0; kt < 2; ++kt)
; #pragma unroll
;         for (int qd = 0; qd < 4; ++qd) {
;           float a = pp[kt][4 * qd] + pp[kt][4 * qd + 1] + pp[kt][4 * qd + 2] + pp[kt][4 * qd + 3];
;           float bb = pp[kt][4 * qd + 3];
;           a += dpp_quad<0xB1>(a); a += dpp_quad<0x4E>(a);
;           bb += dpp_quad<0xB1>(bb); bb += dpp_quad<0x4E>(bb);
;           if (r4 == 0) {
;             const int sblk = (n0 >> 2) + 8 * kt + 2 * qd + h;
;             impA[j * 128 + sblk] = a;
;             impB[j * 132 + sblk + 1] = bb;
;           }
;         }
;     };
;     run_dense<false, true, true>(st, Kc, 64, Vc, 512, 0, bhi, qf, pre, fullc, vfn, mfix, invl, post, smem, tid);
.LBB0_1613:
	v_lshlrev_b64 v[10:11], 10, v[188:189]
	v_lshl_add_u64 v[10:11], s[50:51], 0, v[10:11]
	v_lshlrev_b32_e32 v0, 1, v42
	v_lshl_add_u64 v[14:15], v[10:11], 0, v[0:1]
	v_lshlrev_b64 v[10:11], 10, v[84:85]
	v_lshl_add_u64 v[10:11], s[50:51], 0, v[10:11]
	global_load_dwordx4 v[2:5], v[44:45], off sc1
	global_load_dwordx4 v[6:9], v[46:47], off sc1
	v_lshl_add_u64 v[88:89], v[10:11], 0, v[0:1]
	global_load_dwordx4 v[80:83], v[14:15], off sc1
	global_load_dwordx4 v[10:13], v[88:89], off sc1
	v_and_b32_e32 v17, 64, v237
	v_xor_b32_e32 v16, 32, v237
	v_add_u32_e32 v17, 64, v17
	v_cmp_lt_i32_e32 vcc, v16, v17
	v_mov_b32_e32 v30, v1
	v_mov_b32_e32 v31, v1
	v_cndmask_b32_e32 v16, v237, v16, vcc
	v_lshlrev_b32_e32 v204, 2, v16
	ds_bpermute_b32 v16, v204, v56
	v_mov_b32_e32 v22, v1
	v_mov_b32_e32 v23, v1
	v_mov_b32_e32 v24, v1
	v_mov_b32_e32 v25, v1
	s_waitcnt lgkmcnt(0)
	v_add_f32_e32 v16, v56, v16
	v_div_scale_f32 v17, s[2:3], v16, v16, 1.0
	v_rcp_f32_e32 v18, v17
	s_movk_i32 s2, 0x210
	v_mov_b32_e32 v26, v1
	v_mov_b32_e32 v27, v1
	v_fma_f32 v19, -v17, v18, 1.0
	v_fmac_f32_e32 v18, v19, v18
	v_div_scale_f32 v19, vcc, 1.0, v16, 1.0
	v_mul_f32_e32 v20, v19, v18
	v_fma_f32 v21, -v17, v20, v19
	v_fmac_f32_e32 v20, v21, v18
	v_fma_f32 v17, -v17, v20, v19
	v_div_fmas_f32 v17, v17, v18, v20
	v_div_fixup_f32 v17, v17, v16, 1.0
	v_cmp_lt_f32_e32 vcc, 0, v16
	v_and_b32_e32 v16, 48, v51
	v_lshlrev_b32_e32 v16, 1, v16
	v_cndmask_b32_e32 v90, 0, v17, vcc
	v_and_b32_e32 v17, 8, v51
	v_add3_u32 v108, v52, v16, v17
	v_lshlrev_b32_e32 v16, 1, v53
	v_lshlrev_b32_e32 v17, 1, v54
	v_lshlrev_b32_e32 v18, 1, v55
	v_add_u32_e32 v205, v16, v17
	v_add_u32_e32 v206, v16, v18
	v_lshlrev_b32_e32 v16, 1, v50
	v_add_u32_e32 v207, v16, v17
	v_add_u32_e32 v208, v16, v18
	v_mad_u32_u24 v16, v100, s2, v103
	s_movk_i32 s2, 0x5804
	v_add3_u32 v109, v16, v198, s2
	v_lshl_add_u32 v16, v100, 9, v103
	v_add3_u32 v110, v16, v198, s69
	v_mov_b32_e32 v16, v1
	v_mov_b32_e32 v17, v1
	v_mov_b32_e32 v18, v1
	v_mov_b32_e32 v19, v1
	v_mov_b32_e32 v20, v1
	v_mov_b32_e32 v21, v1
	v_mov_b32_e32 v28, v1
	v_mov_b32_e32 v29, v1
	v_mov_b64_e32 v[62:63], v[30:31]
	s_mov_b32 s15, 0
	v_cmp_eq_u32_e64 s[38:39], 0, v43
	v_mov_b32_e32 v91, v90
	v_mov_b64_e32 v[60:61], v[28:29]
	v_mov_b64_e32 v[58:59], v[26:27]
	v_mov_b64_e32 v[56:57], v[24:25]
	v_mov_b64_e32 v[54:55], v[22:23]
	v_mov_b64_e32 v[52:53], v[20:21]
	v_mov_b64_e32 v[50:51], v[18:19]
	v_mov_b64_e32 v[48:49], v[16:17]
	s_mov_b32 s42, 0
; template <bool ONLINE, bool HASV, bool FAST, class VF> ...
;     ...
;   float ps = 0.f;
; #pragma unroll
;   for (int kt = 0; kt < 2; ++kt)
; #pragma unroll
;     for (int r = 0; r < 16; ++r) {
;       float e = __builtin_amdgcn_exp2f(s[kt][r] - mnew);
;       if (!ONLINE) e *= fixed_invl;
;       s[kt][r] = e;
;       ps += e;
;     }
;   st.l += ps;
;   if (pout) { pout[0] = s[0]; pout[1] = s[1]; }
;   if (HASV) {
; #pragma unroll
;     for (int ks = 0; ks < 4; ++ks) {
;       h8 pf;
; #pragma unroll
;       for (int jj = 0; jj < 8; ++jj) pf[jj] = (half_t)s[ks >> 1][8 * (ks & 1) + jj];
; #pragma unroll
;       for (int dt = 0; dt < 2; ++dt) {
;         const h8 vf = *(const h8*)&Vs[(32 * dt + c) * 72 + 16 * ks + 8 * h];
;         st.o[dt] = __builtin_amdgcn_mfma_f32_32x32x16_f16(vf, pf, st.o[dt], 0, 0, 0);
;       }
;     }
;   }
; template <bool ONLINE, bool HASV, bool WANTP, class PRE, class FU, class VF, class PO> ...
;     ...
;   for (int blk = blk_lo; blk <= blk_hi; ++blk) {
;     __syncthreads();
;     write_stage<HASV>(sr, Ks, Vs, tid);
;     __syncthreads();
;     const int nb = blk < blk_hi ? blk + 1 : blk;
;     load_stage<HASV>(sr, Kb, ldk, VT, ldv, nb * 64, tid);
;     const int flag = pre(blk);
;     if (__ballot(flag != 0) != 0ull) {
;       f32x16 pp[2];
;       if (full(blk))
;         dense_block<ONLINE, HASV, true>(st, Ks, Vs, qf, blk * 64, flag, valid, fixed_m, fixed_invl,
;                                         WANTP ? pp : (f32x16*)nullptr, lane);
;       else
;         dense_block<ONLINE, HASV, false>(st, Ks, Vs, qf, blk * 64, flag, valid, fixed_m, fixed_invl,
;                                          WANTP ? pp : (f32x16*)nullptr, lane);
;       if (WANTP) post(blk * 64, pp);
.LBB0_1614:
	s_add_i32 s43, s42, 1
	s_cmp_lt_u32 s42, s14
	s_cselect_b32 s2, s43, s42
	s_lshl_b32 s8, s2, 6
	s_barrier
	s_waitcnt vmcnt(3)
	ds_write_b128 v199, v[2:5]
	s_waitcnt vmcnt(2)
	ds_write_b128 v199, v[6:9] offset:4608
	v_add_u32_e32 v2, s8, v188
	v_ashrrev_i32_e32 v3, 31, v2
	v_lshlrev_b64 v[2:3], 7, v[2:3]
	v_lshl_add_u64 v[2:3], v[86:87], 0, v[2:3]
	v_add_u32_e32 v210, 0x3000, v108
	v_add_co_u32_e32 v6, vcc, 0x1000, v2
	s_lshl_b64 s[2:3], s[8:9], 1
	v_add_u32_e32 v209, 0x2000, v108
	s_waitcnt vmcnt(0)
	ds_write2_b64 v210, v[10:11], v[12:13] offset0:192 offset1:194
	v_addc_co_u32_e32 v7, vcc, 0, v3, vcc
	v_lshl_add_u64 v[10:11], v[14:15], 0, s[2:3]
	v_lshl_add_u64 v[12:13], v[88:89], 0, s[2:3]
	ds_write2_b64 v209, v[80:81], v[82:83] offset0:128 offset1:130
	s_waitcnt lgkmcnt(0)
	s_barrier
	global_load_dwordx4 v[2:5], v[2:3], off sc1
	s_nop 0
	global_load_dwordx4 v[6:9], v[6:7], off sc1
	s_nop 0
	global_load_dwordx4 v[80:83], v[10:11], off sc1
	s_nop 0
	global_load_dwordx4 v[10:13], v[12:13], off sc1
	s_cmp_eq_u64 exec, 0
	s_cbranch_scc1 .LBB0_1636
	s_add_i32 s2, s15, 63
	v_cmp_le_i32_e32 vcc, s2, v106
	s_and_saveexec_b64 s[2:3], vcc
	s_xor_b64 s[40:41], exec, s[2:3]
	s_cbranch_execz .LBB0_1617
	ds_read_b128 v[32:35], v200
	ds_read_b128 v[36:39], v200 offset:32
	s_waitcnt lgkmcnt(1)
	v_mfma_f32_32x32x16_f16 v[64:79], v[32:35], v[148:151], 0
	ds_read_b128 v[32:35], v200 offset:64
	s_waitcnt lgkmcnt(1)
	v_mfma_f32_32x32x16_f16 v[64:79], v[36:39], v[152:155], v[64:79]
	s_waitcnt lgkmcnt(0)
	v_mfma_f32_32x32x16_f16 v[64:79], v[32:35], v[156:159], v[64:79]
	ds_read_b128 v[32:35], v200 offset:96
	s_waitcnt lgkmcnt(0)
	v_mfma_f32_32x32x16_f16 v[64:79], v[32:35], v[144:147], v[64:79]
	ds_read_b128 v[32:35], v201
	ds_read_b128 v[92:95], v201 offset:32
	s_waitcnt lgkmcnt(1)
	v_mfma_f32_32x32x16_f16 v[32:47], v[32:35], v[148:151], 0
	s_nop 7
	v_sub_f32_e32 v64, v64, v107
	v_exp_f32_e32 v122, v64
	v_sub_f32_e32 v64, v65, v107
	v_exp_f32_e32 v116, v64
	v_sub_f32_e32 v64, v66, v107
	v_sub_f32_e32 v66, v73, v107
	v_exp_f32_e32 v98, v66
	s_waitcnt lgkmcnt(0)
	v_mfma_f32_32x32x16_f16 v[32:47], v[92:95], v[152:155], v[32:47]
	ds_read_b128 v[92:95], v201 offset:64
	v_sub_f32_e32 v66, v74, v107
	v_exp_f32_e32 v99, v66
	v_sub_f32_e32 v66, v75, v107
	v_exp_f32_e32 v117, v64
	v_sub_f32_e32 v64, v67, v107
	v_exp_f32_e32 v118, v64
	s_waitcnt lgkmcnt(0)
	v_mfma_f32_32x32x16_f16 v[32:47], v[92:95], v[156:159], v[32:47]
	ds_read_b128 v[92:95], v201 offset:96
	v_sub_f32_e32 v64, v68, v107
	v_exp_f32_e32 v119, v64
	v_sub_f32_e32 v64, v69, v107
	v_exp_f32_e32 v120, v64
	v_sub_f32_e32 v64, v70, v107
	v_exp_f32_e32 v121, v64
	s_waitcnt lgkmcnt(0)
	v_mfma_f32_32x32x16_f16 v[32:47], v[92:95], v[144:147], v[32:47]
	v_exp_f32_e32 v92, v66
	v_sub_f32_e32 v66, v76, v107
	v_exp_f32_e32 v93, v66
	v_sub_f32_e32 v66, v77, v107
	v_exp_f32_e32 v76, v66
	v_sub_f32_e32 v66, v78, v107
	v_exp_f32_e32 v77, v66
	s_nop 4
	v_sub_f32_e32 v32, v32, v107
	v_sub_f32_e32 v66, v79, v107
	v_exp_f32_e32 v78, v32
	v_sub_f32_e32 v32, v33, v107
	v_exp_f32_e32 v79, v66
	v_exp_f32_e32 v66, v32
	v_sub_f32_e32 v32, v34, v107
	v_exp_f32_e32 v67, v32
	v_sub_f32_e32 v32, v35, v107
	v_exp_f32_e32 v68, v32
	v_sub_f32_e32 v32, v36, v107
	v_exp_f32_e32 v69, v32
	v_sub_f32_e32 v32, v37, v107
	v_exp_f32_e32 v70, v32
	v_sub_f32_e32 v32, v38, v107
	v_sub_f32_e32 v64, v71, v107
	v_exp_f32_e32 v71, v32
	v_sub_f32_e32 v32, v39, v107
	v_sub_f32_e32 v33, v40, v107
	v_exp_f32_e32 v32, v32
	v_exp_f32_e32 v33, v33
	v_sub_f32_e32 v65, v72, v107
	v_exp_f32_e32 v64, v64
	v_exp_f32_e32 v65, v65
	v_pk_mul_f32 v[36:37], v[90:91], v[32:33]
	v_sub_f32_e32 v32, v41, v107
	v_exp_f32_e32 v72, v32
	v_sub_f32_e32 v32, v42, v107
	v_exp_f32_e32 v73, v32
	v_sub_f32_e32 v32, v43, v107
	v_pk_mul_f32 v[64:65], v[90:91], v[64:65]
	v_exp_f32_e32 v94, v32
	v_sub_f32_e32 v32, v44, v107
	v_exp_f32_e32 v95, v32
	v_sub_f32_e32 v32, v45, v107
	v_cvt_f16_f32_e32 v44, v64
	v_exp_f32_e32 v96, v32
	v_sub_f32_e32 v32, v46, v107
	v_exp_f32_e32 v97, v32
	v_sub_f32_e32 v32, v47, v107
	v_pk_mul_f32 v[42:43], v[90:91], v[116:117]
	v_pk_mul_f32 v[38:39], v[90:91], v[118:119]
	v_pk_mul_f32 v[40:41], v[90:91], v[120:121]
	v_exp_f32_e32 v115, v32
	v_fma_mixlo_f16 v32, v90, v122, 0
	v_cvt_pk_f16_f32 v33, v42, v43
	v_cvt_pk_f16_f32 v34, v38, v39
	v_cvt_pk_f16_f32 v35, v40, v41
	v_pack_b32_f16 v32, v32, v33
	v_alignbit_b32 v33, v34, v33, 16
	v_alignbit_b32 v34, v35, v34, 16
	v_alignbit_b32 v35, v44, v35, 16
	ds_read_b128 v[44:47], v200 offset:9216
	v_pk_mul_f32 v[74:75], v[90:91], v[98:99]
	s_waitcnt lgkmcnt(0)
	v_mfma_f32_32x32x16_f16 v[48:63], v[44:47], v[32:35], v[48:63]
	ds_read_b128 v[44:47], v201 offset:9216
	v_mul_f32_e32 v113, v90, v122
	ds_read_b128 v[116:119], v205 offset:9248
	ds_read_b128 v[120:123], v205 offset:9280
	v_mul_f32_e32 v111, v90, v79
	v_mul_f32_e32 v114, v90, v78
	v_mul_f32_e32 v112, v90, v115
	s_waitcnt lgkmcnt(2)
	v_mfma_f32_32x32x16_f16 v[16:31], v[44:47], v[32:35], v[16:31]
	v_cvt_f16_f32_e32 v32, v65
	v_cvt_pk_f16_f32 v34, v74, v75
	v_pack_b32_f16 v44, v32, v34
	v_mul_f32_e64 v32, v90, v92
	v_mul_f32_e64 v33, v91, v93
	v_pk_mul_f32 v[92:93], v[90:91], v[66:67]
	v_cvt_pk_f16_f32 v46, v32, v33
	v_alignbit_b32 v45, v46, v34, 16
	v_pk_mul_f32 v[34:35], v[90:91], v[76:77]
	v_cvt_f16_f32_e32 v66, v36
	v_cvt_pk_f16_f32 v47, v34, v35
	v_alignbit_b32 v46, v47, v46, 16
	v_lshrrev_b32_e32 v47, 16, v47
	v_fma_mixhi_f16 v47, v90, v79, 0
	v_pk_mul_f32 v[76:77], v[90:91], v[68:69]
	s_waitcnt lgkmcnt(1)
	v_mfma_f32_32x32x16_f16 v[48:63], v[116:119], v[44:47], v[48:63]
	ds_read_b128 v[116:119], v206 offset:9248
	ds_read_b128 v[124:127], v206 offset:9280
	s_waitcnt lgkmcnt(1)
	v_mfma_f32_32x32x16_f16 v[16:31], v[116:119], v[44:47], v[16:31]
	v_fma_mixlo_f16 v44, v90, v78, 0
	v_mul_f32_e64 v78, v90, v70
	v_mul_f32_e64 v79, v91, v71
	v_cvt_pk_f16_f32 v45, v92, v93
	v_cvt_pk_f16_f32 v46, v76, v77
	v_cvt_pk_f16_f32 v47, v78, v79
	v_pack_b32_f16 v44, v44, v45
	v_alignbit_b32 v45, v46, v45, 16
	v_alignbit_b32 v46, v47, v46, 16
	v_alignbit_b32 v47, v66, v47, 16
	v_pk_mul_f32 v[66:67], v[90:91], v[72:73]
	s_nop 0
	v_mfma_f32_32x32x16_f16 v[48:63], v[120:123], v[44:47], v[48:63]
	s_waitcnt lgkmcnt(0)
	v_mfma_f32_32x32x16_f16 v[16:31], v[124:127], v[44:47], v[16:31]
	v_cvt_f16_f32_e32 v44, v37
	v_cvt_pk_f16_f32 v46, v66, v67
	v_pack_b32_f16 v68, v44, v46
	v_mul_f32_e64 v44, v90, v94
	v_mul_f32_e64 v45, v91, v95
	v_cvt_pk_f16_f32 v70, v44, v45
	v_alignbit_b32 v69, v70, v46, 16
	v_pk_mul_f32 v[46:47], v[90:91], v[96:97]
	ds_read_b128 v[94:97], v205 offset:9312
	v_cvt_pk_f16_f32 v71, v46, v47
	v_alignbit_b32 v70, v71, v70, 16
	v_lshrrev_b32_e32 v71, 16, v71
	v_fma_mixhi_f16 v71, v90, v115, 0
	s_waitcnt lgkmcnt(0)
	s_nop 0
	v_mfma_f32_32x32x16_f16 v[48:63], v[94:97], v[68:71], v[48:63]
	ds_read_b128 v[94:97], v206 offset:9312
	s_waitcnt lgkmcnt(0)
	v_mfma_f32_32x32x16_f16 v[16:31], v[94:97], v[68:71], v[16:31]

;   __device__ __forceinline__ half_t* vsT() const { return (half_t*)(ws() + OFF_vsT); }
; __device__ __forceinline__ void nsa_item(const KP& p, int b, int g, int tile, char* smem) {
;     ...
;   const unsigned long long mylo = msk[j * 2], myhi = msk[j * 2 + 1];
;   {
;     const half_t* Ksel = ub + C_CKS + g * 64;
;     const half_t* Vsel = p.vsT() + (size_t)(b * 2 + g) * 64 * SEQ;
;     auto pre = [&](int blk) __attribute__((always_inline)) {
;       const unsigned long long mm_ = (blk < 64) ? mylo : myhi;
;       return (int)((mm_ >> (blk & 63)) & 1ull);
;     };
;     auto vfn = [&](int key, int flag) __attribute__((always_inline)) { return flag != 0 && key <= tj; };
;     ds_reset(st);
;     auto fulls = [&](int blk) __attribute__((always_inline)) { return blk * 64 + 63 <= tw0; };
;     run_dense<true, true, false>(st, Ksel, NU, Vsel, SEQ, 0, (t0 + 31) >> 6, qf, pre, fulls, vfn, 0.f, 0.f, nopost, smem, tid);
.LBB0_1646:
	v_mov_b64_e32 v[4:5], s[52:53]
	v_mad_i64_i32 v[6:7], s[2:3], v188, s5, v[4:5]
	v_mad_i64_i32 v[4:5], s[2:3], v84, s5, v[4:5]
	v_lshl_add_u64 v[6:7], v[6:7], 0, v[0:1]
	v_lshl_add_u64 v[4:5], v[4:5], 0, v[0:1]
	v_lshlrev_b64 v[14:15], 14, v[188:189]
	global_load_dwordx4 v[6:9], v[6:7], off sc1
	s_nop 0
	global_load_dwordx4 v[10:13], v[4:5], off sc1
	v_lshl_add_u64 v[4:5], s[54:55], 0, v[14:15]
	v_lshlrev_b64 v[120:121], 14, v[84:85]
	v_lshl_add_u64 v[122:123], v[4:5], 0, v[0:1]
	v_lshl_add_u64 v[4:5], s[54:55], 0, v[120:121]
	v_lshl_add_u64 v[124:125], v[4:5], 0, v[0:1]
	global_load_dwordx4 v[116:119], v[122:123], off sc1
	global_load_dwordx4 v[112:115], v[124:125], off sc1
	v_lshl_add_u32 v2, v100, 4, v2
	ds_read_b128 v[2:5], v2 offset:51712
	v_mov_b32_e32 v46, v1
	v_mov_b32_e32 v47, v1
	v_mov_b32_e32 v32, v1
	v_mov_b32_e32 v33, v1
	v_mov_b32_e32 v34, v1
	v_mov_b32_e32 v35, v1
	v_mov_b32_e32 v36, v1
	v_mov_b32_e32 v37, v1
	v_mov_b32_e32 v38, v1
	v_mov_b32_e32 v39, v1
	v_mov_b32_e32 v40, v1
	v_mov_b32_e32 v41, v1
	v_mov_b32_e32 v42, v1
	v_mov_b32_e32 v43, v1
	v_mov_b32_e32 v44, v1
	v_mov_b32_e32 v45, v1
	v_mov_b64_e32 v[94:95], v[46:47]
	s_lshr_b32 s2, s31, 6
	v_lshl_add_u64 v[126:127], s[52:53], 0, v[0:1]
	s_mov_b32 s3, 0
	v_mov_b32_e32 v128, 0xc61c4000
	v_mov_b32_e32 v189, 0
	s_mov_b32 s14, 63
	v_mov_b64_e32 v[92:93], v[44:45]
	v_mov_b64_e32 v[90:91], v[42:43]
	v_mov_b64_e32 v[88:89], v[40:41]
	v_mov_b64_e32 v[86:87], v[38:39]
	v_mov_b64_e32 v[84:85], v[36:37]
	v_mov_b64_e32 v[82:83], v[34:35]
	v_mov_b64_e32 v[80:81], v[32:33]
	s_movk_i32 s69, 0x4800
; template <bool ONLINE, bool HASV, bool FAST, class VF> ...
;   const int h = lane >> 5, c = lane & 31;
;   f32x16 s[2];
; #pragma unroll
;   for (int kt = 0; kt < 2; ++kt) {
; #pragma unroll
;     for (int r = 0; r < 16; ++r) s[kt][r] = 0.f;
; #pragma unroll
;     for (int ks = 0; ks < 4; ++ks) {
;       const h8 a = *(const h8*)&Ks[(32 * kt + c) * 72 + 16 * ks + 8 * h];
;       s[kt] = __builtin_amdgcn_mfma_f32_32x32x16_f16(a, qf[ks], s[kt], 0, 0, 0);
;     }
;   }
;   float cm = NEGF;
; #pragma unroll
;   for (int kt = 0; kt < 2; ++kt)
; #pragma unroll
;     for (int r = 0; r < 16; ++r) {
;       const int key = key0 + 32 * kt + (r & 3) + 8 * (r >> 2) + 4 * h;
;       const float v = (FAST ? (flag != 0) : valid(key, flag)) ? s[kt][r] : NEGF;
;       s[kt][r] = v;
;       cm = fmaxf(cm, v);
;     }
;   float mnew;
;   if (ONLINE) {
;     cm = fmaxf(cm, __shfl_xor(cm, 32));
;     mnew = st.m;
;     if (__ballot(cm > st.m + 8.0f) != 0ull) {
;       mnew = fmaxf(st.m, cm);
;       const float alpha = __builtin_amdgcn_exp2f(st.m - mnew);
;       st.m = mnew;
;       st.l *= alpha;
;       if (HASV) {
; #pragma unroll
;         for (int dt = 0; dt < 2; ++dt)
; #pragma unroll
;           for (int r = 0; r < 16; ++r) st.o[dt][r] *= alpha;
;       }
;     }
; template <bool ONLINE, bool HASV, bool WANTP, class PRE, class FU, class VF, class PO> ...
;     ...
;   for (int blk = blk_lo; blk <= blk_hi; ++blk) {
;     __syncthreads();
;     write_stage<HASV>(sr, Ks, Vs, tid);
;     __syncthreads();
;     const int nb = blk < blk_hi ? blk + 1 : blk;
;     load_stage<HASV>(sr, Kb, ldk, VT, ldv, nb * 64, tid);
;     const int flag = pre(blk);
;     if (__ballot(flag != 0) != 0ull) {
; __device__ __forceinline__ void nsa_item(const KP& p, int b, int g, int tile, char* smem) {
;     ...
;     auto pre = [&](int blk) __attribute__((always_inline)) {
;       const unsigned long long mm_ = (blk < 64) ? mylo : myhi;
;       return (int)((mm_ >> (blk & 63)) & 1ull);
;     };
.LBB0_1647:
	s_add_i32 s15, s3, 1
	s_cmp_lt_u32 s3, s2
	s_cselect_b32 s8, s15, s3
	s_lshl_b32 s8, s8, 6
	s_waitcnt lgkmcnt(0)
	s_barrier
	s_waitcnt vmcnt(3)
	ds_write_b128 v199, v[6:9]
	s_waitcnt vmcnt(2)
	ds_write_b128 v199, v[10:13] offset:4608
	s_waitcnt vmcnt(1)
	ds_write2_b64 v209, v[116:117], v[118:119] offset0:128 offset1:130
	s_waitcnt vmcnt(0)
	ds_write2_b64 v210, v[112:113], v[114:115] offset0:192 offset1:194
	v_add_u32_e32 v8, s8, v188
	v_mad_i64_i32 v[6:7], s[38:39], v8, s5, v[126:127]
	v_add_u32_e32 v8, 32, v8
	v_mad_i64_i32 v[10:11], s[38:39], v8, s5, v[126:127]
	s_lshl_b64 s[38:39], s[8:9], 1
	s_nop 0
	v_lshl_add_u64 v[64:65], v[122:123], 0, s[38:39]
	s_waitcnt lgkmcnt(0)
	s_barrier
	global_load_dwordx4 v[6:9], v[6:7], off sc1
	s_nop 0
	global_load_dwordx4 v[10:13], v[10:11], off sc1
	v_lshl_add_u64 v[66:67], v[124:125], 0, s[38:39]
	global_load_dwordx4 v[116:119], v[64:65], off sc1
	global_load_dwordx4 v[112:115], v[66:67], off sc1
	s_cmp_lt_u32 s3, 64
	s_cselect_b64 vcc, -1, 0
	v_cndmask_b32_e32 v65, v5, v3, vcc
	v_cndmask_b32_e32 v64, v4, v2, vcc
	v_lshrrev_b64 v[64:65], s3, v[64:65]
	v_and_b32_e32 v130, 1, v64
	v_cmp_ne_u32_e32 vcc, 0, v130
	s_cbranch_vccz .LBB0_1657
	v_cmp_le_i32_e32 vcc, s14, v190
	v_add_f32_e32 v129, 0x41000000, v128
	s_and_saveexec_b64 s[38:39], vcc
	s_xor_b64 s[38:39], exec, s[38:39]
	s_cbranch_execz .LBB0_1652
	ds_read_b128 v[64:67], v200
	ds_read_b128 v[68:71], v200 offset:32
	v_cmp_eq_u32_e32 vcc, 0, v130
	s_waitcnt lgkmcnt(1)
	v_mfma_f32_32x32x16_f16 v[96:111], v[64:67], v[148:151], 0
	ds_read_b128 v[64:67], v200 offset:64
	s_waitcnt lgkmcnt(1)
	v_mfma_f32_32x32x16_f16 v[96:111], v[68:71], v[152:155], v[96:111]
	s_waitcnt lgkmcnt(0)
	v_mfma_f32_32x32x16_f16 v[96:111], v[64:67], v[156:159], v[96:111]
	ds_read_b128 v[64:67], v200 offset:96
	s_waitcnt lgkmcnt(0)
	v_mfma_f32_32x32x16_f16 v[96:111], v[64:67], v[144:147], v[96:111]
	ds_read_b128 v[64:67], v201
	ds_read_b128 v[132:135], v201 offset:32
	s_waitcnt lgkmcnt(1)
	v_mfma_f32_32x32x16_f16 v[64:79], v[64:67], v[148:151], 0
	s_nop 7
	v_cndmask_b32_e32 v141, v96, v242, vcc
	v_cndmask_b32_e32 v138, v97, v242, vcc
	v_max3_f32 v96, v141, s74, v138
	v_cndmask_b32_e32 v139, v98, v242, vcc
	v_cndmask_b32_e32 v137, v99, v242, vcc
	v_max3_f32 v96, v96, v139, v137
	v_cndmask_b32_e32 v140, v103, v242, vcc
	s_waitcnt lgkmcnt(0)
	v_mfma_f32_32x32x16_f16 v[64:79], v[132:135], v[152:155], v[64:79]
	ds_read_b128 v[132:135], v201 offset:64
	v_cndmask_b32_e32 v136, v104, v242, vcc
	v_cndmask_b32_e32 v131, v106, v242, vcc
	v_cndmask_b32_e32 v130, v107, v242, vcc
	v_cndmask_b32_e32 v107, v108, v242, vcc
	v_cndmask_b32_e32 v106, v109, v242, vcc
	v_cndmask_b32_e32 v104, v111, v242, vcc
	s_waitcnt lgkmcnt(0)
	v_mfma_f32_32x32x16_f16 v[64:79], v[132:135], v[156:159], v[64:79]
	ds_read_b128 v[132:135], v201 offset:96
	s_waitcnt lgkmcnt(0)
	v_mfma_f32_32x32x16_f16 v[64:79], v[132:135], v[144:147], v[64:79]
	v_cndmask_b32_e32 v135, v100, v242, vcc
	v_cndmask_b32_e32 v132, v101, v242, vcc
	v_max3_f32 v96, v96, v135, v132
	v_cndmask_b32_e32 v134, v102, v242, vcc
	v_max3_f32 v96, v96, v134, v140
	v_cndmask_b32_e32 v133, v105, v242, vcc
	v_max3_f32 v96, v96, v136, v133
	v_max3_f32 v96, v96, v131, v130
	v_max3_f32 v96, v96, v107, v106
	v_cndmask_b32_e32 v105, v110, v242, vcc
	v_max3_f32 v96, v96, v105, v104
	s_nop 0
	v_cndmask_b32_e32 v103, v64, v242, vcc
	v_cndmask_b32_e32 v102, v65, v242, vcc
	v_max3_f32 v64, v96, v103, v102
	v_cndmask_b32_e32 v101, v66, v242, vcc
	v_cndmask_b32_e32 v100, v67, v242, vcc
	v_max3_f32 v64, v64, v101, v100
	v_cndmask_b32_e32 v99, v68, v242, vcc
	v_cndmask_b32_e32 v98, v69, v242, vcc
	v_max3_f32 v64, v64, v99, v98
	v_cndmask_b32_e32 v97, v70, v242, vcc
	v_cndmask_b32_e32 v96, v71, v242, vcc
	v_max3_f32 v64, v64, v97, v96
	v_cndmask_b32_e32 v71, v72, v242, vcc
	v_cndmask_b32_e32 v69, v73, v242, vcc
	v_max3_f32 v64, v64, v71, v69
	v_cndmask_b32_e32 v70, v74, v242, vcc
	v_cndmask_b32_e32 v68, v75, v242, vcc
	v_max3_f32 v64, v64, v70, v68
	v_cndmask_b32_e32 v67, v76, v242, vcc
	v_cndmask_b32_e32 v65, v77, v242, vcc
	v_max3_f32 v72, v64, v67, v65
	v_cndmask_b32_e32 v66, v78, v242, vcc
	v_cndmask_b32_e32 v64, v79, v242, vcc
	v_max3_f32 v72, v72, v66, v64
	ds_bpermute_b32 v73, v204, v72
	s_waitcnt lgkmcnt(0)
	v_max_f32_e32 v73, v73, v73
	v_max_f32_e32 v72, v72, v73
	v_cmp_gt_f32_e32 vcc, v72, v129
	s_cbranch_vccz .LBB0_1651
	v_max_f32_e32 v72, v72, v72
	v_max_f32_e32 v73, v128, v128
	v_max_f32_e32 v73, v73, v72
	v_sub_f32_e32 v72, v128, v73
	v_exp_f32_e32 v72, v72
	v_mov_b32_e32 v128, v73
	v_mul_f32_e32 v189, v189, v72
	v_pk_mul_f32 v[94:95], v[94:95], v[72:73] op_sel_hi:[1,0]
	v_pk_mul_f32 v[92:93], v[92:93], v[72:73] op_sel_hi:[1,0]
	v_pk_mul_f32 v[90:91], v[90:91], v[72:73] op_sel_hi:[1,0]
	v_pk_mul_f32 v[88:89], v[88:89], v[72:73] op_sel_hi:[1,0]
	v_pk_mul_f32 v[86:87], v[86:87], v[72:73] op_sel_hi:[1,0]
	v_pk_mul_f32 v[84:85], v[84:85], v[72:73] op_sel_hi:[1,0]
	v_pk_mul_f32 v[82:83], v[82:83], v[72:73] op_sel_hi:[1,0]
	v_pk_mul_f32 v[80:81], v[80:81], v[72:73] op_sel_hi:[1,0]
	v_pk_mul_f32 v[46:47], v[46:47], v[72:73] op_sel_hi:[1,0]
	v_pk_mul_f32 v[44:45], v[44:45], v[72:73] op_sel_hi:[1,0]
	v_pk_mul_f32 v[42:43], v[42:43], v[72:73] op_sel_hi:[1,0]
	v_pk_mul_f32 v[40:41], v[40:41], v[72:73] op_sel_hi:[1,0]
	v_pk_mul_f32 v[38:39], v[38:39], v[72:73] op_sel_hi:[1,0]
	v_pk_mul_f32 v[36:37], v[36:37], v[72:73] op_sel_hi:[1,0]
	v_pk_mul_f32 v[34:35], v[34:35], v[72:73] op_sel_hi:[1,0]
	v_pk_mul_f32 v[32:33], v[32:33], v[72:73] op_sel_hi:[1,0]

;   __device__ __forceinline__ half_t* vwT() const { return (half_t*)(ws() + OFF_vwT); }
; __device__ __forceinline__ void nsa_item(const KP& p, int b, int g, int tile, char* smem) {
;     ...
;     float lt = st.l;
;     lt += __shfl_xor(lt, 32);
;     const float sc = lt > 0.f ? gate[1] / lt : 0.f;
; #pragma unroll
;     for (int dt = 0; dt < 2; ++dt)
; #pragma unroll
;       for (int r = 0; r < 16; ++r) res[dt][r] += sc * st.o[dt][r];
;   }
;   {
;     const half_t* Kw = ub + C_CKW + g * 64;
;     const half_t* Vw = p.vwT() + (size_t)(b * 2 + g) * 64 * SEQ;
;     auto pre = [&](int blk) __attribute__((always_inline)) {
;       return (int)((blk * 64 <= tj) && (blk * 64 + 63 > tj - 512));
;     };
;     auto vfn = [&](int key, int) __attribute__((always_inline)) { return key <= tj && key > tj - 512; };
;     ds_reset(st);
;     auto fullw = [&](int blk) __attribute__((always_inline)) { return blk * 64 + 63 <= tw0 && blk * 64 > tw0 + 7 - 512; };
;     run_dense<true, true, false>(st, Kw, NU, Vw, SEQ, max(0, t0 - 511) >> 6, (t0 + 31) >> 6, qf, pre, fullw, vfn, 0.f, 0.f,
;                                  nopost, smem, tid);
.LBB0_1659:
	ds_bpermute_b32 v187, v204, v189
	s_max_i32 s8, s31, 0x1ff
	s_addk_i32 s8, 0xfe01
	s_lshr_b32 s3, s8, 6
	s_cmp_le_u32 s3, s2
	s_cbranch_scc0 .LBB0_1590
	s_andn2_b32 s8, s8, 63
	v_lshl_add_u64 v[2:3], s[60:61], 0, v[14:15]
	v_lshl_add_u64 v[4:5], s[60:61], 0, v[120:121]
	s_lshl_b64 s[14:15], s[8:9], 1
	s_waitcnt vmcnt(3)
	v_lshl_add_u64 v[6:7], v[4:5], 0, s[14:15]
	v_lshl_add_u64 v[8:9], v[2:3], 0, s[14:15]
	v_lshl_add_u64 v[6:7], v[6:7], 0, v[0:1]
	v_lshl_add_u64 v[8:9], v[8:9], 0, v[0:1]
	s_waitcnt vmcnt(2)
	v_add_u32_e32 v10, s8, v188
	global_load_dwordx4 v[160:163], v[6:7], off sc1
	global_load_dwordx4 v[164:167], v[8:9], off sc1
	v_add_u32_e32 v8, 32, v10
	v_mov_b64_e32 v[6:7], s[56:57]
	v_mad_i64_i32 v[8:9], s[14:15], v8, s5, v[6:7]
	v_lshl_add_u64 v[8:9], v[8:9], 0, v[0:1]
	v_mad_i64_i32 v[6:7], s[14:15], v10, s5, v[6:7]
	v_lshl_add_u64 v[6:7], v[6:7], 0, v[0:1]
	global_load_dwordx4 v[168:171], v[8:9], off sc1
	global_load_dwordx4 v[172:175], v[6:7], off sc1
	s_lshl_b32 s8, s30, 6
	s_or_b32 s8, s91, s8
	s_andn2_b32 s8, s8, 31
	s_sub_i32 s8, 0x1fe0, s8
	s_max_i32 s8, s8, 0x1ff
	v_mov_b32_e32 v14, v1
	v_mov_b32_e32 v15, v1
	v_lshl_add_u64 v[192:193], s[56:57], 0, v[0:1]
	v_lshl_add_u64 v[194:195], v[2:3], 0, v[0:1]
	v_lshl_add_u64 v[196:197], v[4:5], 0, v[0:1]
	s_addk_i32 s8, 0xfe01
	v_mov_b32_e32 v0, v1
	v_mov_b32_e32 v2, v1
	v_mov_b32_e32 v3, v1
	v_mov_b32_e32 v4, v1
	v_mov_b32_e32 v5, v1
	v_mov_b32_e32 v6, v1
	v_mov_b32_e32 v7, v1
	v_mov_b32_e32 v8, v1
	v_mov_b32_e32 v9, v1
	v_mov_b32_e32 v10, v1
	v_mov_b32_e32 v11, v1
	v_mov_b32_e32 v12, v1
	v_mov_b32_e32 v13, v1
	v_mov_b64_e32 v[78:79], v[14:15]
	v_mov_b64_e32 v[110:111], v[14:15]
	v_add_u32_e32 v211, 0xfffffe00, v181
	v_add_u32_e32 v212, 0xfffffe07, v190
	s_and_b32 s14, s8, 0xffffffc0
	v_mov_b32_e32 v213, 0xc61c4000
	v_mov_b32_e32 v191, 0
	v_mov_b64_e32 v[76:77], v[12:13]
	v_mov_b64_e32 v[74:75], v[10:11]
	v_mov_b64_e32 v[72:73], v[8:9]
	v_mov_b64_e32 v[70:71], v[6:7]
	v_mov_b64_e32 v[68:69], v[4:5]
	v_mov_b64_e32 v[66:67], v[2:3]
	v_mov_b64_e32 v[64:65], v[0:1]
	v_mov_b64_e32 v[108:109], v[12:13]
	v_mov_b64_e32 v[106:107], v[10:11]
	v_mov_b64_e32 v[104:105], v[8:9]
	v_mov_b64_e32 v[102:103], v[6:7]
	v_mov_b64_e32 v[100:101], v[4:5]
	v_mov_b64_e32 v[98:99], v[2:3]
	v_mov_b64_e32 v[96:97], v[0:1]
	s_branch .LBB0_1664

; template <bool ONLINE, bool HASV, bool FAST, class VF> ...
;   const int h = lane >> 5, c = lane & 31;
;   f32x16 s[2];
; #pragma unroll
;   for (int kt = 0; kt < 2; ++kt) {
; #pragma unroll
;     for (int r = 0; r < 16; ++r) s[kt][r] = 0.f;
; #pragma unroll
;     for (int ks = 0; ks < 4; ++ks) {
;       const h8 a = *(const h8*)&Ks[(32 * kt + c) * 72 + 16 * ks + 8 * h];
;       s[kt] = __builtin_amdgcn_mfma_f32_32x32x16_f16(a, qf[ks], s[kt], 0, 0, 0);
;     }
;   }
;   float cm = NEGF;
; #pragma unroll
;   for (int kt = 0; kt < 2; ++kt)
; #pragma unroll
;     for (int r = 0; r < 16; ++r) {
;       const int key = key0 + 32 * kt + (r & 3) + 8 * (r >> 2) + 4 * h;
;       const float v = (FAST ? (flag != 0) : valid(key, flag)) ? s[kt][r] : NEGF;
;       s[kt][r] = v;
;       cm = fmaxf(cm, v);
;     }
; template <bool ONLINE, bool HASV, bool WANTP, class PRE, class FU, class VF, class PO> ...
;     ...
;   for (int blk = blk_lo; blk <= blk_hi; ++blk) {
;     __syncthreads();
;     write_stage<HASV>(sr, Ks, Vs, tid);
;     __syncthreads();
;     const int nb = blk < blk_hi ? blk + 1 : blk;
;     load_stage<HASV>(sr, Kb, ldk, VT, ldv, nb * 64, tid);
;     const int flag = pre(blk);
;     if (__ballot(flag != 0) != 0ull) {
;       f32x16 pp[2];
;       if (full(blk))
;         dense_block<ONLINE, HASV, true>(st, Ks, Vs, qf, blk * 64, flag, valid, fixed_m, fixed_invl,
;                                         WANTP ? pp : (f32x16*)nullptr, lane);
;       else
;         dense_block<ONLINE, HASV, false>(st, Ks, Vs, qf, blk * 64, flag, valid, fixed_m, fixed_invl,
; __device__ __forceinline__ void nsa_item(const KP& p, int b, int g, int tile, char* smem) {
;     ...
;     auto pre = [&](int blk) __attribute__((always_inline)) {
;       return (int)((blk * 64 <= tj) && (blk * 64 + 63 > tj - 512));
;     };
;     auto vfn = [&](int key, int) __attribute__((always_inline)) { return key <= tj && key > tj - 512; };
;     ds_reset(st);
;     auto fullw = [&](int blk) __attribute__((always_inline)) { return blk * 64 + 63 <= tw0 && blk * 64 > tw0 + 7 - 512; };
;     run_dense<true, true, false>(st, Kw, NU, Vw, SEQ, max(0, t0 - 511) >> 6, (t0 + 31) >> 6, qf, pre, fullw, vfn, 0.f, 0.f,
;                                  nopost, smem, tid);
.LBB0_1664:
	s_cmp_ge_u32 s3, s2
	s_mov_b32 s8, s3
	s_cselect_b64 s[42:43], -1, 0
	s_add_i32 s3, s3, 1
	s_cmp_lt_u32 s8, s2
	s_cselect_b32 s8, s3, s8
	s_lshl_b32 s8, s8, 6
	v_add_u32_e32 v0, s8, v188
	v_mad_i64_i32 v[2:3], s[30:31], v0, s5, v[192:193]
	v_add_u32_e32 v0, 32, v0
	v_mad_i64_i32 v[4:5], s[30:31], v0, s5, v[192:193]
	s_lshl_b64 s[30:31], s[8:9], 1
	s_waitcnt lgkmcnt(0)
	s_barrier
	s_waitcnt vmcnt(0)
	ds_write_b128 v199, v[172:175]
	ds_write_b128 v199, v[168:171] offset:4608
	ds_write2_b64 v209, v[164:165], v[166:167] offset0:128 offset1:130
	ds_write2_b64 v210, v[160:161], v[162:163] offset0:192 offset1:194
	s_waitcnt lgkmcnt(0)
	s_barrier
	global_load_dwordx4 v[172:175], v[2:3], off sc1
	global_load_dwordx4 v[168:171], v[4:5], off sc1
	v_lshl_add_u64 v[2:3], v[194:195], 0, s[30:31]
	v_lshl_add_u64 v[4:5], v[196:197], 0, s[30:31]
	global_load_dwordx4 v[164:167], v[2:3], off sc1
	global_load_dwordx4 v[160:163], v[4:5], off sc1
	s_add_i32 s8, s14, 63
	v_cmp_le_i32_e32 vcc, s14, v181
	v_cmp_gt_i32_e64 s[38:39], s8, v211
	s_and_b64 s[38:39], vcc, s[38:39]
	s_mov_b64 vcc, s[38:39]
	s_cbranch_vccz .LBB0_1663
	v_cmp_gt_i32_e32 vcc, s8, v190
	v_cmp_le_i32_e64 s[40:41], s14, v212
	s_or_b64 s[30:31], vcc, s[40:41]
	v_add_f32_e32 v0, 0x41000000, v213
	s_and_saveexec_b64 s[40:41], s[30:31]
	s_xor_b64 s[44:45], exec, s[40:41]
	s_cbranch_execz .LBB0_1669
	ds_read_b128 v[2:5], v202
	ds_read_b128 v[6:9], v202 offset:32
	s_waitcnt lgkmcnt(1)
	v_mfma_f32_32x32x16_f16 v[128:143], v[2:5], v[148:151], 0
	ds_read_b128 v[2:5], v202 offset:64
	s_waitcnt lgkmcnt(1)
	v_mfma_f32_32x32x16_f16 v[128:143], v[6:9], v[152:155], v[128:143]
	s_waitcnt lgkmcnt(0)
	v_mfma_f32_32x32x16_f16 v[128:143], v[2:5], v[156:159], v[128:143]
	ds_read_b128 v[2:5], v202 offset:96
	s_waitcnt lgkmcnt(0)
	v_mfma_f32_32x32x16_f16 v[128:143], v[2:5], v[144:147], v[128:143]
	ds_read_b128 v[2:5], v203
	ds_read_b128 v[6:9], v203 offset:32
	s_waitcnt lgkmcnt(1)
	v_mfma_f32_32x32x16_f16 v[112:127], v[2:5], v[148:151], 0
	ds_read_b128 v[2:5], v203 offset:64
	s_waitcnt lgkmcnt(1)
	v_mfma_f32_32x32x16_f16 v[112:127], v[6:9], v[152:155], v[112:127]
	v_add_u32_e32 v8, s14, v198
	v_cmp_le_i32_e32 vcc, v8, v181
	v_cmp_gt_i32_e64 s[40:41], v8, v211
	s_and_b64 vcc, vcc, s[40:41]
	s_nop 0
	v_cndmask_b32_e32 v10, v242, v128, vcc
	v_cmp_lt_i32_e32 vcc, v8, v181
	v_cmp_ge_i32_e64 s[40:41], v8, v211
	s_waitcnt lgkmcnt(0)
	v_mfma_f32_32x32x16_f16 v[112:127], v[2:5], v[156:159], v[112:127]
	ds_read_b128 v[2:5], v203 offset:96
	s_and_b64 vcc, vcc, s[40:41]
	v_cndmask_b32_e32 v11, v242, v129, vcc
	s_waitcnt lgkmcnt(0)
; template <bool ONLINE, bool HASV, bool FAST, class VF> ...
;     ...
;   float cm = NEGF;
; #pragma unroll
;   for (int kt = 0; kt < 2; ++kt)
; #pragma unroll
;     for (int r = 0; r < 16; ++r) {
;       const int key = key0 + 32 * kt + (r & 3) + 8 * (r >> 2) + 4 * h;
;       const float v = (FAST ? (flag != 0) : valid(key, flag)) ? s[kt][r] : NEGF;
;       s[kt][r] = v;
;       cm = fmaxf(cm, v);
;     }
;   float mnew;
;   if (ONLINE) {
;     cm = fmaxf(cm, __shfl_xor(cm, 32));
;     mnew = st.m;
;     if (__ballot(cm > st.m + 8.0f) != 0ull) {
;       mnew = fmaxf(st.m, cm);
;       const float alpha = __builtin_amdgcn_exp2f(st.m - mnew);
;       st.m = mnew;
;       st.l *= alpha;
;       if (HASV) {
; #pragma unroll
;         for (int dt = 0; dt < 2; ++dt)
; #pragma unroll
;           for (int r = 0; r < 16; ++r) st.o[dt][r] *= alpha;
;       }
;     }
	v_mfma_f32_32x32x16_f16 v[112:127], v[2:5], v[144:147], v[112:127]
	v_add_u32_e32 v3, 2, v8
	v_cmp_le_i32_e32 vcc, v3, v181
	v_cmp_gt_i32_e64 s[40:41], v3, v211
	s_and_b64 vcc, vcc, s[40:41]
	v_add_u32_e32 v3, 3, v8
	v_cndmask_b32_e32 v13, v242, v130, vcc
	v_cmp_le_i32_e32 vcc, v3, v181
	v_cmp_gt_i32_e64 s[40:41], v3, v211
	s_and_b64 vcc, vcc, s[40:41]
	v_add_u32_e32 v3, 8, v8
	v_cndmask_b32_e32 v15, v242, v131, vcc
	v_cmp_le_i32_e32 vcc, v3, v181
	v_cmp_gt_i32_e64 s[40:41], v3, v211
	s_and_b64 vcc, vcc, s[40:41]
	v_add_u32_e32 v3, 9, v8
	v_cndmask_b32_e32 v128, v242, v132, vcc
	v_cmp_le_i32_e32 vcc, v3, v181
	v_cmp_gt_i32_e64 s[40:41], v3, v211
	s_and_b64 vcc, vcc, s[40:41]
	v_add_u32_e32 v3, 10, v8
	v_cndmask_b32_e32 v129, v242, v133, vcc
	v_cmp_le_i32_e32 vcc, v3, v181
	v_cmp_gt_i32_e64 s[40:41], v3, v211
	s_and_b64 vcc, vcc, s[40:41]
	v_add_u32_e32 v3, 11, v8
	v_cndmask_b32_e32 v130, v242, v134, vcc
	v_cmp_le_i32_e32 vcc, v3, v181
	v_cmp_gt_i32_e64 s[40:41], v3, v211
	s_and_b64 vcc, vcc, s[40:41]
	v_add_u32_e32 v3, 16, v8
	v_cndmask_b32_e32 v131, v242, v135, vcc
	v_cmp_le_i32_e32 vcc, v3, v181
	v_cmp_gt_i32_e64 s[40:41], v3, v211
	s_and_b64 vcc, vcc, s[40:41]
	v_add_u32_e32 v3, 17, v8
	v_cndmask_b32_e32 v132, v242, v136, vcc
	v_cmp_le_i32_e32 vcc, v3, v181
	v_cmp_gt_i32_e64 s[40:41], v3, v211
	s_and_b64 vcc, vcc, s[40:41]
	v_add_u32_e32 v3, 18, v8
	v_cndmask_b32_e32 v133, v242, v137, vcc
	v_cmp_le_i32_e32 vcc, v3, v181
	v_cmp_gt_i32_e64 s[40:41], v3, v211
	s_and_b64 vcc, vcc, s[40:41]
	v_add_u32_e32 v3, 19, v8
	v_cndmask_b32_e32 v136, v242, v138, vcc
	v_cmp_le_i32_e32 vcc, v3, v181
	v_cmp_gt_i32_e64 s[40:41], v3, v211
	s_and_b64 vcc, vcc, s[40:41]
	v_add_u32_e32 v3, 24, v8
	v_cndmask_b32_e32 v137, v242, v139, vcc
	v_cmp_le_i32_e32 vcc, v3, v181
	v_cmp_gt_i32_e64 s[40:41], v3, v211
	s_and_b64 vcc, vcc, s[40:41]
	v_add_u32_e32 v3, 25, v8
	v_cndmask_b32_e32 v134, v242, v140, vcc
	v_cmp_le_i32_e32 vcc, v3, v181
	v_cmp_gt_i32_e64 s[40:41], v3, v211
	s_and_b64 vcc, vcc, s[40:41]
	v_add_u32_e32 v3, 26, v8
	v_cndmask_b32_e32 v135, v242, v141, vcc
	v_cmp_le_i32_e32 vcc, v3, v181
	v_cmp_gt_i32_e64 s[40:41], v3, v211
	s_and_b64 vcc, vcc, s[40:41]
	v_add_u32_e32 v3, 27, v8
	v_cndmask_b32_e32 v138, v242, v142, vcc
	v_cmp_le_i32_e32 vcc, v3, v181
	v_cmp_gt_i32_e64 s[40:41], v3, v211
	s_and_b64 vcc, vcc, s[40:41]
	v_add_u32_e32 v3, 32, v8
	v_cndmask_b32_e32 v139, v242, v143, vcc
	v_cmp_le_i32_e32 vcc, v3, v181
	v_cmp_gt_i32_e64 s[40:41], v3, v211
	s_and_b64 vcc, vcc, s[40:41]
	v_add_u32_e32 v3, 33, v8
	v_cndmask_b32_e32 v112, v242, v112, vcc
	v_cmp_le_i32_e32 vcc, v3, v181
	v_cmp_gt_i32_e64 s[40:41], v3, v211
	s_and_b64 vcc, vcc, s[40:41]
	v_add_u32_e32 v3, 34, v8
	v_cndmask_b32_e32 v113, v242, v113, vcc
	v_cmp_le_i32_e32 vcc, v3, v181
	v_cmp_gt_i32_e64 s[40:41], v3, v211
	s_and_b64 vcc, vcc, s[40:41]
	v_add_u32_e32 v3, 35, v8
	v_max3_f32 v2, v10, s74, v11
	v_cndmask_b32_e32 v140, v242, v114, vcc
	v_cmp_le_i32_e32 vcc, v3, v181
	v_cmp_gt_i32_e64 s[40:41], v3, v211
	v_max3_f32 v2, v2, v13, v15
	s_and_b64 vcc, vcc, s[40:41]
	v_add_u32_e32 v3, 40, v8
	v_max3_f32 v2, v2, v128, v129
	v_cndmask_b32_e32 v115, v242, v115, vcc
	v_cmp_le_i32_e32 vcc, v3, v181
	v_cmp_gt_i32_e64 s[40:41], v3, v211
	v_max3_f32 v2, v2, v130, v131
	s_and_b64 vcc, vcc, s[40:41]
	v_add_u32_e32 v3, 41, v8
	v_max3_f32 v2, v2, v132, v133
	v_cndmask_b32_e32 v114, v242, v116, vcc
	v_cmp_le_i32_e32 vcc, v3, v181
	v_cmp_gt_i32_e64 s[40:41], v3, v211
	v_max3_f32 v2, v2, v136, v137
	s_and_b64 vcc, vcc, s[40:41]
	v_add_u32_e32 v3, 42, v8
	v_max3_f32 v2, v2, v134, v135
	v_cndmask_b32_e32 v116, v242, v117, vcc
	v_cmp_le_i32_e32 vcc, v3, v181
	v_cmp_gt_i32_e64 s[40:41], v3, v211
	v_max3_f32 v2, v2, v138, v139
	s_and_b64 vcc, vcc, s[40:41]
	v_add_u32_e32 v3, 43, v8
	v_max3_f32 v2, v2, v112, v113
	v_cndmask_b32_e32 v14, v242, v118, vcc
	v_cmp_le_i32_e32 vcc, v3, v181
	v_cmp_gt_i32_e64 s[40:41], v3, v211
	v_max3_f32 v2, v2, v140, v115
	s_and_b64 vcc, vcc, s[40:41]
	v_max3_f32 v2, v2, v114, v116
	v_cndmask_b32_e32 v12, v242, v119, vcc
	v_max3_f32 v3, v2, v14, v12
	v_add_u32_e32 v2, 48, v8
	v_cmp_le_i32_e32 vcc, v2, v181
	v_cmp_gt_i32_e64 s[40:41], v2, v211
	s_and_b64 vcc, vcc, s[40:41]
	v_add_u32_e32 v2, 49, v8
	v_cndmask_b32_e32 v9, v242, v120, vcc
	v_cmp_le_i32_e32 vcc, v2, v181
	v_cmp_gt_i32_e64 s[40:41], v2, v211
	s_and_b64 vcc, vcc, s[40:41]
	v_add_u32_e32 v4, 50, v8
	v_cndmask_b32_e32 v2, v242, v121, vcc
	v_cmp_le_i32_e32 vcc, v4, v181
	v_cmp_gt_i32_e64 s[40:41], v4, v211
	s_and_b64 vcc, vcc, s[40:41]
	v_add_u32_e32 v4, 51, v8
	v_cndmask_b32_e32 v5, v242, v122, vcc
	v_cmp_le_i32_e32 vcc, v4, v181
	v_cmp_gt_i32_e64 s[40:41], v4, v211
	s_and_b64 vcc, vcc, s[40:41]
	v_max3_f32 v3, v3, v9, v2
	v_cndmask_b32_e32 v7, v242, v123, vcc
	v_max3_f32 v6, v3, v5, v7
	v_add_u32_e32 v3, 56, v8
	v_cmp_le_i32_e32 vcc, v3, v181
	v_cmp_gt_i32_e64 s[40:41], v3, v211
	s_and_b64 vcc, vcc, s[40:41]
	v_add_u32_e32 v3, 57, v8
	v_cndmask_b32_e32 v4, v242, v124, vcc
	v_cmp_le_i32_e32 vcc, v3, v181
	v_cmp_gt_i32_e64 s[40:41], v3, v211
	s_and_b64 vcc, vcc, s[40:41]
	v_cndmask_b32_e32 v3, v242, v125, vcc
	v_max3_f32 v117, v6, v4, v3
	v_add_u32_e32 v6, 58, v8
	v_cmp_le_i32_e32 vcc, v6, v181
	v_cmp_gt_i32_e64 s[40:41], v6, v211
	s_and_b64 vcc, vcc, s[40:41]
	v_add_u32_e32 v8, 59, v8
	v_cndmask_b32_e32 v6, v242, v126, vcc
	v_cmp_le_i32_e32 vcc, v8, v181
	v_cmp_gt_i32_e64 s[40:41], v8, v211
	s_and_b64 vcc, vcc, s[40:41]
	v_cndmask_b32_e32 v8, v242, v127, vcc
	v_max3_f32 v117, v117, v6, v8
	ds_bpermute_b32 v118, v204, v117
	s_waitcnt lgkmcnt(0)
	v_max_f32_e32 v118, v118, v118
	v_max_f32_e32 v117, v117, v118
	v_cmp_gt_f32_e32 vcc, v117, v0
	s_cbranch_vccz .LBB0_1668
	v_max_f32_e32 v0, v117, v117
	v_max_f32_e32 v117, v213, v213
	v_max_f32_e32 v117, v117, v0
	v_sub_f32_e32 v0, v213, v117
	v_exp_f32_e32 v0, v0
	v_mov_b32_e32 v213, v117
	v_mul_f32_e32 v191, v191, v0
	v_pk_mul_f32 v[110:111], v[110:111], v[0:1] op_sel_hi:[1,0]
	v_pk_mul_f32 v[108:109], v[108:109], v[0:1] op_sel_hi:[1,0]
	v_pk_mul_f32 v[106:107], v[106:107], v[0:1] op_sel_hi:[1,0]
	v_pk_mul_f32 v[104:105], v[104:105], v[0:1] op_sel_hi:[1,0]
	v_pk_mul_f32 v[102:103], v[102:103], v[0:1] op_sel_hi:[1,0]
	v_pk_mul_f32 v[100:101], v[100:101], v[0:1] op_sel_hi:[1,0]
	v_pk_mul_f32 v[98:99], v[98:99], v[0:1] op_sel_hi:[1,0]
	v_pk_mul_f32 v[96:97], v[96:97], v[0:1] op_sel_hi:[1,0]
	v_pk_mul_f32 v[78:79], v[78:79], v[0:1] op_sel_hi:[1,0]
	v_pk_mul_f32 v[76:77], v[76:77], v[0:1] op_sel_hi:[1,0]
	v_pk_mul_f32 v[74:75], v[74:75], v[0:1] op_sel_hi:[1,0]
	v_pk_mul_f32 v[72:73], v[72:73], v[0:1] op_sel_hi:[1,0]
	v_pk_mul_f32 v[70:71], v[70:71], v[0:1] op_sel_hi:[1,0]
	v_pk_mul_f32 v[68:69], v[68:69], v[0:1] op_sel_hi:[1,0]
	v_pk_mul_f32 v[66:67], v[66:67], v[0:1] op_sel_hi:[1,0]
	v_pk_mul_f32 v[64:65], v[64:65], v[0:1] op_sel_hi:[1,0]

;   __device__ __forceinline__ half_t* u() const { return (half_t*)(ws() + OFF_u); }
;   __device__ __forceinline__ half_t* wpT() const { return (half_t*)(ws() + OFF_wpT); }
;   __device__ __forceinline__ half_t* ya() const { return (half_t*)(ws() + OFF_ya); }
;   __device__ __forceinline__ half_t* yb() const { return (half_t*)(ws() + OFF_yb); }
;   __device__ __forceinline__ half_t* yc() const { return (half_t*)(ws() + OFF_yc); }
; template <int NI, class LA, class LB, class EP>
; __device__ __forceinline__ void gemm_tile(int K, LA loadA, LB loadB, EP epi, char* smem) {
;     ...
;   f32x16 acc[2][NI];
; #pragma unroll
;   for (int i = 0; i < 2; ++i)
; #pragma unroll
;     for (int j = 0; j < NI; ++j)
; #pragma unroll
;       for (int r = 0; r < 16; ++r) acc[i][j][r] = 0.f;
;   const int lr = tid >> 3, lc = (tid & 7) * 8;
;   uint4 ra[4], rb[NB];
; #pragma unroll
;   for (int i = 0; i < 4; ++i) ra[i] = loadA(lr + 32 * i, lc);
; #pragma unroll
;   for (int i = 0; i < NB; ++i) rb[i] = loadB(lr + 32 * i, lc);
; __device__ __forceinline__ void phase_merge(const KP& p, char* smem, int* q, int xcc) {
;     ...
;     for (int br = 0; br < 3; ++br) {
;       const half_t* A = (br == 0 ? p.ya() : (br == 1 ? p.yb() : p.yc())) + (size_t)m0 * 512;
;       const half_t* B = p.wpT() + (size_t)br * DM * 512 + (size_t)n0 * 512;
;       const half_t* G = p.u() + (size_t)m0 * NU + C_GM + br * 1024 + n0;
;       gemm_tile<2>(
;           512, [&](int r, int k) { return *(const uint4*)(A + (size_t)r * 512 + k); },
.LBB0_1742:
	s_cmp_eq_u32 s56, 1
	s_mov_b32 s2, 0x174a0200
	s_cselect_b32 s2, s2, 0x184a0200
	s_cmp_lg_u32 s56, 0
	v_mov_b32_e32 v169, v224
	s_cselect_b32 s57, s2, 0x164a0200
	s_add_u32 s2, s15, s57
	v_lshlrev_b32_e32 v0, 3, v169
	v_ashrrev_i32_e32 v2, 3, v169
	v_and_b32_e32 v16, 56, v0
	s_addc_u32 s3, s49, 0
	v_lshlrev_b32_e32 v0, 1, v16
	v_ashrrev_i32_e32 v3, 31, v2
	v_lshl_add_u64 v[4:5], s[2:3], 0, v[0:1]
	v_lshlrev_b64 v[6:7], 10, v[2:3]
	s_mov_b64 s[2:3], 0x8000
	s_lshl_b32 s40, s56, 20
	v_lshl_add_u64 v[8:9], v[4:5], 0, v[6:7]
	v_lshl_add_u64 v[10:11], v[6:7], 0, s[2:3]
	s_mov_b64 s[2:3], 0x18000
	s_add_u32 s40, s50, s40
	v_lshl_add_u64 v[12:13], v[4:5], 0, v[10:11]
	global_load_dwordx4 v[192:195], v[8:9], off sc1
	global_load_dwordx4 v[196:199], v[12:13], off sc1
	v_lshl_add_u64 v[8:9], v[6:7], 0, s[20:21]
	v_lshl_add_u64 v[14:15], v[6:7], 0, s[2:3]
	s_addc_u32 s41, s51, 0
	v_lshl_add_u64 v[12:13], v[4:5], 0, v[8:9]
	v_lshl_add_u64 v[4:5], v[4:5], 0, v[14:15]
	global_load_dwordx4 v[200:203], v[12:13], off sc1
	global_load_dwordx4 v[204:207], v[4:5], off sc1
	v_lshl_add_u64 v[4:5], s[40:41], 0, v[0:1]
	v_lshl_add_u64 v[12:13], v[4:5], 0, v[6:7]
	v_lshl_add_u64 v[8:9], v[4:5], 0, v[8:9]
	v_lshl_add_u64 v[10:11], v[4:5], 0, v[10:11]
	global_load_dwordx4 v[208:211], v[12:13], off sc1
	global_load_dwordx4 v[212:215], v[10:11], off sc1
	v_lshl_add_u64 v[4:5], v[4:5], 0, v[14:15]
	global_load_dwordx4 v[216:219], v[8:9], off sc1
	global_load_dwordx4 v[220:223], v[4:5], off sc1
	v_ashrrev_i32_e32 v0, 1, v169
	v_and_b32_e32 v170, 0xffffffc0, v0
	v_lshrrev_b32_e32 v4, 1, v169
	v_and_or_b32 v3, v169, 31, v170
	v_and_b32_e32 v0, 0x5f, v169
	v_and_b32_e32 v4, 16, v4
	v_mul_lo_u32 v2, v2, s37
	v_mad_u64_u32 v[162:163], s[2:3], v3, s36, v[4:5]
	v_add_lshl_u32 v172, v2, v16, 1
	v_mul_u32_u24_e32 v2, 0x48, v0
	v_lshl_add_u32 v163, v2, 1, v4
	v_and_b32_e32 v2, 7, v169
	s_add_u32 s2, s54, s57
	v_lshl_or_b32 v6, v2, 4, v6
	s_addc_u32 s3, s55, 0
	v_add_u32_e32 v171, 0x1200, v163
	v_lshl_add_u64 v[164:165], s[38:39], 0, v[6:7]
	v_lshl_add_u64 v[166:167], s[2:3], 0, v[6:7]
	s_mov_b64 s[2:3], 0x80
	v_lshl_add_u64 v[228:229], v[166:167], 0, s[2:3]
	s_nop 0
	v_add_co_u32_e32 v230, vcc, s73, v228
	s_nop 1
	v_addc_co_u32_e32 v231, vcc, 0, v229, vcc
	v_add_co_u32_e32 v232, vcc, s72, v228
	s_nop 1
	v_addc_co_u32_e32 v233, vcc, 0, v229, vcc
	v_add_co_u32_e32 v234, vcc, s77, v228
	s_nop 1
	v_addc_co_u32_e32 v235, vcc, 0, v229, vcc
	s_mov_b64 s[2:3], 0x15680080
	v_lshl_add_u64 v[238:239], v[164:165], 0, s[2:3]
	s_mov_b64 s[2:3], 0x15688080
	v_lshl_add_u64 v[240:241], v[164:165], 0, s[2:3]
	s_mov_b64 s[2:3], 0x15690080
	v_lshl_add_u64 v[242:243], v[164:165], 0, s[2:3]
	s_mov_b64 s[2:3], 0x15698080
	v_lshl_add_u64 v[244:245], v[164:165], 0, s[2:3]
	s_mov_b64 s[2:3], 0x80
	s_mov_b64 s[40:41], 0
	v_mov_b32_e32 v2, 0
	v_mov_b32_e32 v3, v168
	v_mov_b32_e32 v4, v168
	v_mov_b32_e32 v5, v168
	v_mov_b32_e32 v6, v168
	v_mov_b32_e32 v7, v168
	v_mov_b32_e32 v8, v168
	v_mov_b32_e32 v9, v168
	v_mov_b32_e32 v10, v168
	v_mov_b32_e32 v11, v168
	v_mov_b32_e32 v12, v168
	v_mov_b32_e32 v13, v168
	v_mov_b32_e32 v14, v168
	v_mov_b32_e32 v15, v168
	v_mov_b32_e32 v16, v168
	v_mov_b32_e32 v17, v168
	v_mov_b32_e32 v18, 0
	v_mov_b32_e32 v19, v168
	v_mov_b32_e32 v20, v168
	v_mov_b32_e32 v21, v168
	v_mov_b32_e32 v22, v168
	v_mov_b32_e32 v23, v168
	v_mov_b32_e32 v24, v168
	v_mov_b32_e32 v25, v168
	v_mov_b32_e32 v26, v168
	v_mov_b32_e32 v27, v168
	v_mov_b32_e32 v28, v168
	v_mov_b32_e32 v29, v168
	v_mov_b32_e32 v30, v168
	v_mov_b32_e32 v31, v168
	v_mov_b32_e32 v32, v168
	v_mov_b32_e32 v33, v168
	v_mov_b32_e32 v34, 0
	v_mov_b32_e32 v35, v168
	v_mov_b32_e32 v36, v168
	v_mov_b32_e32 v37, v168
	v_mov_b32_e32 v38, v168
	v_mov_b32_e32 v39, v168
	v_mov_b32_e32 v40, v168
	v_mov_b32_e32 v41, v168
	v_mov_b32_e32 v42, v168
	v_mov_b32_e32 v43, v168
	v_mov_b32_e32 v44, v168
	v_mov_b32_e32 v45, v168
	v_mov_b32_e32 v46, v168
	v_mov_b32_e32 v47, v168
	v_mov_b32_e32 v48, v168
	v_mov_b32_e32 v49, v168
	v_mov_b32_e32 v50, 0
	v_mov_b32_e32 v51, v168
	v_mov_b32_e32 v52, v168
	v_mov_b32_e32 v53, v168
	v_mov_b32_e32 v54, v168
	v_mov_b32_e32 v55, v168
	v_mov_b32_e32 v56, v168
	v_mov_b32_e32 v57, v168
	v_mov_b32_e32 v58, v168
	v_mov_b32_e32 v59, v168
	v_mov_b32_e32 v60, v168
	v_mov_b32_e32 v61, v168
	v_mov_b32_e32 v62, v168
	v_mov_b32_e32 v63, v168
	v_mov_b32_e32 v64, v168
	v_mov_b32_e32 v65, v168
; template <int NI, class LA, class LB, class EP>
; __device__ __forceinline__ void gemm_tile(int K, LA loadA, LB loadB, EP epi, char* smem) {
;     ...
;   for (int kt = 0; kt < nk; ++kt) {
;     __syncthreads();
; #pragma unroll
;     for (int i = 0; i < 4; ++i) *(uint4*)&sA[(lr + 32 * i) * 72 + lc] = ra[i];
; #pragma unroll
;     for (int i = 0; i < NB; ++i) *(uint4*)&sB[(lr + 32 * i) * 72 + lc] = rb[i];
;     __syncthreads();
;     if (kt + 1 < nk) {
;       const int kk = (kt + 1) * 64 + lc;
; #pragma unroll
;       for (int i = 0; i < 4; ++i) ra[i] = loadA(lr + 32 * i, kk);
; #pragma unroll
;       for (int i = 0; i < NB; ++i) rb[i] = loadB(lr + 32 * i, kk);
;     }
; #pragma unroll
;     for (int s = 0; s < 4; ++s) {
;       h8 af[2], bf[NI];
; #pragma unroll
;       for (int mi = 0; mi < 2; ++mi)
;         af[mi] = *(const h8*)&sA[(wm * 64 + mi * 32 + (lane & 31)) * 72 + s * 16 + (lane >> 5) * 8];
; #pragma unroll
;       for (int ni = 0; ni < NI; ++ni)
;         bf[ni] = *(const h8*)&sB[(wn * (NI * 32) + ni * 32 + (lane & 31)) * 72 + s * 16 + (lane >> 5) * 8];
; #pragma unroll
;       for (int mi = 0; mi < 2; ++mi)
; #pragma unroll
;         for (int ni = 0; ni < NI; ++ni)
;           acc[mi][ni] = __builtin_amdgcn_mfma_f32_32x32x16_f16(af[mi], bf[ni], acc[mi][ni], 0, 0, 0);
;     }
.LBB0_1743:
	s_waitcnt vmcnt(63) expcnt(7) lgkmcnt(15)
	s_barrier
	s_waitcnt vmcnt(7)
	ds_write_b128 v172, v[192:195]
	s_waitcnt vmcnt(6)
	ds_write_b128 v172, v[196:199] offset:4608
	s_waitcnt vmcnt(5)
	ds_write_b128 v172, v[200:203] offset:9216
	s_waitcnt vmcnt(4)
	ds_write_b128 v172, v[204:207] offset:13824
	s_waitcnt vmcnt(3)
	ds_write_b128 v172, v[208:211] offset:18432
	s_waitcnt vmcnt(2)
	ds_write_b128 v172, v[212:215] offset:23040
	s_waitcnt vmcnt(1)
	ds_write_b128 v172, v[216:219] offset:27648
	s_waitcnt vmcnt(0)
	ds_write_b128 v172, v[220:223] offset:32256
	global_load_dwordx4 v[192:195], v[228:229], off sc1
	global_load_dwordx4 v[196:199], v[230:231], off sc1
	global_load_dwordx4 v[200:203], v[232:233], off sc1
	global_load_dwordx4 v[204:207], v[234:235], off sc1
	global_load_dwordx4 v[208:211], v[238:239], off sc1
	global_load_dwordx4 v[212:215], v[240:241], off sc1
	global_load_dwordx4 v[216:219], v[242:243], off sc1
	global_load_dwordx4 v[220:223], v[244:245], off sc1
	s_waitcnt lgkmcnt(0)
	s_barrier
	ds_read_b128 v[66:69], v162
	ds_read_b128 v[70:73], v163 offset:18432
	ds_read_b128 v[74:77], v162 offset:32
	ds_read_b128 v[78:81], v163 offset:18464
	ds_read_b128 v[82:85], v171 offset:18432
	ds_read_b128 v[174:177], v163 offset:23136
	s_waitcnt lgkmcnt(4)
	v_mfma_f32_32x32x16_f16 v[50:65], v[66:69], v[70:73], v[50:65]
	s_waitcnt lgkmcnt(1)
	v_mfma_f32_32x32x16_f16 v[34:49], v[66:69], v[82:85], v[34:49]
	v_lshl_add_u64 v[228:229], v[228:229], 0, s[2:3]
	ds_read_b128 v[66:69], v162 offset:4608
	ds_read_b128 v[86:89], v162 offset:4640
	s_waitcnt lgkmcnt(1)
	v_mfma_f32_32x32x16_f16 v[18:33], v[66:69], v[70:73], v[18:33]
	v_mfma_f32_32x32x16_f16 v[2:17], v[66:69], v[82:85], v[2:17]
	v_lshl_add_u64 v[230:231], v[230:231], 0, s[2:3]
	ds_read_b128 v[66:69], v163 offset:23072
	ds_read_b128 v[70:73], v163 offset:23104
	v_mfma_f32_32x32x16_f16 v[50:65], v[74:77], v[78:81], v[50:65]
	s_waitcnt lgkmcnt(1)
	v_mfma_f32_32x32x16_f16 v[34:49], v[74:77], v[66:69], v[34:49]
	v_lshl_add_u64 v[232:233], v[232:233], 0, s[2:3]
	v_mfma_f32_32x32x16_f16 v[18:33], v[86:89], v[78:81], v[18:33]
	v_mfma_f32_32x32x16_f16 v[2:17], v[86:89], v[66:69], v[2:17]
	v_lshl_add_u64 v[234:235], v[234:235], 0, s[2:3]
	ds_read_b128 v[66:69], v162 offset:64
	ds_read_b128 v[74:77], v163 offset:18496
	ds_read_b128 v[78:81], v162 offset:96
	ds_read_b128 v[82:85], v163 offset:18528
	ds_read_b128 v[86:89], v162 offset:4672
	ds_read_b128 v[178:181], v162 offset:4704
	s_waitcnt lgkmcnt(4)
	v_mfma_f32_32x32x16_f16 v[50:65], v[66:69], v[74:77], v[50:65]
	v_mfma_f32_32x32x16_f16 v[34:49], v[66:69], v[70:73], v[34:49]
	v_lshl_add_u64 v[238:239], v[238:239], 0, s[2:3]
	s_waitcnt lgkmcnt(1)
	v_mfma_f32_32x32x16_f16 v[18:33], v[86:89], v[74:77], v[18:33]
	v_mfma_f32_32x32x16_f16 v[2:17], v[86:89], v[70:73], v[2:17]
	v_lshl_add_u64 v[240:241], v[240:241], 0, s[2:3]
	v_mfma_f32_32x32x16_f16 v[50:65], v[78:81], v[82:85], v[50:65]
	v_mfma_f32_32x32x16_f16 v[34:49], v[78:81], v[174:177], v[34:49]
	v_lshl_add_u64 v[242:243], v[242:243], 0, s[2:3]
	s_waitcnt lgkmcnt(0)
	v_mfma_f32_32x32x16_f16 v[18:33], v[178:181], v[82:85], v[18:33]
	v_mfma_f32_32x32x16_f16 v[2:17], v[178:181], v[174:177], v[2:17]
	v_lshl_add_u64 v[244:245], v[244:245], 0, s[2:3]
	s_add_u32 s40, s40, 0x80
	s_addc_u32 s41, s41, 0
	s_cmpk_lg_i32 s40, 0x380
	s_cbranch_scc1 .LBB0_1743
	s_barrier
	s_waitcnt vmcnt(7)
	ds_write_b128 v172, v[192:195]
	s_waitcnt vmcnt(6)
	ds_write_b128 v172, v[196:199] offset:4608
	s_waitcnt vmcnt(5)
	ds_write_b128 v172, v[200:203] offset:9216
	s_waitcnt vmcnt(4)
	ds_write_b128 v172, v[204:207] offset:13824
	s_waitcnt vmcnt(3)
	ds_write_b128 v172, v[208:211] offset:18432
	s_waitcnt vmcnt(2)
	ds_write_b128 v172, v[212:215] offset:23040
	s_waitcnt vmcnt(1)
	ds_write_b128 v172, v[216:219] offset:27648
	s_waitcnt vmcnt(0)
	ds_write_b128 v172, v[220:223] offset:32256
	s_waitcnt lgkmcnt(0)
	s_barrier
	ds_read_b128 v[66:69], v162 offset:4608
	ds_read_b128 v[70:73], v171 offset:18432
	ds_read_b128 v[74:77], v162
	ds_read_b128 v[78:81], v162 offset:32
	ds_read_b128 v[82:85], v163 offset:18432
	ds_read_b128 v[86:89], v163 offset:18464
	s_waitcnt lgkmcnt(1)
	v_mfma_f32_32x32x16_f16 v[50:65], v[74:77], v[82:85], v[50:65]
	s_lshl_b32 s2, s56, 11
	s_add_u32 s2, s52, s2
	s_addc_u32 s3, s53, 0
	v_lshlrev_b32_e32 v0, 1, v0
	s_add_i32 s56, s56, 1
	s_add_u32 s38, s38, 0x100000
	s_addc_u32 s39, s39, 0
	v_mfma_f32_32x32x16_f16 v[34:49], v[74:77], v[70:73], v[34:49]
	s_cmp_lg_u32 s56, 3
	v_mfma_f32_32x32x16_f16 v[18:33], v[66:69], v[82:85], v[18:33]
	v_mfma_f32_32x32x16_f16 v[2:17], v[66:69], v[70:73], v[2:17]
	ds_read_b128 v[66:69], v162 offset:4640
	ds_read_b128 v[70:73], v163 offset:23072
	s_waitcnt lgkmcnt(2)
	v_mfma_f32_32x32x16_f16 v[50:65], v[78:81], v[86:89], v[50:65]
	s_waitcnt lgkmcnt(0)
	v_mfma_f32_32x32x16_f16 v[34:49], v[78:81], v[70:73], v[34:49]
	v_mfma_f32_32x32x16_f16 v[18:33], v[66:69], v[86:89], v[18:33]
	v_mfma_f32_32x32x16_f16 v[2:17], v[66:69], v[70:73], v[2:17]
	ds_read_b128 v[66:69], v162 offset:64
	ds_read_b128 v[70:73], v162 offset:4672
	ds_read_b128 v[74:77], v163 offset:18496
	ds_read_b128 v[78:81], v163 offset:23104
	s_waitcnt lgkmcnt(1)
	v_mfma_f32_32x32x16_f16 v[50:65], v[66:69], v[74:77], v[50:65]
	s_waitcnt lgkmcnt(0)
	v_mfma_f32_32x32x16_f16 v[34:49], v[66:69], v[78:81], v[34:49]
	v_mfma_f32_32x32x16_f16 v[18:33], v[70:73], v[74:77], v[18:33]
	v_mfma_f32_32x32x16_f16 v[2:17], v[70:73], v[78:81], v[2:17]
	ds_read_b128 v[66:69], v162 offset:96
	ds_read_b128 v[70:73], v162 offset:4704
	ds_read_b128 v[74:77], v163 offset:18528
	ds_read_b128 v[78:81], v163 offset:23136
	s_waitcnt lgkmcnt(1)
;   __device__ __forceinline__ const float* x() const { return (const float*)(const __attribute__((address_space(1))) float*)kp[0]; }
; __device__ __forceinline__ float sigmoidf_(float x) { return 1.f / (1.f + __expf(-x)); }
; __device__ __forceinline__ void phase_merge(const KP& p, char* smem, int* q, int xcc) {
;     ...
;           [&](int mi, int ni, int r, int row, int col, float v) {
;             const float gz = (float)G[(size_t)row * NU + col];
;             tot[mi][ni][r] += sigmoidf_(gz) * v;
;           },
	v_mfma_f32_32x32x16_f16 v[50:65], v[66:69], v[74:77], v[50:65]
	s_waitcnt lgkmcnt(0)
	v_mfma_f32_32x32x16_f16 v[34:49], v[66:69], v[78:81], v[34:49]
	v_mfma_f32_32x32x16_f16 v[18:33], v[70:73], v[74:77], v[18:33]
	v_mfma_f32_32x32x16_f16 v[2:17], v[70:73], v[78:81], v[2:17]
	v_mov_b32_e32 v228, 0x11fe4
	v_mov_b32_e32 v229, 0x100
	v_mov_b32_e32 v230, 2
	v_mov_b32_e32 v231, 0x3727c5ac
	v_mov_b32_e32 v232, 0x11fa0
	v_mov_b32_e32 v233, 0x80000
	v_mov_b32_e32 v234, 0x1d0000
	v_mov_b32_e32 v235, 0xa800
	v_mov_b32_e32 v238, 0x4000
	v_mov_b32_e32 v239, 0x4400
	v_mov_b32_e32 v240, 0x4800
	v_mov_b32_e32 v241, 0x4c00
	v_mov_b32_e32 v242, 0xf149f2ca
	v_mov_b32_e32 v243, 0x200
	v_mov_b32_e32 v244, 0x400
	v_mov_b32_e32 v245, 0x600
	v_lshrrev_b32_e32 v94, 7, v224
	v_lshlrev_b32_e32 v94, 4, v94
	v_bfe_u32 v95, v224, 5, 1
	v_add_u32_e32 v94, v94, v95
	v_mul_u32_u24_e32 v94, 0xe800, v94
	v_bfe_u32 v95, v224, 6, 1
	v_lshl_add_u32 v94, v95, 7, v94
	v_and_b32_e32 v95, 31, v224
	v_lshl_add_u32 v94, v95, 1, v94
	s_mov_b64 s[40:41], s[2:3]
	v_mov_b32_e32 v96, v94
	global_load_ushort v192, v96, s[40:41]
	v_add_u32_e32 v96, 0x3a00, v94
	global_load_ushort v193, v96, s[40:41]
	v_add_u32_e32 v96, 0x7400, v94
	global_load_ushort v194, v96, s[40:41]
	v_add_u32_e32 v96, 0xae00, v94
	global_load_ushort v195, v96, s[40:41]
	v_add_u32_e32 v96, 0x1d000, v94
	global_load_ushort v196, v96, s[40:41]
	v_add_u32_e32 v96, 0x20a00, v94
	global_load_ushort v197, v96, s[40:41]
	v_add_u32_e32 v96, 0x24400, v94
	global_load_ushort v198, v96, s[40:41]
	v_add_u32_e32 v96, 0x27e00, v94
	global_load_ushort v199, v96, s[40:41]
	v_add_u32_e32 v96, 0x3a000, v94
	global_load_ushort v200, v96, s[40:41]
	v_add_u32_e32 v96, 0x3da00, v94
	global_load_ushort v201, v96, s[40:41]
	v_add_u32_e32 v96, 0x41400, v94
	global_load_ushort v202, v96, s[40:41]
	v_add_u32_e32 v96, 0x44e00, v94
	global_load_ushort v203, v96, s[40:41]
	v_add_u32_e32 v96, 0x57000, v94
	global_load_ushort v204, v96, s[40:41]
	v_add_u32_e32 v96, 0x5aa00, v94
	global_load_ushort v205, v96, s[40:41]
	v_add_u32_e32 v96, 0x5e400, v94
	global_load_ushort v206, v96, s[40:41]
	v_add_u32_e32 v96, 0x61e00, v94
	global_load_ushort v207, v96, s[40:41]
	v_mov_b32_e32 v96, v94
	global_load_ushort v208, v96, s[40:41] offset:64
	v_add_u32_e32 v96, 0x3a00, v94
	global_load_ushort v209, v96, s[40:41] offset:64
	v_add_u32_e32 v96, 0x7400, v94
	global_load_ushort v210, v96, s[40:41] offset:64
	v_add_u32_e32 v96, 0xae00, v94
	global_load_ushort v211, v96, s[40:41] offset:64
	v_add_u32_e32 v96, 0x1d000, v94
	global_load_ushort v212, v96, s[40:41] offset:64
	v_add_u32_e32 v96, 0x20a00, v94
	global_load_ushort v213, v96, s[40:41] offset:64
	v_add_u32_e32 v96, 0x24400, v94
	global_load_ushort v214, v96, s[40:41] offset:64
	v_add_u32_e32 v96, 0x27e00, v94
	global_load_ushort v215, v96, s[40:41] offset:64
	v_add_u32_e32 v96, 0x3a000, v94
	global_load_ushort v216, v96, s[40:41] offset:64
	v_add_u32_e32 v96, 0x3da00, v94
	global_load_ushort v217, v96, s[40:41] offset:64
	v_add_u32_e32 v96, 0x41400, v94
	global_load_ushort v218, v96, s[40:41] offset:64
	v_add_u32_e32 v96, 0x44e00, v94
	global_load_ushort v219, v96, s[40:41] offset:64
	v_add_u32_e32 v96, 0x57000, v94
	global_load_ushort v220, v96, s[40:41] offset:64
	v_add_u32_e32 v96, 0x5aa00, v94
	global_load_ushort v221, v96, s[40:41] offset:64
	v_add_u32_e32 v96, 0x5e400, v94
	global_load_ushort v222, v96, s[40:41] offset:64
	v_add_u32_e32 v96, 0x61e00, v94
	global_load_ushort v223, v96, s[40:41] offset:64
	s_nop 7
	s_waitcnt vmcnt(30)
	v_cvt_f32_f16_e32 v68, v192
	v_cvt_f32_f16_e32 v69, v193
	v_add_u32_e32 v96, 0x74000, v94
	global_load_ushort v192, v96, s[40:41]
	v_add_u32_e32 v96, 0x77a00, v94
	global_load_ushort v193, v96, s[40:41]
	v_mul_f32_e32 v68, 0xbfb8aa3b, v68
	v_mul_f32_e32 v69, 0xbfb8aa3b, v69
	v_exp_f32_e32 v68, v68
	v_exp_f32_e32 v69, v69
	s_nop 0
	v_pk_add_f32 v[68:69], v[68:69], 1.0 op_sel_hi:[1,0]
	s_nop 0
	v_div_scale_f32 v70, s[2:3], v69, v69, 1.0
	v_rcp_f32_e32 v71, v70
	s_nop 0
	v_fma_f32 v72, -v70, v71, 1.0
	v_fmac_f32_e32 v71, v72, v71
	v_div_scale_f32 v72, vcc, 1.0, v69, 1.0
	v_mul_f32_e32 v73, v72, v71
	v_fma_f32 v74, -v70, v73, v72
	v_fmac_f32_e32 v73, v74, v71
	v_fma_f32 v70, -v70, v73, v72
	v_div_fmas_f32 v70, v70, v71, v73
	v_div_fixup_f32 v69, v70, v69, 1.0
	v_div_scale_f32 v70, s[2:3], v68, v68, 1.0
	v_rcp_f32_e32 v71, v70
	s_nop 0
	v_fma_f32 v72, -v70, v71, 1.0
	v_fmac_f32_e32 v71, v72, v71
	v_div_scale_f32 v72, vcc, 1.0, v68, 1.0
	v_mul_f32_e32 v73, v72, v71
	v_fma_f32 v74, -v70, v73, v72
	v_fmac_f32_e32 v73, v74, v71
	v_fma_f32 v70, -v70, v73, v72
	v_div_fmas_f32 v70, v70, v71, v73
	v_div_fixup_f32 v68, v70, v68, 1.0
	v_pk_fma_f32 v[160:161], v[50:51], v[68:69], v[160:161]
	s_waitcnt vmcnt(30)
	v_cvt_f32_f16_e32 v68, v194
	v_cvt_f32_f16_e32 v69, v195
	v_add_u32_e32 v96, 0x7b400, v94
	global_load_ushort v194, v96, s[40:41]
	v_add_u32_e32 v96, 0x7ee00, v94
	global_load_ushort v195, v96, s[40:41]
	v_mul_f32_e32 v68, 0xbfb8aa3b, v68
	v_mul_f32_e32 v69, 0xbfb8aa3b, v69
	v_exp_f32_e32 v68, v68
	v_exp_f32_e32 v69, v69
	s_nop 0
	v_pk_add_f32 v[68:69], v[68:69], 1.0 op_sel_hi:[1,0]
	s_nop 0
	v_div_scale_f32 v70, s[2:3], v69, v69, 1.0
	v_rcp_f32_e32 v71, v70
	s_nop 0
	v_fma_f32 v72, -v70, v71, 1.0
	v_fmac_f32_e32 v71, v72, v71
	v_div_scale_f32 v72, vcc, 1.0, v69, 1.0
	v_mul_f32_e32 v73, v72, v71
	v_fma_f32 v74, -v70, v73, v72
	v_fmac_f32_e32 v73, v74, v71
	v_fma_f32 v70, -v70, v73, v72
	v_div_fmas_f32 v70, v70, v71, v73
	v_div_fixup_f32 v69, v70, v69, 1.0
	v_div_scale_f32 v70, s[2:3], v68, v68, 1.0
	v_rcp_f32_e32 v71, v70
	s_nop 0
	v_fma_f32 v72, -v70, v71, 1.0
	v_fmac_f32_e32 v71, v72, v71
	v_div_scale_f32 v72, vcc, 1.0, v68, 1.0
	v_mul_f32_e32 v73, v72, v71
	v_fma_f32 v74, -v70, v73, v72
	v_fmac_f32_e32 v73, v74, v71
	v_fma_f32 v70, -v70, v73, v72
	v_div_fmas_f32 v70, v70, v71, v73
	v_div_fixup_f32 v68, v70, v68, 1.0
	v_pk_fma_f32 v[158:159], v[52:53], v[68:69], v[158:159]
	s_waitcnt vmcnt(30)
;   __device__ __forceinline__ const float* x() const { return (const float*)(const __attribute__((address_space(1))) float*)kp[0]; }
; __device__ __forceinline__ float sigmoidf_(float x) { return 1.f / (1.f + __expf(-x)); }
; __device__ __forceinline__ void phase_merge(const KP& p, char* smem, int* q, int xcc) {
;     ...
;           [&](int mi, int ni, int r, int row, int col, float v) {
;             const float gz = (float)G[(size_t)row * NU + col];
;             tot[mi][ni][r] += sigmoidf_(gz) * v;
;           },
	v_cvt_f32_f16_e32 v68, v196
	v_cvt_f32_f16_e32 v69, v197
	v_add_u32_e32 v96, 0x91000, v94
	global_load_ushort v196, v96, s[40:41]
	v_add_u32_e32 v96, 0x94a00, v94
	global_load_ushort v197, v96, s[40:41]
	v_mul_f32_e32 v68, 0xbfb8aa3b, v68
	v_mul_f32_e32 v69, 0xbfb8aa3b, v69
	v_exp_f32_e32 v68, v68
	v_exp_f32_e32 v69, v69
	s_nop 0
	v_pk_add_f32 v[68:69], v[68:69], 1.0 op_sel_hi:[1,0]
	s_nop 0
	v_div_scale_f32 v70, s[2:3], v69, v69, 1.0
	v_rcp_f32_e32 v71, v70
	s_nop 0
	v_fma_f32 v72, -v70, v71, 1.0
	v_fmac_f32_e32 v71, v72, v71
	v_div_scale_f32 v72, vcc, 1.0, v69, 1.0
	v_mul_f32_e32 v73, v72, v71
	v_fma_f32 v74, -v70, v73, v72
	v_fmac_f32_e32 v73, v74, v71
	v_fma_f32 v70, -v70, v73, v72
	v_div_fmas_f32 v70, v70, v71, v73
	v_div_fixup_f32 v69, v70, v69, 1.0
	v_div_scale_f32 v70, s[2:3], v68, v68, 1.0
	v_rcp_f32_e32 v71, v70
	s_nop 0
	v_fma_f32 v72, -v70, v71, 1.0
	v_fmac_f32_e32 v71, v72, v71
	v_div_scale_f32 v72, vcc, 1.0, v68, 1.0
	v_mul_f32_e32 v73, v72, v71
	v_fma_f32 v74, -v70, v73, v72
	v_fmac_f32_e32 v73, v74, v71
	v_fma_f32 v70, -v70, v73, v72
	v_div_fmas_f32 v70, v70, v71, v73
	v_div_fixup_f32 v68, v70, v68, 1.0
	v_pk_fma_f32 v[156:157], v[54:55], v[68:69], v[156:157]
	s_waitcnt vmcnt(30)
	v_cvt_f32_f16_e32 v68, v198
	v_cvt_f32_f16_e32 v69, v199
	v_add_u32_e32 v96, 0x98400, v94
	global_load_ushort v198, v96, s[40:41]
	v_add_u32_e32 v96, 0x9be00, v94
	global_load_ushort v199, v96, s[40:41]
	v_mul_f32_e32 v68, 0xbfb8aa3b, v68
	v_mul_f32_e32 v69, 0xbfb8aa3b, v69
	v_exp_f32_e32 v68, v68
	v_exp_f32_e32 v69, v69
	s_nop 0
	v_pk_add_f32 v[68:69], v[68:69], 1.0 op_sel_hi:[1,0]
	s_nop 0
	v_div_scale_f32 v70, s[2:3], v69, v69, 1.0
	v_rcp_f32_e32 v71, v70
	s_nop 0
	v_fma_f32 v72, -v70, v71, 1.0
	v_fmac_f32_e32 v71, v72, v71
	v_div_scale_f32 v72, vcc, 1.0, v69, 1.0
	v_mul_f32_e32 v73, v72, v71
	v_fma_f32 v74, -v70, v73, v72
	v_fmac_f32_e32 v73, v74, v71
	v_fma_f32 v70, -v70, v73, v72
	v_div_fmas_f32 v70, v70, v71, v73
	v_div_fixup_f32 v69, v70, v69, 1.0
	v_div_scale_f32 v70, s[2:3], v68, v68, 1.0
	v_rcp_f32_e32 v71, v70
	s_nop 0
	v_fma_f32 v72, -v70, v71, 1.0
	v_fmac_f32_e32 v71, v72, v71
	v_div_scale_f32 v72, vcc, 1.0, v68, 1.0
	v_mul_f32_e32 v73, v72, v71
	v_fma_f32 v74, -v70, v73, v72
	v_fmac_f32_e32 v73, v74, v71
	v_fma_f32 v70, -v70, v73, v72
	v_div_fmas_f32 v70, v70, v71, v73
	v_div_fixup_f32 v68, v70, v68, 1.0
	v_pk_fma_f32 v[154:155], v[56:57], v[68:69], v[154:155]
	s_waitcnt vmcnt(30)
	v_cvt_f32_f16_e32 v68, v200
	v_cvt_f32_f16_e32 v69, v201
	v_add_u32_e32 v96, 0xae000, v94
	global_load_ushort v200, v96, s[40:41]
	v_add_u32_e32 v96, 0xb1a00, v94
	global_load_ushort v201, v96, s[40:41]
	v_mul_f32_e32 v68, 0xbfb8aa3b, v68
	v_mul_f32_e32 v69, 0xbfb8aa3b, v69
	v_exp_f32_e32 v68, v68
	v_exp_f32_e32 v69, v69
	s_nop 0
	v_pk_add_f32 v[68:69], v[68:69], 1.0 op_sel_hi:[1,0]
	s_nop 0
	v_div_scale_f32 v70, s[2:3], v69, v69, 1.0
	v_rcp_f32_e32 v71, v70
	s_nop 0
	v_fma_f32 v72, -v70, v71, 1.0
	v_fmac_f32_e32 v71, v72, v71
	v_div_scale_f32 v72, vcc, 1.0, v69, 1.0
	v_mul_f32_e32 v73, v72, v71
	v_fma_f32 v74, -v70, v73, v72
	v_fmac_f32_e32 v73, v74, v71
	v_fma_f32 v70, -v70, v73, v72
	v_div_fmas_f32 v70, v70, v71, v73
	v_div_fixup_f32 v69, v70, v69, 1.0
	v_div_scale_f32 v70, s[2:3], v68, v68, 1.0
	v_rcp_f32_e32 v71, v70
	s_nop 0
	v_fma_f32 v72, -v70, v71, 1.0
	v_fmac_f32_e32 v71, v72, v71
	v_div_scale_f32 v72, vcc, 1.0, v68, 1.0
	v_mul_f32_e32 v73, v72, v71
	v_fma_f32 v74, -v70, v73, v72
	v_fmac_f32_e32 v73, v74, v71
	v_fma_f32 v70, -v70, v73, v72
	v_div_fmas_f32 v70, v70, v71, v73
	v_div_fixup_f32 v68, v70, v68, 1.0
	v_pk_fma_f32 v[152:153], v[58:59], v[68:69], v[152:153]
	s_waitcnt vmcnt(30)
	v_cvt_f32_f16_e32 v68, v202
	v_cvt_f32_f16_e32 v69, v203
	v_add_u32_e32 v96, 0xb5400, v94
	global_load_ushort v202, v96, s[40:41]
	v_add_u32_e32 v96, 0xb8e00, v94
	global_load_ushort v203, v96, s[40:41]
	v_mul_f32_e32 v68, 0xbfb8aa3b, v68
	v_mul_f32_e32 v69, 0xbfb8aa3b, v69
	v_exp_f32_e32 v68, v68
	v_exp_f32_e32 v69, v69
	s_nop 0
	v_pk_add_f32 v[68:69], v[68:69], 1.0 op_sel_hi:[1,0]
	s_nop 0
	v_div_scale_f32 v70, s[2:3], v69, v69, 1.0
	v_rcp_f32_e32 v71, v70
	s_nop 0
	v_fma_f32 v72, -v70, v71, 1.0
	v_fmac_f32_e32 v71, v72, v71
	v_div_scale_f32 v72, vcc, 1.0, v69, 1.0
	v_mul_f32_e32 v73, v72, v71
	v_fma_f32 v74, -v70, v73, v72
	v_fmac_f32_e32 v73, v74, v71
	v_fma_f32 v70, -v70, v73, v72
	v_div_fmas_f32 v70, v70, v71, v73
	v_div_fixup_f32 v69, v70, v69, 1.0
	v_div_scale_f32 v70, s[2:3], v68, v68, 1.0
	v_rcp_f32_e32 v71, v70
	s_nop 0
	v_fma_f32 v72, -v70, v71, 1.0
	v_fmac_f32_e32 v71, v72, v71
	v_div_scale_f32 v72, vcc, 1.0, v68, 1.0
	v_mul_f32_e32 v73, v72, v71
	v_fma_f32 v74, -v70, v73, v72
	v_fmac_f32_e32 v73, v74, v71
	v_fma_f32 v70, -v70, v73, v72
	v_div_fmas_f32 v70, v70, v71, v73
	v_div_fixup_f32 v68, v70, v68, 1.0
	v_pk_fma_f32 v[150:151], v[60:61], v[68:69], v[150:151]
	s_waitcnt vmcnt(30)
	v_cvt_f32_f16_e32 v68, v204
	v_cvt_f32_f16_e32 v69, v205
	v_add_u32_e32 v96, 0xcb000, v94
	global_load_ushort v204, v96, s[40:41]
	v_add_u32_e32 v96, 0xcea00, v94
	global_load_ushort v205, v96, s[40:41]
	v_mul_f32_e32 v68, 0xbfb8aa3b, v68
	v_mul_f32_e32 v69, 0xbfb8aa3b, v69
	v_exp_f32_e32 v68, v68
	v_exp_f32_e32 v69, v69
	s_nop 0
	v_pk_add_f32 v[68:69], v[68:69], 1.0 op_sel_hi:[1,0]
	s_nop 0
	v_div_scale_f32 v70, s[2:3], v69, v69, 1.0
	v_rcp_f32_e32 v71, v70
	s_nop 0
	v_fma_f32 v72, -v70, v71, 1.0
	v_fmac_f32_e32 v71, v72, v71
	v_div_scale_f32 v72, vcc, 1.0, v69, 1.0
	v_mul_f32_e32 v73, v72, v71
	v_fma_f32 v74, -v70, v73, v72
	v_fmac_f32_e32 v73, v74, v71
	v_fma_f32 v70, -v70, v73, v72
	v_div_fmas_f32 v70, v70, v71, v73
	v_div_fixup_f32 v69, v70, v69, 1.0
	v_div_scale_f32 v70, s[2:3], v68, v68, 1.0
	v_rcp_f32_e32 v71, v70
	s_nop 0
	v_fma_f32 v72, -v70, v71, 1.0
	v_fmac_f32_e32 v71, v72, v71
	v_div_scale_f32 v72, vcc, 1.0, v68, 1.0
	v_mul_f32_e32 v73, v72, v71
	v_fma_f32 v74, -v70, v73, v72
	v_fmac_f32_e32 v73, v74, v71
	v_fma_f32 v70, -v70, v73, v72
	v_div_fmas_f32 v70, v70, v71, v73
	v_div_fixup_f32 v68, v70, v68, 1.0
	v_pk_fma_f32 v[148:149], v[62:63], v[68:69], v[148:149]
	s_waitcnt vmcnt(30)
;   __device__ __forceinline__ const float* x() const { return (const float*)(const __attribute__((address_space(1))) float*)kp[0]; }
; __device__ __forceinline__ float sigmoidf_(float x) { return 1.f / (1.f + __expf(-x)); }
; __device__ __forceinline__ void phase_merge(const KP& p, char* smem, int* q, int xcc) {
;     ...
;           [&](int mi, int ni, int r, int row, int col, float v) {
;             const float gz = (float)G[(size_t)row * NU + col];
;             tot[mi][ni][r] += sigmoidf_(gz) * v;
;           },
	v_cvt_f32_f16_e32 v68, v206
	v_cvt_f32_f16_e32 v69, v207
	v_add_u32_e32 v96, 0xd2400, v94
	global_load_ushort v206, v96, s[40:41]
	v_add_u32_e32 v96, 0xd5e00, v94
	global_load_ushort v207, v96, s[40:41]
	v_mul_f32_e32 v68, 0xbfb8aa3b, v68
	v_mul_f32_e32 v69, 0xbfb8aa3b, v69
	v_exp_f32_e32 v68, v68
	v_exp_f32_e32 v69, v69
	s_nop 0
	v_pk_add_f32 v[68:69], v[68:69], 1.0 op_sel_hi:[1,0]
	s_nop 0
	v_div_scale_f32 v70, s[2:3], v69, v69, 1.0
	v_rcp_f32_e32 v71, v70
	s_nop 0
	v_fma_f32 v72, -v70, v71, 1.0
	v_fmac_f32_e32 v71, v72, v71
	v_div_scale_f32 v72, vcc, 1.0, v69, 1.0
	v_mul_f32_e32 v73, v72, v71
	v_fma_f32 v74, -v70, v73, v72
	v_fmac_f32_e32 v73, v74, v71
	v_fma_f32 v70, -v70, v73, v72
	v_div_fmas_f32 v70, v70, v71, v73
	v_div_fixup_f32 v69, v70, v69, 1.0
	v_div_scale_f32 v70, s[2:3], v68, v68, 1.0
	v_rcp_f32_e32 v71, v70
	s_nop 0
	v_fma_f32 v72, -v70, v71, 1.0
	v_fmac_f32_e32 v71, v72, v71
	v_div_scale_f32 v72, vcc, 1.0, v68, 1.0
	v_mul_f32_e32 v73, v72, v71
	v_fma_f32 v74, -v70, v73, v72
	v_fmac_f32_e32 v73, v74, v71
	v_fma_f32 v70, -v70, v73, v72
	v_div_fmas_f32 v70, v70, v71, v73
	v_div_fixup_f32 v68, v70, v68, 1.0
	v_pk_fma_f32 v[146:147], v[64:65], v[68:69], v[146:147]
	s_waitcnt vmcnt(30)
	v_cvt_f32_f16_e32 v68, v208
	v_cvt_f32_f16_e32 v69, v209
	v_add_u32_e32 v96, 0x74000, v94
	global_load_ushort v208, v96, s[40:41] offset:64
	v_add_u32_e32 v96, 0x77a00, v94
	global_load_ushort v209, v96, s[40:41] offset:64
	v_mul_f32_e32 v68, 0xbfb8aa3b, v68
	v_mul_f32_e32 v69, 0xbfb8aa3b, v69
	v_exp_f32_e32 v68, v68
	v_exp_f32_e32 v69, v69
	s_nop 0
	v_pk_add_f32 v[68:69], v[68:69], 1.0 op_sel_hi:[1,0]
	s_nop 0
	v_div_scale_f32 v70, s[2:3], v69, v69, 1.0
	v_rcp_f32_e32 v71, v70
	s_nop 0
	v_fma_f32 v72, -v70, v71, 1.0
	v_fmac_f32_e32 v71, v72, v71
	v_div_scale_f32 v72, vcc, 1.0, v69, 1.0
	v_mul_f32_e32 v73, v72, v71
	v_fma_f32 v74, -v70, v73, v72
	v_fmac_f32_e32 v73, v74, v71
	v_fma_f32 v70, -v70, v73, v72
	v_div_fmas_f32 v70, v70, v71, v73
	v_div_fixup_f32 v69, v70, v69, 1.0
	v_div_scale_f32 v70, s[2:3], v68, v68, 1.0
	v_rcp_f32_e32 v71, v70
	s_nop 0
	v_fma_f32 v72, -v70, v71, 1.0
	v_fmac_f32_e32 v71, v72, v71
	v_div_scale_f32 v72, vcc, 1.0, v68, 1.0
	v_mul_f32_e32 v73, v72, v71
	v_fma_f32 v74, -v70, v73, v72
	v_fmac_f32_e32 v73, v74, v71
	v_fma_f32 v70, -v70, v73, v72
	v_div_fmas_f32 v70, v70, v71, v73
	v_div_fixup_f32 v68, v70, v68, 1.0
	v_pk_fma_f32 v[144:145], v[34:35], v[68:69], v[144:145]
	s_waitcnt vmcnt(30)
	v_cvt_f32_f16_e32 v68, v210
	v_cvt_f32_f16_e32 v69, v211
	v_add_u32_e32 v96, 0x7b400, v94
	global_load_ushort v210, v96, s[40:41] offset:64
	v_add_u32_e32 v96, 0x7ee00, v94
	global_load_ushort v211, v96, s[40:41] offset:64
	v_mul_f32_e32 v68, 0xbfb8aa3b, v68
	v_mul_f32_e32 v69, 0xbfb8aa3b, v69
	v_exp_f32_e32 v68, v68
	v_exp_f32_e32 v69, v69
	s_nop 0
	v_pk_add_f32 v[68:69], v[68:69], 1.0 op_sel_hi:[1,0]
	s_nop 0
	v_div_scale_f32 v70, s[2:3], v69, v69, 1.0
	v_rcp_f32_e32 v71, v70
	s_nop 0
	v_fma_f32 v72, -v70, v71, 1.0
	v_fmac_f32_e32 v71, v72, v71
	v_div_scale_f32 v72, vcc, 1.0, v69, 1.0
	v_mul_f32_e32 v73, v72, v71
	v_fma_f32 v74, -v70, v73, v72
	v_fmac_f32_e32 v73, v74, v71
	v_fma_f32 v70, -v70, v73, v72
	v_div_fmas_f32 v70, v70, v71, v73
	v_div_fixup_f32 v69, v70, v69, 1.0
	v_div_scale_f32 v70, s[2:3], v68, v68, 1.0
	v_rcp_f32_e32 v71, v70
	s_nop 0
	v_fma_f32 v72, -v70, v71, 1.0
	v_fmac_f32_e32 v71, v72, v71
	v_div_scale_f32 v72, vcc, 1.0, v68, 1.0
	v_mul_f32_e32 v73, v72, v71
	v_fma_f32 v74, -v70, v73, v72
	v_fmac_f32_e32 v73, v74, v71
	v_fma_f32 v70, -v70, v73, v72
	v_div_fmas_f32 v70, v70, v71, v73
	v_div_fixup_f32 v68, v70, v68, 1.0
	v_pk_fma_f32 v[142:143], v[36:37], v[68:69], v[142:143]
	s_waitcnt vmcnt(30)
	v_cvt_f32_f16_e32 v68, v212
	v_cvt_f32_f16_e32 v69, v213
	v_add_u32_e32 v96, 0x91000, v94
	global_load_ushort v212, v96, s[40:41] offset:64
	v_add_u32_e32 v96, 0x94a00, v94
	global_load_ushort v213, v96, s[40:41] offset:64
	v_mul_f32_e32 v68, 0xbfb8aa3b, v68
	v_mul_f32_e32 v69, 0xbfb8aa3b, v69
	v_exp_f32_e32 v68, v68
	v_exp_f32_e32 v69, v69
	s_nop 0
	v_pk_add_f32 v[68:69], v[68:69], 1.0 op_sel_hi:[1,0]
	s_nop 0
	v_div_scale_f32 v70, s[2:3], v69, v69, 1.0
	v_rcp_f32_e32 v71, v70
	s_nop 0
	v_fma_f32 v72, -v70, v71, 1.0
	v_fmac_f32_e32 v71, v72, v71
	v_div_scale_f32 v72, vcc, 1.0, v69, 1.0
	v_mul_f32_e32 v73, v72, v71
	v_fma_f32 v74, -v70, v73, v72
	v_fmac_f32_e32 v73, v74, v71
	v_fma_f32 v70, -v70, v73, v72
	v_div_fmas_f32 v70, v70, v71, v73
	v_div_fixup_f32 v69, v70, v69, 1.0
	v_div_scale_f32 v70, s[2:3], v68, v68, 1.0
	v_rcp_f32_e32 v71, v70
	s_nop 0
	v_fma_f32 v72, -v70, v71, 1.0
	v_fmac_f32_e32 v71, v72, v71
	v_div_scale_f32 v72, vcc, 1.0, v68, 1.0
	v_mul_f32_e32 v73, v72, v71
	v_fma_f32 v74, -v70, v73, v72
	v_fmac_f32_e32 v73, v74, v71
	v_fma_f32 v70, -v70, v73, v72
	v_div_fmas_f32 v70, v70, v71, v73
	v_div_fixup_f32 v68, v70, v68, 1.0
	v_pk_fma_f32 v[140:141], v[38:39], v[68:69], v[140:141]
	s_waitcnt vmcnt(30)
	v_cvt_f32_f16_e32 v68, v214
	v_cvt_f32_f16_e32 v69, v215
	v_add_u32_e32 v96, 0x98400, v94
	global_load_ushort v214, v96, s[40:41] offset:64
	v_add_u32_e32 v96, 0x9be00, v94
	global_load_ushort v215, v96, s[40:41] offset:64
	v_mul_f32_e32 v68, 0xbfb8aa3b, v68
	v_mul_f32_e32 v69, 0xbfb8aa3b, v69
	v_exp_f32_e32 v68, v68
	v_exp_f32_e32 v69, v69
	s_nop 0
	v_pk_add_f32 v[68:69], v[68:69], 1.0 op_sel_hi:[1,0]
	s_nop 0
	v_div_scale_f32 v70, s[2:3], v69, v69, 1.0
	v_rcp_f32_e32 v71, v70
	s_nop 0
	v_fma_f32 v72, -v70, v71, 1.0
	v_fmac_f32_e32 v71, v72, v71
	v_div_scale_f32 v72, vcc, 1.0, v69, 1.0
	v_mul_f32_e32 v73, v72, v71
	v_fma_f32 v74, -v70, v73, v72
	v_fmac_f32_e32 v73, v74, v71
	v_fma_f32 v70, -v70, v73, v72
	v_div_fmas_f32 v70, v70, v71, v73
	v_div_fixup_f32 v69, v70, v69, 1.0
	v_div_scale_f32 v70, s[2:3], v68, v68, 1.0
	v_rcp_f32_e32 v71, v70
	s_nop 0
	v_fma_f32 v72, -v70, v71, 1.0
	v_fmac_f32_e32 v71, v72, v71
	v_div_scale_f32 v72, vcc, 1.0, v68, 1.0
	v_mul_f32_e32 v73, v72, v71
	v_fma_f32 v74, -v70, v73, v72
	v_fmac_f32_e32 v73, v74, v71
	v_fma_f32 v70, -v70, v73, v72
	v_div_fmas_f32 v70, v70, v71, v73
	v_div_fixup_f32 v68, v70, v68, 1.0
	v_pk_fma_f32 v[138:139], v[40:41], v[68:69], v[138:139]
	s_waitcnt vmcnt(30)
;   __device__ __forceinline__ const float* x() const { return (const float*)(const __attribute__((address_space(1))) float*)kp[0]; }
; __device__ __forceinline__ float sigmoidf_(float x) { return 1.f / (1.f + __expf(-x)); }
; __device__ __forceinline__ void phase_merge(const KP& p, char* smem, int* q, int xcc) {
;     ...
;           [&](int mi, int ni, int r, int row, int col, float v) {
;             const float gz = (float)G[(size_t)row * NU + col];
;             tot[mi][ni][r] += sigmoidf_(gz) * v;
;           },
	v_cvt_f32_f16_e32 v68, v216
	v_cvt_f32_f16_e32 v69, v217
	v_add_u32_e32 v96, 0xae000, v94
	global_load_ushort v216, v96, s[40:41] offset:64
	v_add_u32_e32 v96, 0xb1a00, v94
	global_load_ushort v217, v96, s[40:41] offset:64
	v_mul_f32_e32 v68, 0xbfb8aa3b, v68
	v_mul_f32_e32 v69, 0xbfb8aa3b, v69
	v_exp_f32_e32 v68, v68
	v_exp_f32_e32 v69, v69
	s_nop 0
	v_pk_add_f32 v[68:69], v[68:69], 1.0 op_sel_hi:[1,0]
	s_nop 0
	v_div_scale_f32 v70, s[2:3], v69, v69, 1.0
	v_rcp_f32_e32 v71, v70
	s_nop 0
	v_fma_f32 v72, -v70, v71, 1.0
	v_fmac_f32_e32 v71, v72, v71
	v_div_scale_f32 v72, vcc, 1.0, v69, 1.0
	v_mul_f32_e32 v73, v72, v71
	v_fma_f32 v74, -v70, v73, v72
	v_fmac_f32_e32 v73, v74, v71
	v_fma_f32 v70, -v70, v73, v72
	v_div_fmas_f32 v70, v70, v71, v73
	v_div_fixup_f32 v69, v70, v69, 1.0
	v_div_scale_f32 v70, s[2:3], v68, v68, 1.0
	v_rcp_f32_e32 v71, v70
	s_nop 0
	v_fma_f32 v72, -v70, v71, 1.0
	v_fmac_f32_e32 v71, v72, v71
	v_div_scale_f32 v72, vcc, 1.0, v68, 1.0
	v_mul_f32_e32 v73, v72, v71
	v_fma_f32 v74, -v70, v73, v72
	v_fmac_f32_e32 v73, v74, v71
	v_fma_f32 v70, -v70, v73, v72
	v_div_fmas_f32 v70, v70, v71, v73
	v_div_fixup_f32 v68, v70, v68, 1.0
	v_pk_fma_f32 v[136:137], v[42:43], v[68:69], v[136:137]
	s_waitcnt vmcnt(30)
	v_cvt_f32_f16_e32 v68, v218
	v_cvt_f32_f16_e32 v69, v219
	v_add_u32_e32 v96, 0xb5400, v94
	global_load_ushort v218, v96, s[40:41] offset:64
	v_add_u32_e32 v96, 0xb8e00, v94
	global_load_ushort v219, v96, s[40:41] offset:64
	v_mul_f32_e32 v68, 0xbfb8aa3b, v68
	v_mul_f32_e32 v69, 0xbfb8aa3b, v69
	v_exp_f32_e32 v68, v68
	v_exp_f32_e32 v69, v69
	s_nop 0
	v_pk_add_f32 v[68:69], v[68:69], 1.0 op_sel_hi:[1,0]
	s_nop 0
	v_div_scale_f32 v70, s[2:3], v69, v69, 1.0
	v_rcp_f32_e32 v71, v70
	s_nop 0
	v_fma_f32 v72, -v70, v71, 1.0
	v_fmac_f32_e32 v71, v72, v71
	v_div_scale_f32 v72, vcc, 1.0, v69, 1.0
	v_mul_f32_e32 v73, v72, v71
	v_fma_f32 v74, -v70, v73, v72
	v_fmac_f32_e32 v73, v74, v71
	v_fma_f32 v70, -v70, v73, v72
	v_div_fmas_f32 v70, v70, v71, v73
	v_div_fixup_f32 v69, v70, v69, 1.0
	v_div_scale_f32 v70, s[2:3], v68, v68, 1.0
	v_rcp_f32_e32 v71, v70
	s_nop 0
	v_fma_f32 v72, -v70, v71, 1.0
	v_fmac_f32_e32 v71, v72, v71
	v_div_scale_f32 v72, vcc, 1.0, v68, 1.0
	v_mul_f32_e32 v73, v72, v71
	v_fma_f32 v74, -v70, v73, v72
	v_fmac_f32_e32 v73, v74, v71
	v_fma_f32 v70, -v70, v73, v72
	v_div_fmas_f32 v70, v70, v71, v73
	v_div_fixup_f32 v68, v70, v68, 1.0
	v_pk_fma_f32 v[134:135], v[44:45], v[68:69], v[134:135]
	s_waitcnt vmcnt(30)
	v_cvt_f32_f16_e32 v68, v220
	v_cvt_f32_f16_e32 v69, v221
	v_add_u32_e32 v96, 0xcb000, v94
	global_load_ushort v220, v96, s[40:41] offset:64
	v_add_u32_e32 v96, 0xcea00, v94
	global_load_ushort v221, v96, s[40:41] offset:64
	v_mul_f32_e32 v68, 0xbfb8aa3b, v68
	v_mul_f32_e32 v69, 0xbfb8aa3b, v69
	v_exp_f32_e32 v68, v68
	v_exp_f32_e32 v69, v69
	s_nop 0
	v_pk_add_f32 v[68:69], v[68:69], 1.0 op_sel_hi:[1,0]
	s_nop 0
	v_div_scale_f32 v70, s[2:3], v69, v69, 1.0
	v_rcp_f32_e32 v71, v70
	s_nop 0
	v_fma_f32 v72, -v70, v71, 1.0
	v_fmac_f32_e32 v71, v72, v71
	v_div_scale_f32 v72, vcc, 1.0, v69, 1.0
	v_mul_f32_e32 v73, v72, v71
	v_fma_f32 v74, -v70, v73, v72
	v_fmac_f32_e32 v73, v74, v71
	v_fma_f32 v70, -v70, v73, v72
	v_div_fmas_f32 v70, v70, v71, v73
	v_div_fixup_f32 v69, v70, v69, 1.0
	v_div_scale_f32 v70, s[2:3], v68, v68, 1.0
	v_rcp_f32_e32 v71, v70
	s_nop 0
	v_fma_f32 v72, -v70, v71, 1.0
	v_fmac_f32_e32 v71, v72, v71
	v_div_scale_f32 v72, vcc, 1.0, v68, 1.0
	v_mul_f32_e32 v73, v72, v71
	v_fma_f32 v74, -v70, v73, v72
	v_fmac_f32_e32 v73, v74, v71
	v_fma_f32 v70, -v70, v73, v72
	v_div_fmas_f32 v70, v70, v71, v73
	v_div_fixup_f32 v68, v70, v68, 1.0
	v_pk_fma_f32 v[132:133], v[46:47], v[68:69], v[132:133]
	s_waitcnt vmcnt(30)
	v_cvt_f32_f16_e32 v68, v222
	v_cvt_f32_f16_e32 v69, v223
	v_add_u32_e32 v96, 0xd2400, v94
	global_load_ushort v222, v96, s[40:41] offset:64
	v_add_u32_e32 v96, 0xd5e00, v94
	global_load_ushort v223, v96, s[40:41] offset:64
	v_mul_f32_e32 v68, 0xbfb8aa3b, v68
	v_mul_f32_e32 v69, 0xbfb8aa3b, v69
	v_exp_f32_e32 v68, v68
	v_exp_f32_e32 v69, v69
	s_nop 0
	v_pk_add_f32 v[68:69], v[68:69], 1.0 op_sel_hi:[1,0]
	s_nop 0
	v_div_scale_f32 v70, s[2:3], v69, v69, 1.0
	v_rcp_f32_e32 v71, v70
	s_nop 0
	v_fma_f32 v72, -v70, v71, 1.0
	v_fmac_f32_e32 v71, v72, v71
	v_div_scale_f32 v72, vcc, 1.0, v69, 1.0
	v_mul_f32_e32 v73, v72, v71
	v_fma_f32 v74, -v70, v73, v72
	v_fmac_f32_e32 v73, v74, v71
	v_fma_f32 v70, -v70, v73, v72
	v_div_fmas_f32 v70, v70, v71, v73
	v_div_fixup_f32 v69, v70, v69, 1.0
	v_div_scale_f32 v70, s[2:3], v68, v68, 1.0
	v_rcp_f32_e32 v71, v70
	s_nop 0
	v_fma_f32 v72, -v70, v71, 1.0
	v_fmac_f32_e32 v71, v72, v71
	v_div_scale_f32 v72, vcc, 1.0, v68, 1.0
	v_mul_f32_e32 v73, v72, v71
	v_fma_f32 v74, -v70, v73, v72
	v_fmac_f32_e32 v73, v74, v71
	v_fma_f32 v70, -v70, v73, v72
	v_div_fmas_f32 v70, v70, v71, v73
	v_div_fixup_f32 v68, v70, v68, 1.0
	v_pk_fma_f32 v[130:131], v[48:49], v[68:69], v[130:131]
	s_waitcnt vmcnt(30)
	v_cvt_f32_f16_e32 v68, v192
	v_cvt_f32_f16_e32 v69, v193
	v_mul_f32_e32 v68, 0xbfb8aa3b, v68
	v_mul_f32_e32 v69, 0xbfb8aa3b, v69
	v_exp_f32_e32 v68, v68
	v_exp_f32_e32 v69, v69
	s_nop 0
	v_pk_add_f32 v[68:69], v[68:69], 1.0 op_sel_hi:[1,0]
	s_nop 0
	v_div_scale_f32 v70, s[2:3], v69, v69, 1.0
	v_rcp_f32_e32 v71, v70
	s_nop 0
	v_fma_f32 v72, -v70, v71, 1.0
	v_fmac_f32_e32 v71, v72, v71
	v_div_scale_f32 v72, vcc, 1.0, v69, 1.0
	v_mul_f32_e32 v73, v72, v71
	v_fma_f32 v74, -v70, v73, v72
	v_fmac_f32_e32 v73, v74, v71
	v_fma_f32 v70, -v70, v73, v72
	v_div_fmas_f32 v70, v70, v71, v73
	v_div_fixup_f32 v69, v70, v69, 1.0
	v_div_scale_f32 v70, s[2:3], v68, v68, 1.0
	v_rcp_f32_e32 v71, v70
	s_nop 0
	v_fma_f32 v72, -v70, v71, 1.0
	v_fmac_f32_e32 v71, v72, v71
	v_div_scale_f32 v72, vcc, 1.0, v68, 1.0
	v_mul_f32_e32 v73, v72, v71
	v_fma_f32 v74, -v70, v73, v72
	v_fmac_f32_e32 v73, v74, v71
	v_fma_f32 v70, -v70, v73, v72
	v_div_fmas_f32 v70, v70, v71, v73
	v_div_fixup_f32 v68, v70, v68, 1.0
	v_pk_fma_f32 v[128:129], v[18:19], v[68:69], v[128:129]
	s_waitcnt vmcnt(28)
;   __device__ __forceinline__ const float* x() const { return (const float*)(const __attribute__((address_space(1))) float*)kp[0]; }
; __device__ __forceinline__ float sigmoidf_(float x) { return 1.f / (1.f + __expf(-x)); }
; __device__ __forceinline__ void phase_merge(const KP& p, char* smem, int* q, int xcc) {
;     ...
;           [&](int mi, int ni, int r, int row, int col, float v) {
;             const float gz = (float)G[(size_t)row * NU + col];
;             tot[mi][ni][r] += sigmoidf_(gz) * v;
;           },
	v_cvt_f32_f16_e32 v68, v194
	v_cvt_f32_f16_e32 v69, v195
	v_mul_f32_e32 v68, 0xbfb8aa3b, v68
	v_mul_f32_e32 v69, 0xbfb8aa3b, v69
	v_exp_f32_e32 v68, v68
	v_exp_f32_e32 v69, v69
	s_nop 0
	v_pk_add_f32 v[68:69], v[68:69], 1.0 op_sel_hi:[1,0]
	s_nop 0
	v_div_scale_f32 v70, s[2:3], v69, v69, 1.0
	v_rcp_f32_e32 v71, v70
	s_nop 0
	v_fma_f32 v72, -v70, v71, 1.0
	v_fmac_f32_e32 v71, v72, v71
	v_div_scale_f32 v72, vcc, 1.0, v69, 1.0
	v_mul_f32_e32 v73, v72, v71
	v_fma_f32 v74, -v70, v73, v72
	v_fmac_f32_e32 v73, v74, v71
	v_fma_f32 v70, -v70, v73, v72
	v_div_fmas_f32 v70, v70, v71, v73
	v_div_fixup_f32 v69, v70, v69, 1.0
	v_div_scale_f32 v70, s[2:3], v68, v68, 1.0
	v_rcp_f32_e32 v71, v70
	s_nop 0
	v_fma_f32 v72, -v70, v71, 1.0
	v_fmac_f32_e32 v71, v72, v71
	v_div_scale_f32 v72, vcc, 1.0, v68, 1.0
	v_mul_f32_e32 v73, v72, v71
	v_fma_f32 v74, -v70, v73, v72
	v_fmac_f32_e32 v73, v74, v71
	v_fma_f32 v70, -v70, v73, v72
	v_div_fmas_f32 v70, v70, v71, v73
	v_div_fixup_f32 v68, v70, v68, 1.0
	v_pk_fma_f32 v[126:127], v[20:21], v[68:69], v[126:127]
	s_waitcnt vmcnt(26)
	v_cvt_f32_f16_e32 v68, v196
	v_cvt_f32_f16_e32 v69, v197
	v_mul_f32_e32 v68, 0xbfb8aa3b, v68
	v_mul_f32_e32 v69, 0xbfb8aa3b, v69
	v_exp_f32_e32 v68, v68
	v_exp_f32_e32 v69, v69
	s_nop 0
	v_pk_add_f32 v[68:69], v[68:69], 1.0 op_sel_hi:[1,0]
	s_nop 0
	v_div_scale_f32 v70, s[2:3], v69, v69, 1.0
	v_rcp_f32_e32 v71, v70
	s_nop 0
	v_fma_f32 v72, -v70, v71, 1.0
	v_fmac_f32_e32 v71, v72, v71
	v_div_scale_f32 v72, vcc, 1.0, v69, 1.0
	v_mul_f32_e32 v73, v72, v71
	v_fma_f32 v74, -v70, v73, v72
	v_fmac_f32_e32 v73, v74, v71
	v_fma_f32 v70, -v70, v73, v72
	v_div_fmas_f32 v70, v70, v71, v73
	v_div_fixup_f32 v69, v70, v69, 1.0
	v_div_scale_f32 v70, s[2:3], v68, v68, 1.0
	v_rcp_f32_e32 v71, v70
	s_nop 0
	v_fma_f32 v72, -v70, v71, 1.0
	v_fmac_f32_e32 v71, v72, v71
	v_div_scale_f32 v72, vcc, 1.0, v68, 1.0
	v_mul_f32_e32 v73, v72, v71
	v_fma_f32 v74, -v70, v73, v72
	v_fmac_f32_e32 v73, v74, v71
	v_fma_f32 v70, -v70, v73, v72
	v_div_fmas_f32 v70, v70, v71, v73
	v_div_fixup_f32 v68, v70, v68, 1.0
	v_pk_fma_f32 v[124:125], v[22:23], v[68:69], v[124:125]
	s_waitcnt vmcnt(24)
	v_cvt_f32_f16_e32 v68, v198
	v_cvt_f32_f16_e32 v69, v199
	v_mul_f32_e32 v68, 0xbfb8aa3b, v68
	v_mul_f32_e32 v69, 0xbfb8aa3b, v69
	v_exp_f32_e32 v68, v68
	v_exp_f32_e32 v69, v69
	s_nop 0
	v_pk_add_f32 v[68:69], v[68:69], 1.0 op_sel_hi:[1,0]
	s_nop 0
	v_div_scale_f32 v70, s[2:3], v69, v69, 1.0
	v_rcp_f32_e32 v71, v70
	s_nop 0
	v_fma_f32 v72, -v70, v71, 1.0
	v_fmac_f32_e32 v71, v72, v71
	v_div_scale_f32 v72, vcc, 1.0, v69, 1.0
	v_mul_f32_e32 v73, v72, v71
	v_fma_f32 v74, -v70, v73, v72
	v_fmac_f32_e32 v73, v74, v71
	v_fma_f32 v70, -v70, v73, v72
	v_div_fmas_f32 v70, v70, v71, v73
	v_div_fixup_f32 v69, v70, v69, 1.0
	v_div_scale_f32 v70, s[2:3], v68, v68, 1.0
	v_rcp_f32_e32 v71, v70
	s_nop 0
	v_fma_f32 v72, -v70, v71, 1.0
	v_fmac_f32_e32 v71, v72, v71
	v_div_scale_f32 v72, vcc, 1.0, v68, 1.0
	v_mul_f32_e32 v73, v72, v71
	v_fma_f32 v74, -v70, v73, v72
	v_fmac_f32_e32 v73, v74, v71
	v_fma_f32 v70, -v70, v73, v72
	v_div_fmas_f32 v70, v70, v71, v73
	v_div_fixup_f32 v68, v70, v68, 1.0
	v_pk_fma_f32 v[122:123], v[24:25], v[68:69], v[122:123]
	s_waitcnt vmcnt(22)
	v_cvt_f32_f16_e32 v68, v200
	v_cvt_f32_f16_e32 v69, v201
	v_mul_f32_e32 v68, 0xbfb8aa3b, v68
	v_mul_f32_e32 v69, 0xbfb8aa3b, v69
	v_exp_f32_e32 v68, v68
	v_exp_f32_e32 v69, v69
	s_nop 0
	v_pk_add_f32 v[68:69], v[68:69], 1.0 op_sel_hi:[1,0]
	s_nop 0
	v_div_scale_f32 v70, s[2:3], v69, v69, 1.0
	v_rcp_f32_e32 v71, v70
	s_nop 0
	v_fma_f32 v72, -v70, v71, 1.0
	v_fmac_f32_e32 v71, v72, v71
	v_div_scale_f32 v72, vcc, 1.0, v69, 1.0
	v_mul_f32_e32 v73, v72, v71
	v_fma_f32 v74, -v70, v73, v72
	v_fmac_f32_e32 v73, v74, v71
	v_fma_f32 v70, -v70, v73, v72
	v_div_fmas_f32 v70, v70, v71, v73
	v_div_fixup_f32 v69, v70, v69, 1.0
	v_div_scale_f32 v70, s[2:3], v68, v68, 1.0
	v_rcp_f32_e32 v71, v70
	s_nop 0
	v_fma_f32 v72, -v70, v71, 1.0
	v_fmac_f32_e32 v71, v72, v71
	v_div_scale_f32 v72, vcc, 1.0, v68, 1.0
	v_mul_f32_e32 v73, v72, v71
	v_fma_f32 v74, -v70, v73, v72
	v_fmac_f32_e32 v73, v74, v71
	v_fma_f32 v70, -v70, v73, v72
	v_div_fmas_f32 v70, v70, v71, v73
	v_div_fixup_f32 v68, v70, v68, 1.0
	v_pk_fma_f32 v[120:121], v[26:27], v[68:69], v[120:121]
	s_waitcnt vmcnt(20)
	v_cvt_f32_f16_e32 v68, v202
	v_cvt_f32_f16_e32 v69, v203
	v_mul_f32_e32 v68, 0xbfb8aa3b, v68
	v_mul_f32_e32 v69, 0xbfb8aa3b, v69
	v_exp_f32_e32 v68, v68
	v_exp_f32_e32 v69, v69
	s_nop 0
	v_pk_add_f32 v[68:69], v[68:69], 1.0 op_sel_hi:[1,0]
	s_nop 0
	v_div_scale_f32 v70, s[2:3], v69, v69, 1.0
	v_rcp_f32_e32 v71, v70
	s_nop 0
	v_fma_f32 v72, -v70, v71, 1.0
	v_fmac_f32_e32 v71, v72, v71
	v_div_scale_f32 v72, vcc, 1.0, v69, 1.0
	v_mul_f32_e32 v73, v72, v71
	v_fma_f32 v74, -v70, v73, v72
	v_fmac_f32_e32 v73, v74, v71
	v_fma_f32 v70, -v70, v73, v72
	v_div_fmas_f32 v70, v70, v71, v73
	v_div_fixup_f32 v69, v70, v69, 1.0
	v_div_scale_f32 v70, s[2:3], v68, v68, 1.0
	v_rcp_f32_e32 v71, v70
	s_nop 0
	v_fma_f32 v72, -v70, v71, 1.0
	v_fmac_f32_e32 v71, v72, v71
	v_div_scale_f32 v72, vcc, 1.0, v68, 1.0
	v_mul_f32_e32 v73, v72, v71
	v_fma_f32 v74, -v70, v73, v72
	v_fmac_f32_e32 v73, v74, v71
	v_fma_f32 v70, -v70, v73, v72
	v_div_fmas_f32 v70, v70, v71, v73
	v_div_fixup_f32 v68, v70, v68, 1.0
	v_pk_fma_f32 v[118:119], v[28:29], v[68:69], v[118:119]
	s_waitcnt vmcnt(18)
;   __device__ __forceinline__ const float* x() const { return (const float*)(const __attribute__((address_space(1))) float*)kp[0]; }
; __device__ __forceinline__ float sigmoidf_(float x) { return 1.f / (1.f + __expf(-x)); }
; __device__ __forceinline__ void phase_merge(const KP& p, char* smem, int* q, int xcc) {
;     ...
;           [&](int mi, int ni, int r, int row, int col, float v) {
;             const float gz = (float)G[(size_t)row * NU + col];
;             tot[mi][ni][r] += sigmoidf_(gz) * v;
;           },
	v_cvt_f32_f16_e32 v68, v204
	v_cvt_f32_f16_e32 v69, v205
	v_mul_f32_e32 v68, 0xbfb8aa3b, v68
	v_mul_f32_e32 v69, 0xbfb8aa3b, v69
	v_exp_f32_e32 v68, v68
	v_exp_f32_e32 v69, v69
	s_nop 0
	v_pk_add_f32 v[68:69], v[68:69], 1.0 op_sel_hi:[1,0]
	s_nop 0
	v_div_scale_f32 v70, s[2:3], v69, v69, 1.0
	v_rcp_f32_e32 v71, v70
	s_nop 0
	v_fma_f32 v72, -v70, v71, 1.0
	v_fmac_f32_e32 v71, v72, v71
	v_div_scale_f32 v72, vcc, 1.0, v69, 1.0
	v_mul_f32_e32 v73, v72, v71
	v_fma_f32 v74, -v70, v73, v72
	v_fmac_f32_e32 v73, v74, v71
	v_fma_f32 v70, -v70, v73, v72
	v_div_fmas_f32 v70, v70, v71, v73
	v_div_fixup_f32 v69, v70, v69, 1.0
	v_div_scale_f32 v70, s[2:3], v68, v68, 1.0
	v_rcp_f32_e32 v71, v70
	s_nop 0
	v_fma_f32 v72, -v70, v71, 1.0
	v_fmac_f32_e32 v71, v72, v71
	v_div_scale_f32 v72, vcc, 1.0, v68, 1.0
	v_mul_f32_e32 v73, v72, v71
	v_fma_f32 v74, -v70, v73, v72
	v_fmac_f32_e32 v73, v74, v71
	v_fma_f32 v70, -v70, v73, v72
	v_div_fmas_f32 v70, v70, v71, v73
	v_div_fixup_f32 v68, v70, v68, 1.0
	v_pk_fma_f32 v[116:117], v[30:31], v[68:69], v[116:117]
	s_waitcnt vmcnt(16)
	v_cvt_f32_f16_e32 v68, v206
	v_cvt_f32_f16_e32 v69, v207
	v_mul_f32_e32 v68, 0xbfb8aa3b, v68
	v_mul_f32_e32 v69, 0xbfb8aa3b, v69
	v_exp_f32_e32 v68, v68
	v_exp_f32_e32 v69, v69
	s_nop 0
	v_pk_add_f32 v[68:69], v[68:69], 1.0 op_sel_hi:[1,0]
	s_nop 0
	v_div_scale_f32 v70, s[2:3], v69, v69, 1.0
	v_rcp_f32_e32 v71, v70
	s_nop 0
	v_fma_f32 v72, -v70, v71, 1.0
	v_fmac_f32_e32 v71, v72, v71
	v_div_scale_f32 v72, vcc, 1.0, v69, 1.0
	v_mul_f32_e32 v73, v72, v71
	v_fma_f32 v74, -v70, v73, v72
	v_fmac_f32_e32 v73, v74, v71
	v_fma_f32 v70, -v70, v73, v72
	v_div_fmas_f32 v70, v70, v71, v73
	v_div_fixup_f32 v69, v70, v69, 1.0
	v_div_scale_f32 v70, s[2:3], v68, v68, 1.0
	v_rcp_f32_e32 v71, v70
	s_nop 0
	v_fma_f32 v72, -v70, v71, 1.0
	v_fmac_f32_e32 v71, v72, v71
	v_div_scale_f32 v72, vcc, 1.0, v68, 1.0
	v_mul_f32_e32 v73, v72, v71
	v_fma_f32 v74, -v70, v73, v72
	v_fmac_f32_e32 v73, v74, v71
	v_fma_f32 v70, -v70, v73, v72
	v_div_fmas_f32 v70, v70, v71, v73
	v_div_fixup_f32 v68, v70, v68, 1.0
	v_pk_fma_f32 v[114:115], v[32:33], v[68:69], v[114:115]
	s_waitcnt vmcnt(14)
	v_cvt_f32_f16_e32 v68, v208
	v_cvt_f32_f16_e32 v69, v209
	v_mul_f32_e32 v68, 0xbfb8aa3b, v68
	v_mul_f32_e32 v69, 0xbfb8aa3b, v69
	v_exp_f32_e32 v68, v68
	v_exp_f32_e32 v69, v69
	s_nop 0
	v_pk_add_f32 v[68:69], v[68:69], 1.0 op_sel_hi:[1,0]
	s_nop 0
	v_div_scale_f32 v70, s[2:3], v69, v69, 1.0
	v_rcp_f32_e32 v71, v70
	s_nop 0
	v_fma_f32 v72, -v70, v71, 1.0
	v_fmac_f32_e32 v71, v72, v71
	v_div_scale_f32 v72, vcc, 1.0, v69, 1.0
	v_mul_f32_e32 v73, v72, v71
	v_fma_f32 v74, -v70, v73, v72
	v_fmac_f32_e32 v73, v74, v71
	v_fma_f32 v70, -v70, v73, v72
	v_div_fmas_f32 v70, v70, v71, v73
	v_div_fixup_f32 v69, v70, v69, 1.0
	v_div_scale_f32 v70, s[2:3], v68, v68, 1.0
	v_rcp_f32_e32 v71, v70
	s_nop 0
	v_fma_f32 v72, -v70, v71, 1.0
	v_fmac_f32_e32 v71, v72, v71
	v_div_scale_f32 v72, vcc, 1.0, v68, 1.0
	v_mul_f32_e32 v73, v72, v71
	v_fma_f32 v74, -v70, v73, v72
	v_fmac_f32_e32 v73, v74, v71
	v_fma_f32 v70, -v70, v73, v72
	v_div_fmas_f32 v70, v70, v71, v73
	v_div_fixup_f32 v68, v70, v68, 1.0
	v_pk_fma_f32 v[112:113], v[2:3], v[68:69], v[112:113]
	s_waitcnt vmcnt(12)
	v_cvt_f32_f16_e32 v68, v210
	v_cvt_f32_f16_e32 v69, v211
	v_mul_f32_e32 v68, 0xbfb8aa3b, v68
	v_mul_f32_e32 v69, 0xbfb8aa3b, v69
	v_exp_f32_e32 v68, v68
	v_exp_f32_e32 v69, v69
	s_nop 0
	v_pk_add_f32 v[68:69], v[68:69], 1.0 op_sel_hi:[1,0]
	s_nop 0
	v_div_scale_f32 v70, s[2:3], v69, v69, 1.0
	v_rcp_f32_e32 v71, v70
	s_nop 0
	v_fma_f32 v72, -v70, v71, 1.0
	v_fmac_f32_e32 v71, v72, v71
	v_div_scale_f32 v72, vcc, 1.0, v69, 1.0
	v_mul_f32_e32 v73, v72, v71
	v_fma_f32 v74, -v70, v73, v72
	v_fmac_f32_e32 v73, v74, v71
	v_fma_f32 v70, -v70, v73, v72
	v_div_fmas_f32 v70, v70, v71, v73
	v_div_fixup_f32 v69, v70, v69, 1.0
	v_div_scale_f32 v70, s[2:3], v68, v68, 1.0
	v_rcp_f32_e32 v71, v70
	s_nop 0
	v_fma_f32 v72, -v70, v71, 1.0
	v_fmac_f32_e32 v71, v72, v71
	v_div_scale_f32 v72, vcc, 1.0, v68, 1.0
	v_mul_f32_e32 v73, v72, v71
	v_fma_f32 v74, -v70, v73, v72
	v_fmac_f32_e32 v73, v74, v71
	v_fma_f32 v70, -v70, v73, v72
	v_div_fmas_f32 v70, v70, v71, v73
	v_div_fixup_f32 v68, v70, v68, 1.0
	v_pk_fma_f32 v[110:111], v[4:5], v[68:69], v[110:111]
	s_waitcnt vmcnt(10)
	v_cvt_f32_f16_e32 v68, v212
	v_cvt_f32_f16_e32 v69, v213
	v_mul_f32_e32 v68, 0xbfb8aa3b, v68
	v_mul_f32_e32 v69, 0xbfb8aa3b, v69
	v_exp_f32_e32 v68, v68
	v_exp_f32_e32 v69, v69
	s_nop 0
	v_pk_add_f32 v[68:69], v[68:69], 1.0 op_sel_hi:[1,0]
	s_nop 0
	v_div_scale_f32 v70, s[2:3], v69, v69, 1.0
	v_rcp_f32_e32 v71, v70
	s_nop 0
	v_fma_f32 v72, -v70, v71, 1.0
	v_fmac_f32_e32 v71, v72, v71
	v_div_scale_f32 v72, vcc, 1.0, v69, 1.0
	v_mul_f32_e32 v73, v72, v71
	v_fma_f32 v74, -v70, v73, v72
	v_fmac_f32_e32 v73, v74, v71
	v_fma_f32 v70, -v70, v73, v72
	v_div_fmas_f32 v70, v70, v71, v73
	v_div_fixup_f32 v69, v70, v69, 1.0
	v_div_scale_f32 v70, s[2:3], v68, v68, 1.0
	v_rcp_f32_e32 v71, v70
	s_nop 0
	v_fma_f32 v72, -v70, v71, 1.0
	v_fmac_f32_e32 v71, v72, v71
	v_div_scale_f32 v72, vcc, 1.0, v68, 1.0
	v_mul_f32_e32 v73, v72, v71
	v_fma_f32 v74, -v70, v73, v72
	v_fmac_f32_e32 v73, v74, v71
	v_fma_f32 v70, -v70, v73, v72
	v_div_fmas_f32 v70, v70, v71, v73
	v_div_fixup_f32 v68, v70, v68, 1.0
	v_pk_fma_f32 v[108:109], v[6:7], v[68:69], v[108:109]
	s_waitcnt vmcnt(8)
;   __device__ __forceinline__ const float* x() const { return (const float*)(const __attribute__((address_space(1))) float*)kp[0]; }
; __device__ __forceinline__ float sigmoidf_(float x) { return 1.f / (1.f + __expf(-x)); }
; __device__ __forceinline__ void phase_merge(const KP& p, char* smem, int* q, int xcc) {
;     ...
;           [&](int mi, int ni, int r, int row, int col, float v) {
;             const float gz = (float)G[(size_t)row * NU + col];
;             tot[mi][ni][r] += sigmoidf_(gz) * v;
;           },
	v_cvt_f32_f16_e32 v68, v214
	v_cvt_f32_f16_e32 v69, v215
	v_mul_f32_e32 v68, 0xbfb8aa3b, v68
	v_mul_f32_e32 v69, 0xbfb8aa3b, v69
	v_exp_f32_e32 v68, v68
	v_exp_f32_e32 v69, v69
	s_nop 0
	v_pk_add_f32 v[68:69], v[68:69], 1.0 op_sel_hi:[1,0]
	s_nop 0
	v_div_scale_f32 v70, s[2:3], v69, v69, 1.0
	v_rcp_f32_e32 v71, v70
	s_nop 0
	v_fma_f32 v72, -v70, v71, 1.0
	v_fmac_f32_e32 v71, v72, v71
	v_div_scale_f32 v72, vcc, 1.0, v69, 1.0
	v_mul_f32_e32 v73, v72, v71
	v_fma_f32 v74, -v70, v73, v72
	v_fmac_f32_e32 v73, v74, v71
	v_fma_f32 v70, -v70, v73, v72
	v_div_fmas_f32 v70, v70, v71, v73
	v_div_fixup_f32 v69, v70, v69, 1.0
	v_div_scale_f32 v70, s[2:3], v68, v68, 1.0
	v_rcp_f32_e32 v71, v70
	s_nop 0
	v_fma_f32 v72, -v70, v71, 1.0
	v_fmac_f32_e32 v71, v72, v71
	v_div_scale_f32 v72, vcc, 1.0, v68, 1.0
	v_mul_f32_e32 v73, v72, v71
	v_fma_f32 v74, -v70, v73, v72
	v_fmac_f32_e32 v73, v74, v71
	v_fma_f32 v70, -v70, v73, v72
	v_div_fmas_f32 v70, v70, v71, v73
	v_div_fixup_f32 v68, v70, v68, 1.0
	v_pk_fma_f32 v[106:107], v[8:9], v[68:69], v[106:107]
	s_waitcnt vmcnt(6)
	v_cvt_f32_f16_e32 v68, v216
	v_cvt_f32_f16_e32 v69, v217
	v_mul_f32_e32 v68, 0xbfb8aa3b, v68
	v_mul_f32_e32 v69, 0xbfb8aa3b, v69
	v_exp_f32_e32 v68, v68
	v_exp_f32_e32 v69, v69
	s_nop 0
	v_pk_add_f32 v[68:69], v[68:69], 1.0 op_sel_hi:[1,0]
	s_nop 0
	v_div_scale_f32 v70, s[2:3], v69, v69, 1.0
	v_rcp_f32_e32 v71, v70
	s_nop 0
	v_fma_f32 v72, -v70, v71, 1.0
	v_fmac_f32_e32 v71, v72, v71
	v_div_scale_f32 v72, vcc, 1.0, v69, 1.0
	v_mul_f32_e32 v73, v72, v71
	v_fma_f32 v74, -v70, v73, v72
	v_fmac_f32_e32 v73, v74, v71
	v_fma_f32 v70, -v70, v73, v72
	v_div_fmas_f32 v70, v70, v71, v73
	v_div_fixup_f32 v69, v70, v69, 1.0
	v_div_scale_f32 v70, s[2:3], v68, v68, 1.0
	v_rcp_f32_e32 v71, v70
	s_nop 0
	v_fma_f32 v72, -v70, v71, 1.0
	v_fmac_f32_e32 v71, v72, v71
	v_div_scale_f32 v72, vcc, 1.0, v68, 1.0
	v_mul_f32_e32 v73, v72, v71
	v_fma_f32 v74, -v70, v73, v72
	v_fmac_f32_e32 v73, v74, v71
	v_fma_f32 v70, -v70, v73, v72
	v_div_fmas_f32 v70, v70, v71, v73
	v_div_fixup_f32 v68, v70, v68, 1.0
	v_pk_fma_f32 v[104:105], v[10:11], v[68:69], v[104:105]
	s_waitcnt vmcnt(4)
	v_cvt_f32_f16_e32 v68, v218
	v_cvt_f32_f16_e32 v69, v219
	v_mul_f32_e32 v68, 0xbfb8aa3b, v68
	v_mul_f32_e32 v69, 0xbfb8aa3b, v69
	v_exp_f32_e32 v68, v68
	v_exp_f32_e32 v69, v69
	s_nop 0
	v_pk_add_f32 v[68:69], v[68:69], 1.0 op_sel_hi:[1,0]
	s_nop 0
	v_div_scale_f32 v70, s[2:3], v69, v69, 1.0
	v_rcp_f32_e32 v71, v70
	s_nop 0
	v_fma_f32 v72, -v70, v71, 1.0
	v_fmac_f32_e32 v71, v72, v71
	v_div_scale_f32 v72, vcc, 1.0, v69, 1.0
	v_mul_f32_e32 v73, v72, v71
	v_fma_f32 v74, -v70, v73, v72
	v_fmac_f32_e32 v73, v74, v71
	v_fma_f32 v70, -v70, v73, v72
	v_div_fmas_f32 v70, v70, v71, v73
	v_div_fixup_f32 v69, v70, v69, 1.0
	v_div_scale_f32 v70, s[2:3], v68, v68, 1.0
	v_rcp_f32_e32 v71, v70
	s_nop 0
	v_fma_f32 v72, -v70, v71, 1.0
	v_fmac_f32_e32 v71, v72, v71
	v_div_scale_f32 v72, vcc, 1.0, v68, 1.0
	v_mul_f32_e32 v73, v72, v71
	v_fma_f32 v74, -v70, v73, v72
	v_fmac_f32_e32 v73, v74, v71
	v_fma_f32 v70, -v70, v73, v72
	v_div_fmas_f32 v70, v70, v71, v73
	v_div_fixup_f32 v68, v70, v68, 1.0
	v_pk_fma_f32 v[102:103], v[12:13], v[68:69], v[102:103]
	s_waitcnt vmcnt(2)
	v_cvt_f32_f16_e32 v68, v220
	v_cvt_f32_f16_e32 v69, v221
	v_mul_f32_e32 v68, 0xbfb8aa3b, v68
	v_mul_f32_e32 v69, 0xbfb8aa3b, v69
	v_exp_f32_e32 v68, v68
	v_exp_f32_e32 v69, v69
	s_nop 0
	v_pk_add_f32 v[68:69], v[68:69], 1.0 op_sel_hi:[1,0]
	s_nop 0
	v_div_scale_f32 v70, s[2:3], v69, v69, 1.0
	v_rcp_f32_e32 v71, v70
	s_nop 0
	v_fma_f32 v72, -v70, v71, 1.0
	v_fmac_f32_e32 v71, v72, v71
	v_div_scale_f32 v72, vcc, 1.0, v69, 1.0
	v_mul_f32_e32 v73, v72, v71
	v_fma_f32 v74, -v70, v73, v72
	v_fmac_f32_e32 v73, v74, v71
	v_fma_f32 v70, -v70, v73, v72
	v_div_fmas_f32 v70, v70, v71, v73
	v_div_fixup_f32 v69, v70, v69, 1.0
	v_div_scale_f32 v70, s[2:3], v68, v68, 1.0
	v_rcp_f32_e32 v71, v70
	s_nop 0
	v_fma_f32 v72, -v70, v71, 1.0
	v_fmac_f32_e32 v71, v72, v71
	v_div_scale_f32 v72, vcc, 1.0, v68, 1.0
	v_mul_f32_e32 v73, v72, v71
	v_fma_f32 v74, -v70, v73, v72
	v_fmac_f32_e32 v73, v74, v71
	v_fma_f32 v70, -v70, v73, v72
	v_div_fmas_f32 v70, v70, v71, v73
	v_div_fixup_f32 v68, v70, v68, 1.0
	v_pk_fma_f32 v[100:101], v[14:15], v[68:69], v[100:101]
	s_waitcnt vmcnt(0)
	v_cvt_f32_f16_e32 v68, v222
	v_cvt_f32_f16_e32 v69, v223
	v_mul_f32_e32 v68, 0xbfb8aa3b, v68
	v_mul_f32_e32 v69, 0xbfb8aa3b, v69
	v_exp_f32_e32 v68, v68
	v_exp_f32_e32 v69, v69
	s_nop 0
	v_pk_add_f32 v[68:69], v[68:69], 1.0 op_sel_hi:[1,0]
	s_nop 0
	v_div_scale_f32 v70, s[2:3], v69, v69, 1.0
	v_rcp_f32_e32 v71, v70
	s_nop 0
	v_fma_f32 v72, -v70, v71, 1.0
	v_fmac_f32_e32 v71, v72, v71
	v_div_scale_f32 v72, vcc, 1.0, v69, 1.0
	v_mul_f32_e32 v73, v72, v71
	v_fma_f32 v74, -v70, v73, v72
	v_fmac_f32_e32 v73, v74, v71
	v_fma_f32 v70, -v70, v73, v72
	v_div_fmas_f32 v70, v70, v71, v73
	v_div_fixup_f32 v69, v70, v69, 1.0
	v_div_scale_f32 v70, s[2:3], v68, v68, 1.0
	v_rcp_f32_e32 v71, v70
	s_nop 0
	v_fma_f32 v72, -v70, v71, 1.0
	v_fmac_f32_e32 v71, v72, v71
	v_div_scale_f32 v72, vcc, 1.0, v68, 1.0
	v_mul_f32_e32 v73, v72, v71
	v_fma_f32 v74, -v70, v73, v72
	v_fmac_f32_e32 v73, v74, v71
	v_fma_f32 v70, -v70, v73, v72
	v_div_fmas_f32 v70, v70, v71, v73
	v_div_fixup_f32 v68, v70, v68, 1.0
	v_pk_fma_f32 v[98:99], v[16:17], v[68:69], v[98:99]
	s_cmp_lg_u32 s56, 3
	s_cbranch_scc1 .LBB0_1742
;   __device__ __forceinline__ const float* x() const { return (const float*)(const __attribute__((address_space(1))) float*)kp[0]; }
;   __device__ __forceinline__ half_t* mm() const { return (half_t*)(ws() + OFF_mm); }
; __device__ __forceinline__ void phase_merge(const KP& p, char* smem, int* q, int xcc) {
;     ...
;     int tidx = threadIdx.x;
;     asm volatile("" : "+v"(tidx));
;     const int lane = tidx & 63, wid = tidx >> 6, wm = wid >> 1, wn = wid & 1;
; #pragma unroll
;     for (int mi = 0; mi < 2; ++mi)
; #pragma unroll
;       for (int ni = 0; ni < 2; ++ni)
; #pragma unroll
;         for (int r = 0; r < 16; ++r) {
;           const int row = wm * 64 + mi * 32 + (r & 3) + 8 * (r >> 2) + 4 * (lane >> 5);
;           const int col = wn * 64 + ni * 32 + (lane & 31);
;           p.mm()[(size_t)(m0 + row) * DM + n0 + col] = (half_t)tot[mi][ni][r];
;         }
	v_mov_b32_e32 v0, v224
	v_ashrrev_i32_e32 v2, 1, v0
	v_and_b32_e32 v2, 0xffffffc0, v2
	v_lshrrev_b32_e32 v3, 3, v0
	v_add_u32_e32 v2, s14, v2
	v_and_or_b32 v2, v3, 4, v2
	v_and_b32_e32 v3, 31, v0
	v_bfe_u32 v4, v0, 6, 1
	v_lshlrev_b32_e32 v3, 1, v3
	v_lshl_or_b32 v3, v4, 21, v3
	v_lshl_add_u32 v4, v2, 6, v3
	s_lshr_b32 s2, s18, 6
	s_lshl_b32 s2, s2, 20
	s_add_u32 s2, s44, s2
	s_addc_u32 s3, s45, 0
	s_add_u32 s40, s2, 0x100000
	s_addc_u32 s41, s3, 0
	v_cvt_f16_f32_e32 v5, v160
	global_store_short v4, v5, s[2:3]
	v_cvt_f16_f32_e32 v6, v161
	global_store_short v4, v6, s[2:3] offset:64
	v_cvt_f16_f32_e32 v7, v158
	global_store_short v4, v7, s[2:3] offset:128
	v_cvt_f16_f32_e32 v8, v159
	global_store_short v4, v8, s[2:3] offset:192
	v_cvt_f16_f32_e32 v9, v156
	global_store_short v4, v9, s[2:3] offset:512
	v_cvt_f16_f32_e32 v10, v157
	global_store_short v4, v10, s[2:3] offset:576
	v_cvt_f16_f32_e32 v11, v154
	global_store_short v4, v11, s[2:3] offset:640
	v_cvt_f16_f32_e32 v12, v155
	global_store_short v4, v12, s[2:3] offset:704
	v_cvt_f16_f32_e32 v5, v152
	global_store_short v4, v5, s[2:3] offset:1024
	v_cvt_f16_f32_e32 v6, v153
	global_store_short v4, v6, s[2:3] offset:1088
	v_cvt_f16_f32_e32 v7, v150
	global_store_short v4, v7, s[2:3] offset:1152
	v_cvt_f16_f32_e32 v8, v151
	global_store_short v4, v8, s[2:3] offset:1216
	v_cvt_f16_f32_e32 v9, v148
	global_store_short v4, v9, s[2:3] offset:1536
	v_cvt_f16_f32_e32 v10, v149
	global_store_short v4, v10, s[2:3] offset:1600
	v_cvt_f16_f32_e32 v11, v146
	global_store_short v4, v11, s[2:3] offset:1664
	v_cvt_f16_f32_e32 v12, v147
	global_store_short v4, v12, s[2:3] offset:1728
	v_cvt_f16_f32_e32 v5, v144
	global_store_short v4, v5, s[40:41]
	v_cvt_f16_f32_e32 v6, v145
	global_store_short v4, v6, s[40:41] offset:64
	v_cvt_f16_f32_e32 v7, v142
	global_store_short v4, v7, s[40:41] offset:128
	v_cvt_f16_f32_e32 v8, v143
	global_store_short v4, v8, s[40:41] offset:192
	v_cvt_f16_f32_e32 v9, v140
	global_store_short v4, v9, s[40:41] offset:512
	v_cvt_f16_f32_e32 v10, v141
	global_store_short v4, v10, s[40:41] offset:576
	v_cvt_f16_f32_e32 v11, v138
	global_store_short v4, v11, s[40:41] offset:640
	v_cvt_f16_f32_e32 v12, v139
	global_store_short v4, v12, s[40:41] offset:704
	v_cvt_f16_f32_e32 v5, v136
	global_store_short v4, v5, s[40:41] offset:1024
	v_cvt_f16_f32_e32 v6, v137
	global_store_short v4, v6, s[40:41] offset:1088
	v_cvt_f16_f32_e32 v7, v134
	global_store_short v4, v7, s[40:41] offset:1152
	v_cvt_f16_f32_e32 v8, v135
	global_store_short v4, v8, s[40:41] offset:1216
	v_cvt_f16_f32_e32 v9, v132
	global_store_short v4, v9, s[40:41] offset:1536
	v_cvt_f16_f32_e32 v10, v133
	global_store_short v4, v10, s[40:41] offset:1600
	v_cvt_f16_f32_e32 v11, v130
	global_store_short v4, v11, s[40:41] offset:1664
	v_cvt_f16_f32_e32 v12, v131
	global_store_short v4, v12, s[40:41] offset:1728
	v_cvt_f16_f32_e32 v5, v128
	global_store_short v4, v5, s[2:3] offset:2048
	v_cvt_f16_f32_e32 v6, v129
	global_store_short v4, v6, s[2:3] offset:2112
	v_cvt_f16_f32_e32 v7, v126
	global_store_short v4, v7, s[2:3] offset:2176
	v_cvt_f16_f32_e32 v8, v127
	global_store_short v4, v8, s[2:3] offset:2240
	v_cvt_f16_f32_e32 v9, v124
	global_store_short v4, v9, s[2:3] offset:2560
	v_cvt_f16_f32_e32 v10, v125
	global_store_short v4, v10, s[2:3] offset:2624
	v_cvt_f16_f32_e32 v11, v122
	global_store_short v4, v11, s[2:3] offset:2688
	v_cvt_f16_f32_e32 v12, v123
	global_store_short v4, v12, s[2:3] offset:2752
	v_cvt_f16_f32_e32 v5, v120
	global_store_short v4, v5, s[2:3] offset:3072
	v_cvt_f16_f32_e32 v6, v121
	global_store_short v4, v6, s[2:3] offset:3136
	v_cvt_f16_f32_e32 v7, v118
	global_store_short v4, v7, s[2:3] offset:3200
	v_cvt_f16_f32_e32 v8, v119
	global_store_short v4, v8, s[2:3] offset:3264
	v_cvt_f16_f32_e32 v9, v116
	global_store_short v4, v9, s[2:3] offset:3584
	v_cvt_f16_f32_e32 v10, v117
	global_store_short v4, v10, s[2:3] offset:3648
	v_cvt_f16_f32_e32 v11, v114
	global_store_short v4, v11, s[2:3] offset:3712
	v_cvt_f16_f32_e32 v12, v115
	global_store_short v4, v12, s[2:3] offset:3776
	v_cvt_f16_f32_e32 v5, v112
	global_store_short v4, v5, s[40:41] offset:2048
	v_cvt_f16_f32_e32 v6, v113
	global_store_short v4, v6, s[40:41] offset:2112
	v_cvt_f16_f32_e32 v7, v110
	global_store_short v4, v7, s[40:41] offset:2176
	v_cvt_f16_f32_e32 v8, v111
	global_store_short v4, v8, s[40:41] offset:2240
	v_cvt_f16_f32_e32 v9, v108
	global_store_short v4, v9, s[40:41] offset:2560
	v_cvt_f16_f32_e32 v10, v109
	global_store_short v4, v10, s[40:41] offset:2624
	v_cvt_f16_f32_e32 v11, v106
	global_store_short v4, v11, s[40:41] offset:2688
	v_cvt_f16_f32_e32 v12, v107
	global_store_short v4, v12, s[40:41] offset:2752
	v_cvt_f16_f32_e32 v5, v104
	global_store_short v4, v5, s[40:41] offset:3072
	v_cvt_f16_f32_e32 v6, v105
	global_store_short v4, v6, s[40:41] offset:3136
	v_cvt_f16_f32_e32 v7, v102
	global_store_short v4, v7, s[40:41] offset:3200
	v_cvt_f16_f32_e32 v8, v103
	global_store_short v4, v8, s[40:41] offset:3264
	v_cvt_f16_f32_e32 v9, v100
	global_store_short v4, v9, s[40:41] offset:3584
	v_cvt_f16_f32_e32 v10, v101
	global_store_short v4, v10, s[40:41] offset:3648
	v_cvt_f16_f32_e32 v11, v98
	global_store_short v4, v11, s[40:41] offset:3712
	v_cvt_f16_f32_e32 v12, v99
	global_store_short v4, v12, s[40:41] offset:3776
	s_branch .LBB0_1731

;   __device__ __forceinline__ half_t* woT() const { return (half_t*)(ws() + OFF_woT); }
;   __device__ __forceinline__ half_t* mm() const { return (half_t*)(ws() + OFF_mm); }
; template <class LA, class LB, class EP>
; __device__ __forceinline__ void gemm_tile_big(int K, LA loadA, LB loadB, EP epi, char* smem) {
;     ...
;   f32x16 acc[4][2];
; #pragma unroll
;   for (int i = 0; i < 4; ++i)
; #pragma unroll
;     for (int j = 0; j < 2; ++j)
; #pragma unroll
;       for (int r = 0; r < 16; ++r) acc[i][j][r] = 0.f;
;   const int lr = tid >> 3, lc = (tid & 7) * 8;
;   uint4 ra[8], rb[4];
; #pragma unroll
;   for (int i = 0; i < 8; ++i) ra[i] = loadA(lr + 32 * i, lc);
; #pragma unroll
;   for (int i = 0; i < 4; ++i) rb[i] = loadB(lr + 32 * i, lc);
;   const int nk = K >> 6;
;   for (int kt = 0; kt < nk; ++kt) {
;     __syncthreads();
; #pragma unroll
;     for (int i = 0; i < 8; ++i) *(uint4*)&sA[(lr + 32 * i) * 72 + lc] = ra[i];
; #pragma unroll
;     for (int i = 0; i < 4; ++i) *(uint4*)&sB[(lr + 32 * i) * 72 + lc] = rb[i];
;     __syncthreads();
; __device__ __forceinline__ void phase_outproj(const KP& p, char* smem, int* q, int xcc) {
;   xcd_schedule(q, xcc, 8, 64, smem, [&](int grp, int within) __attribute__((always_inline)) {
;     const int mt = grp * 8 + (within & 7), nt = (within >> 3);
;     const int m0 = mt * 256, n0 = nt * 128;
;     const half_t* A = p.mm() + (size_t)m0 * DM;
;     const half_t* B = p.woT() + (size_t)n0 * DM;
;     gemm_tile_big(
;         DM, [&](int r, int k) { return *(const uint4*)(A + (size_t)r * DM + k); },
;         [&](int r, int k) { return *(const uint4*)(B + (size_t)r * DM + k); },
.LBB0_1815:
	s_lshl_b32 s2, s14, 6
	s_sub_i32 s2, s15, s2
	s_lshl_b32 s15, s2, 8
	s_lshl_b32 s3, s38, 11
	s_and_b32 s15, s15, 0x700
	s_or_b32 s40, s3, s15
	s_lshl_b32 s2, s2, 4
	s_ashr_i32 s41, s40, 31
	v_mov_b32_e32 v193, v224
	s_and_b32 s38, s2, 0xffffff80
	s_lshl_b64 s[2:3], s[40:41], 11
	v_mov_b32_e32 v2, 0
	v_mov_b32_e32 v3, v2
	v_mov_b32_e32 v4, v2
	v_mov_b32_e32 v5, v2
	v_mov_b32_e32 v6, v2
	v_mov_b32_e32 v7, v2
	v_mov_b32_e32 v8, v2
	v_mov_b32_e32 v9, v2
	v_mov_b32_e32 v10, v2
	v_mov_b32_e32 v11, v2
	v_mov_b32_e32 v12, v2
	v_mov_b32_e32 v13, v2
	v_mov_b32_e32 v14, v2
	v_mov_b32_e32 v15, v2
	v_mov_b32_e32 v16, v2
	v_mov_b32_e32 v17, v2
	v_mov_b32_e32 v18, v2
	v_mov_b32_e32 v19, v2
	v_mov_b32_e32 v20, v2
	v_mov_b32_e32 v21, v2
	v_mov_b32_e32 v22, v2
	v_mov_b32_e32 v23, v2
	v_mov_b32_e32 v24, v2
	v_mov_b32_e32 v25, v2
	v_mov_b32_e32 v26, v2
	v_mov_b32_e32 v27, v2
	v_mov_b32_e32 v28, v2
	v_mov_b32_e32 v29, v2
	v_mov_b32_e32 v30, v2
	v_mov_b32_e32 v31, v2
	v_mov_b32_e32 v32, v2
	v_mov_b32_e32 v33, v2
	v_mov_b32_e32 v34, v2
	v_mov_b32_e32 v35, v2
	v_mov_b32_e32 v36, v2
	v_mov_b32_e32 v37, v2
	v_mov_b32_e32 v38, v2
	v_mov_b32_e32 v39, v2
	v_mov_b32_e32 v40, v2
	v_mov_b32_e32 v41, v2
	v_mov_b32_e32 v42, v2
	v_mov_b32_e32 v43, v2
	v_mov_b32_e32 v44, v2
	v_mov_b32_e32 v45, v2
	v_mov_b32_e32 v46, v2
	v_mov_b32_e32 v47, v2
	v_mov_b32_e32 v48, v2
	v_mov_b32_e32 v49, v2
	v_mov_b32_e32 v50, v2
	v_mov_b32_e32 v51, v2
	v_mov_b32_e32 v52, v2
	v_mov_b32_e32 v53, v2
	v_mov_b32_e32 v54, v2
	v_mov_b32_e32 v55, v2
	v_mov_b32_e32 v56, v2
	v_mov_b32_e32 v57, v2
	v_mov_b32_e32 v58, v2
	v_mov_b32_e32 v59, v2
	v_mov_b32_e32 v60, v2
	v_mov_b32_e32 v61, v2
	v_mov_b32_e32 v62, v2
	v_mov_b32_e32 v63, v2
	v_mov_b32_e32 v64, v2
	v_mov_b32_e32 v65, v2
	v_mov_b32_e32 v66, v2
	v_mov_b32_e32 v67, v2
	v_mov_b32_e32 v68, v2
	v_mov_b32_e32 v69, v2
	v_mov_b32_e32 v70, v2
	v_mov_b32_e32 v71, v2
	v_mov_b32_e32 v72, v2
	v_mov_b32_e32 v73, v2
	v_mov_b32_e32 v74, v2
	v_mov_b32_e32 v75, v2
	v_mov_b32_e32 v76, v2
	v_mov_b32_e32 v77, v2
	v_mov_b32_e32 v78, v2
	v_mov_b32_e32 v79, v2
	v_mov_b32_e32 v80, v2
	v_mov_b32_e32 v81, v2
	v_mov_b32_e32 v82, v2
	v_mov_b32_e32 v83, v2
	v_mov_b32_e32 v84, v2
	v_mov_b32_e32 v85, v2
	v_mov_b32_e32 v86, v2
	v_mov_b32_e32 v87, v2
	v_mov_b32_e32 v88, v2
	v_mov_b32_e32 v89, v2
	v_mov_b32_e32 v90, v2
	v_mov_b32_e32 v91, v2
	v_mov_b32_e32 v92, v2
	v_mov_b32_e32 v93, v2
	v_mov_b32_e32 v94, v2
	v_mov_b32_e32 v95, v2
	v_mov_b32_e32 v96, v2
	v_mov_b32_e32 v97, v2
	v_mov_b32_e32 v98, v2
	v_mov_b32_e32 v99, v2
	v_mov_b32_e32 v100, v2
	v_mov_b32_e32 v101, v2
	v_mov_b32_e32 v102, v2
	v_mov_b32_e32 v103, v2
	v_mov_b32_e32 v104, v2
	v_mov_b32_e32 v105, v2
	v_mov_b32_e32 v106, v2
	v_mov_b32_e32 v107, v2
	v_mov_b32_e32 v108, v2
	v_mov_b32_e32 v109, v2
	v_mov_b32_e32 v110, v2
	v_mov_b32_e32 v111, v2
	v_mov_b32_e32 v112, v2
	v_mov_b32_e32 v113, v2
	v_mov_b32_e32 v114, v2
	v_mov_b32_e32 v115, v2
	v_mov_b32_e32 v116, v2
	v_mov_b32_e32 v117, v2
	v_mov_b32_e32 v118, v2
	v_mov_b32_e32 v119, v2
	v_mov_b32_e32 v120, v2
	v_mov_b32_e32 v121, v2
	v_mov_b32_e32 v122, v2
	v_mov_b32_e32 v123, v2
	v_mov_b32_e32 v124, v2
	v_mov_b32_e32 v125, v2
	v_mov_b32_e32 v126, v2
	v_mov_b32_e32 v127, v2
	v_mov_b32_e32 v128, v2
	v_mov_b32_e32 v129, v2
	v_lshrrev_b32_e32 v208, 2, v224
	v_and_b32_e32 v209, 3, v224
	v_lshlrev_b32_e32 v210, 11, v208
	v_mul_u32_u24_e32 v196, 0x50, v208
	v_lshl_add_u32 v196, v209, 4, v196
	v_lshlrev_b32_e32 v208, 4, v224
	v_add_u32_e32 v209, 0x1000, v208
	v_add_u32_e32 v210, 0x2000, v208
	v_add_u32_e32 v211, 0x3000, v208
	v_lshrrev_b32_e32 v178, 7, v224
	v_and_b32_e32 v179, 31, v224
	v_lshl_or_b32 v178, v178, 7, v179
	v_mul_u32_u24_e32 v178, 0x50, v178
	v_bfe_u32 v212, v224, 5, 1
	v_lshl_add_u32 v178, v212, 4, v178
	v_bfe_u32 v213, v224, 6, 1
	v_lshl_or_b32 v179, v213, 6, v179
	v_mul_u32_u24_e32 v179, 0x50, v179
	v_lshl_add_u32 v179, v212, 4, v179
	s_lshl_b64 s[2:3], s[40:41], 6
	s_add_u32 s52, s44, s2
	s_addc_u32 s53, s45, s3
	s_ashr_i32 s39, s38, 31
	s_lshl_b64 s[2:3], s[38:39], 6
	s_add_u32 s42, s46, s2
	s_addc_u32 s43, s47, s3
	global_load_dwordx4 v[130:133], v208, s[52:53] sc1
	global_load_dwordx4 v[134:137], v209, s[52:53] sc1
	global_load_dwordx4 v[138:141], v210, s[52:53] sc1
	global_load_dwordx4 v[142:145], v211, s[52:53] sc1
	global_load_dwordx4 v[146:149], v208, s[42:43] sc1
	global_load_dwordx4 v[150:153], v209, s[42:43] sc1
	s_add_u32 s52, s52, 0x100000
	s_addc_u32 s53, s53, 0
	s_add_u32 s42, s42, 0x10000
	s_addc_u32 s43, s43, 0
	global_load_dwordx4 v[154:157], v208, s[52:53] sc1
	global_load_dwordx4 v[158:161], v209, s[52:53] sc1
	global_load_dwordx4 v[162:165], v210, s[52:53] sc1
	global_load_dwordx4 v[166:169], v211, s[52:53] sc1
	global_load_dwordx4 v[170:173], v208, s[42:43] sc1
	global_load_dwordx4 v[174:177], v209, s[42:43] sc1
	s_add_u32 s52, s52, 0x100000
	s_addc_u32 s53, s53, 0
	s_add_u32 s42, s42, 0x10000
	s_addc_u32 s43, s43, 0
	s_barrier
	s_waitcnt vmcnt(11)
	ds_write_b128 v196, v[130:133]
	s_waitcnt vmcnt(10)
	ds_write_b128 v196, v[134:137] offset:5120
	s_waitcnt vmcnt(9)
	ds_write_b128 v196, v[138:141] offset:10240
	s_waitcnt vmcnt(8)
	ds_write_b128 v196, v[142:145] offset:15360
	s_waitcnt vmcnt(7)
	ds_write_b128 v196, v[146:149] offset:20480
	s_waitcnt vmcnt(6)
	ds_write_b128 v196, v[150:153] offset:25600
	s_waitcnt lgkmcnt(0)
	s_barrier
	s_mov_b32 s15, 0
; template <class LA, class LB, class EP>
; __device__ __forceinline__ void gemm_tile_big(int K, LA loadA, LB loadB, EP epi, char* smem) {
;     ...
;   for (int kt = 0; kt < nk; ++kt) {
;     __syncthreads();
; #pragma unroll
;     for (int i = 0; i < 8; ++i) *(uint4*)&sA[(lr + 32 * i) * 72 + lc] = ra[i];
; #pragma unroll
;     for (int i = 0; i < 4; ++i) *(uint4*)&sB[(lr + 32 * i) * 72 + lc] = rb[i];
;     __syncthreads();
;     if (kt + 1 < nk) {
;       const int kk = (kt + 1) * 64 + lc;
; #pragma unroll
;       for (int i = 0; i < 8; ++i) ra[i] = loadA(lr + 32 * i, kk);
; #pragma unroll
;       for (int i = 0; i < 4; ++i) rb[i] = loadB(lr + 32 * i, kk);
;     }
; #pragma unroll
;     for (int s = 0; s < 4; ++s) {
;       h8 af[4], bf[2];
; #pragma unroll
;       for (int mi = 0; mi < 4; ++mi)
;         af[mi] = *(const h8*)&sA[(wm * 128 + mi * 32 + (lane & 31)) * 72 + s * 16 + (lane >> 5) * 8];
; #pragma unroll
;       for (int ni = 0; ni < 2; ++ni)
;         bf[ni] = *(const h8*)&sB[(wn * 64 + ni * 32 + (lane & 31)) * 72 + s * 16 + (lane >> 5) * 8];
; #pragma unroll
;       for (int mi = 0; mi < 4; ++mi)
; #pragma unroll
;         for (int ni = 0; ni < 2; ++ni)
;           acc[mi][ni] = __builtin_amdgcn_mfma_f32_32x32x16_f16(af[mi], bf[ni], acc[mi][ni], 0, 0, 0);
;     }
.Lgp2_loop:
	ds_read_b128 v[238:241], v179 offset:20480
	ds_read_b128 v[242:245], v179 offset:23040
	ds_read_b128 v[200:203], v178
	ds_read_b128 v[204:207], v178 offset:2560
	ds_read_b128 v[214:217], v178 offset:5120
	ds_read_b128 v[218:221], v178 offset:7680
	global_load_dwordx4 v[130:133], v208, s[52:53] sc1
	global_load_dwordx4 v[134:137], v209, s[52:53] sc1
	global_load_dwordx4 v[138:141], v210, s[52:53] sc1
	global_load_dwordx4 v[142:145], v211, s[52:53] sc1
	global_load_dwordx4 v[146:149], v208, s[42:43] sc1
	global_load_dwordx4 v[150:153], v209, s[42:43] sc1
	s_add_u32 s52, s52, 0x100000
	s_addc_u32 s53, s53, 0
	s_add_u32 s42, s42, 0x10000
	s_addc_u32 s43, s43, 0
	ds_read_b128 v[226:229], v179 offset:20512
	ds_read_b128 v[230:233], v179 offset:23072
	s_waitcnt lgkmcnt(5)
	v_mfma_f32_32x32x16_f16 v[114:129], v[200:203], v[238:241], v[114:129]
	v_mfma_f32_32x32x16_f16 v[98:113], v[200:203], v[242:245], v[98:113]
	ds_read_b128 v[200:203], v178 offset:32
	s_waitcnt lgkmcnt(5)
	v_mfma_f32_32x32x16_f16 v[82:97], v[204:207], v[238:241], v[82:97]
	v_mfma_f32_32x32x16_f16 v[66:81], v[204:207], v[242:245], v[66:81]
	ds_read_b128 v[204:207], v178 offset:2592
	s_waitcnt vmcnt(11)
	ds_write_b128 v196, v[154:157] offset:30720
	s_waitcnt lgkmcnt(6)
	v_mfma_f32_32x32x16_f16 v[50:65], v[214:217], v[238:241], v[50:65]
	v_mfma_f32_32x32x16_f16 v[34:49], v[214:217], v[242:245], v[34:49]
	ds_read_b128 v[214:217], v178 offset:5152
	s_waitcnt vmcnt(10)
	ds_write_b128 v196, v[158:161] offset:35840
	s_waitcnt lgkmcnt(7)
	v_mfma_f32_32x32x16_f16 v[18:33], v[218:221], v[238:241], v[18:33]
	v_mfma_f32_32x32x16_f16 v[2:17], v[218:221], v[242:245], v[2:17]
	ds_read_b128 v[218:221], v178 offset:7712
	s_waitcnt vmcnt(9)
	ds_write_b128 v196, v[162:165] offset:40960
	s_waitcnt lgkmcnt(6)
	v_mfma_f32_32x32x16_f16 v[114:129], v[200:203], v[226:229], v[114:129]
	v_mfma_f32_32x32x16_f16 v[98:113], v[200:203], v[230:233], v[98:113]
	s_waitcnt vmcnt(8)
	ds_write_b128 v196, v[166:169] offset:46080
	s_waitcnt lgkmcnt(6)
	v_mfma_f32_32x32x16_f16 v[82:97], v[204:207], v[226:229], v[82:97]
	v_mfma_f32_32x32x16_f16 v[66:81], v[204:207], v[230:233], v[66:81]
	s_waitcnt vmcnt(7)
	ds_write_b128 v196, v[170:173] offset:51200
	s_waitcnt lgkmcnt(5)
	v_mfma_f32_32x32x16_f16 v[50:65], v[214:217], v[226:229], v[50:65]
	v_mfma_f32_32x32x16_f16 v[34:49], v[214:217], v[230:233], v[34:49]
	s_waitcnt vmcnt(6)
	ds_write_b128 v196, v[174:177] offset:56320
	s_waitcnt lgkmcnt(4)
	v_mfma_f32_32x32x16_f16 v[18:33], v[218:221], v[226:229], v[18:33]
	v_mfma_f32_32x32x16_f16 v[2:17], v[218:221], v[230:233], v[2:17]
	s_waitcnt lgkmcnt(0)
	s_barrier
	ds_read_b128 v[238:241], v179 offset:51200
	ds_read_b128 v[242:245], v179 offset:53760
	ds_read_b128 v[200:203], v178 offset:30720
	ds_read_b128 v[204:207], v178 offset:33280
	ds_read_b128 v[214:217], v178 offset:35840
	ds_read_b128 v[218:221], v178 offset:38400
	global_load_dwordx4 v[154:157], v208, s[52:53] sc1
	global_load_dwordx4 v[158:161], v209, s[52:53] sc1
	global_load_dwordx4 v[162:165], v210, s[52:53] sc1
	global_load_dwordx4 v[166:169], v211, s[52:53] sc1
	global_load_dwordx4 v[170:173], v208, s[42:43] sc1
	global_load_dwordx4 v[174:177], v209, s[42:43] sc1
	s_add_u32 s52, s52, 0x100000
	s_addc_u32 s53, s53, 0
	s_add_u32 s42, s42, 0x10000
	s_addc_u32 s43, s43, 0
	ds_read_b128 v[226:229], v179 offset:51232
	ds_read_b128 v[230:233], v179 offset:53792
	s_waitcnt lgkmcnt(5)
	v_mfma_f32_32x32x16_f16 v[114:129], v[200:203], v[238:241], v[114:129]
	v_mfma_f32_32x32x16_f16 v[98:113], v[200:203], v[242:245], v[98:113]
	ds_read_b128 v[200:203], v178 offset:30752
	s_waitcnt lgkmcnt(5)
	v_mfma_f32_32x32x16_f16 v[82:97], v[204:207], v[238:241], v[82:97]
	v_mfma_f32_32x32x16_f16 v[66:81], v[204:207], v[242:245], v[66:81]
	ds_read_b128 v[204:207], v178 offset:33312
	s_waitcnt vmcnt(11)
	ds_write_b128 v196, v[130:133]
	s_waitcnt lgkmcnt(6)
	v_mfma_f32_32x32x16_f16 v[50:65], v[214:217], v[238:241], v[50:65]
	v_mfma_f32_32x32x16_f16 v[34:49], v[214:217], v[242:245], v[34:49]
	ds_read_b128 v[214:217], v178 offset:35872
	s_waitcnt vmcnt(10)
	ds_write_b128 v196, v[134:137] offset:5120
	s_waitcnt lgkmcnt(7)
	v_mfma_f32_32x32x16_f16 v[18:33], v[218:221], v[238:241], v[18:33]
	v_mfma_f32_32x32x16_f16 v[2:17], v[218:221], v[242:245], v[2:17]
	ds_read_b128 v[218:221], v178 offset:38432
	s_waitcnt vmcnt(9)
	ds_write_b128 v196, v[138:141] offset:10240
	s_waitcnt lgkmcnt(6)
	v_mfma_f32_32x32x16_f16 v[114:129], v[200:203], v[226:229], v[114:129]
	v_mfma_f32_32x32x16_f16 v[98:113], v[200:203], v[230:233], v[98:113]
	s_waitcnt vmcnt(8)
	ds_write_b128 v196, v[142:145] offset:15360
	s_waitcnt lgkmcnt(6)
	v_mfma_f32_32x32x16_f16 v[82:97], v[204:207], v[226:229], v[82:97]
	v_mfma_f32_32x32x16_f16 v[66:81], v[204:207], v[230:233], v[66:81]
	s_waitcnt vmcnt(7)
	ds_write_b128 v196, v[146:149] offset:20480
	s_waitcnt lgkmcnt(5)
	v_mfma_f32_32x32x16_f16 v[50:65], v[214:217], v[226:229], v[50:65]
	v_mfma_f32_32x32x16_f16 v[34:49], v[214:217], v[230:233], v[34:49]
	s_waitcnt vmcnt(6)
	ds_write_b128 v196, v[150:153] offset:25600
	s_waitcnt lgkmcnt(4)
	v_mfma_f32_32x32x16_f16 v[18:33], v[218:221], v[226:229], v[18:33]
	v_mfma_f32_32x32x16_f16 v[2:17], v[218:221], v[230:233], v[2:17]
	s_waitcnt lgkmcnt(0)
	s_barrier
	s_add_i32 s15, s15, 1
	s_cmp_lt_u32 s15, 15
	s_cbranch_scc1 .Lgp2_loop
;   __device__ __forceinline__ float* xr() const { return (float*)(ws() + OFF_xr); }
;   __device__ __forceinline__ half_t* u() const { return (half_t*)(ws() + OFF_u); }
; template <class LA, class LB, class EP>
; __device__ __forceinline__ void gemm_tile_big(int K, LA loadA, LB loadB, EP epi, char* smem) {
;     ...
; #pragma unroll
;     for (int s = 0; s < 4; ++s) {
;       h8 af[4], bf[2];
; #pragma unroll
;       for (int mi = 0; mi < 4; ++mi)
;         af[mi] = *(const h8*)&sA[(wm * 128 + mi * 32 + (lane & 31)) * 72 + s * 16 + (lane >> 5) * 8];
; #pragma unroll
;       for (int ni = 0; ni < 2; ++ni)
;         bf[ni] = *(const h8*)&sB[(wn * 64 + ni * 32 + (lane & 31)) * 72 + s * 16 + (lane >> 5) * 8];
; #pragma unroll
;       for (int mi = 0; mi < 4; ++mi)
; #pragma unroll
;         for (int ni = 0; ni < 2; ++ni)
;           acc[mi][ni] = __builtin_amdgcn_mfma_f32_32x32x16_f16(af[mi], bf[ni], acc[mi][ni], 0, 0, 0);
;     }
; __device__ __forceinline__ void phase_outproj(const KP& p, char* smem, int* q, int xcc) {
;     ...
;         [&](int mi, int ni, int r, int row, int col, float v) {
;           const size_t xi = (size_t)(m0 + row) * DM + n0 + col;
;           ((float*)p.u())[xi] = ALPHA_F * p.xr()[xi] + v;
	ds_read_b128 v[238:241], v179 offset:20480
	ds_read_b128 v[242:245], v179 offset:23040
	ds_read_b128 v[200:203], v178
	ds_read_b128 v[204:207], v178 offset:2560
	ds_read_b128 v[214:217], v178 offset:5120
	ds_read_b128 v[218:221], v178 offset:7680
	ds_read_b128 v[226:229], v179 offset:20512
	ds_read_b128 v[230:233], v179 offset:23072
	s_waitcnt lgkmcnt(5)
	v_mfma_f32_32x32x16_f16 v[114:129], v[200:203], v[238:241], v[114:129]
	v_mfma_f32_32x32x16_f16 v[98:113], v[200:203], v[242:245], v[98:113]
	ds_read_b128 v[200:203], v178 offset:32
	s_waitcnt lgkmcnt(5)
	v_mfma_f32_32x32x16_f16 v[82:97], v[204:207], v[238:241], v[82:97]
	v_mfma_f32_32x32x16_f16 v[66:81], v[204:207], v[242:245], v[66:81]
	ds_read_b128 v[204:207], v178 offset:2592
	s_waitcnt vmcnt(5)
	ds_write_b128 v196, v[154:157] offset:30720
	s_waitcnt lgkmcnt(6)
	v_mfma_f32_32x32x16_f16 v[50:65], v[214:217], v[238:241], v[50:65]
	v_mfma_f32_32x32x16_f16 v[34:49], v[214:217], v[242:245], v[34:49]
	ds_read_b128 v[214:217], v178 offset:5152
	s_waitcnt vmcnt(4)
	ds_write_b128 v196, v[158:161] offset:35840
	s_waitcnt lgkmcnt(7)
	v_mfma_f32_32x32x16_f16 v[18:33], v[218:221], v[238:241], v[18:33]
	v_mfma_f32_32x32x16_f16 v[2:17], v[218:221], v[242:245], v[2:17]
	ds_read_b128 v[218:221], v178 offset:7712
	s_waitcnt vmcnt(3)
	ds_write_b128 v196, v[162:165] offset:40960
	s_waitcnt lgkmcnt(6)
	v_mfma_f32_32x32x16_f16 v[114:129], v[200:203], v[226:229], v[114:129]
	v_mfma_f32_32x32x16_f16 v[98:113], v[200:203], v[230:233], v[98:113]
	s_waitcnt vmcnt(2)
	ds_write_b128 v196, v[166:169] offset:46080
	s_waitcnt lgkmcnt(6)
	v_mfma_f32_32x32x16_f16 v[82:97], v[204:207], v[226:229], v[82:97]
	v_mfma_f32_32x32x16_f16 v[66:81], v[204:207], v[230:233], v[66:81]
	s_waitcnt vmcnt(1)
	ds_write_b128 v196, v[170:173] offset:51200
	s_waitcnt lgkmcnt(5)
	v_mfma_f32_32x32x16_f16 v[50:65], v[214:217], v[226:229], v[50:65]
	v_mfma_f32_32x32x16_f16 v[34:49], v[214:217], v[230:233], v[34:49]
	s_waitcnt vmcnt(0)
	ds_write_b128 v196, v[174:177] offset:56320
	s_waitcnt lgkmcnt(4)
	v_mfma_f32_32x32x16_f16 v[18:33], v[218:221], v[226:229], v[18:33]
	v_mfma_f32_32x32x16_f16 v[2:17], v[218:221], v[230:233], v[2:17]
	s_waitcnt lgkmcnt(0)
	s_barrier
	ds_read_b128 v[238:241], v179 offset:51200
	ds_read_b128 v[242:245], v179 offset:53760
	ds_read_b128 v[200:203], v178 offset:30720
	ds_read_b128 v[204:207], v178 offset:33280
	ds_read_b128 v[214:217], v178 offset:35840
	ds_read_b128 v[218:221], v178 offset:38400
	ds_read_b128 v[226:229], v179 offset:51232
	ds_read_b128 v[230:233], v179 offset:53792
	s_waitcnt lgkmcnt(5)
	v_mfma_f32_32x32x16_f16 v[114:129], v[200:203], v[238:241], v[114:129]
	v_mfma_f32_32x32x16_f16 v[98:113], v[200:203], v[242:245], v[98:113]
	ds_read_b128 v[200:203], v178 offset:30752
	s_waitcnt lgkmcnt(5)
	v_mfma_f32_32x32x16_f16 v[82:97], v[204:207], v[238:241], v[82:97]
	v_mfma_f32_32x32x16_f16 v[66:81], v[204:207], v[242:245], v[66:81]
	ds_read_b128 v[204:207], v178 offset:33312
	s_waitcnt lgkmcnt(5)
	v_mfma_f32_32x32x16_f16 v[50:65], v[214:217], v[238:241], v[50:65]
	v_mfma_f32_32x32x16_f16 v[34:49], v[214:217], v[242:245], v[34:49]
	ds_read_b128 v[214:217], v178 offset:35872
	s_waitcnt lgkmcnt(5)
	v_mfma_f32_32x32x16_f16 v[18:33], v[218:221], v[238:241], v[18:33]
	v_mfma_f32_32x32x16_f16 v[2:17], v[218:221], v[242:245], v[2:17]
	ds_read_b128 v[218:221], v178 offset:38432
	s_waitcnt lgkmcnt(3)
	v_mfma_f32_32x32x16_f16 v[114:129], v[200:203], v[226:229], v[114:129]
	v_mfma_f32_32x32x16_f16 v[98:113], v[200:203], v[230:233], v[98:113]
	s_waitcnt lgkmcnt(2)
	v_mfma_f32_32x32x16_f16 v[82:97], v[204:207], v[226:229], v[82:97]
	v_mfma_f32_32x32x16_f16 v[66:81], v[204:207], v[230:233], v[66:81]
	s_waitcnt lgkmcnt(1)
	v_mfma_f32_32x32x16_f16 v[50:65], v[214:217], v[226:229], v[50:65]
	v_mfma_f32_32x32x16_f16 v[34:49], v[214:217], v[230:233], v[34:49]
	s_waitcnt lgkmcnt(0)
	v_mfma_f32_32x32x16_f16 v[18:33], v[218:221], v[226:229], v[18:33]
	v_mfma_f32_32x32x16_f16 v[2:17], v[218:221], v[230:233], v[2:17]
	s_waitcnt lgkmcnt(0)
	v_mov_b32_e32 v226, 1
	v_mov_b32_e32 v227, 0x11fe0
	v_mov_b32_e32 v228, 0x11fe4
	v_mov_b32_e32 v229, 0x100
	v_mov_b32_e32 v230, 2
	v_mov_b32_e32 v231, 0x3727c5ac
	v_mov_b32_e32 v232, 0x11fa0
	v_mov_b32_e32 v233, 0x80000
	v_mov_b32_e32 v238, 0x4000
	v_mov_b32_e32 v239, 0x4400
	v_mov_b32_e32 v240, 0x4800
	v_mov_b32_e32 v241, 0x4c00
	v_mov_b32_e32 v242, 0xf149f2ca
	v_mov_b32_e32 v243, 0x200
	v_mov_b32_e32 v244, 0x400
	v_mov_b32_e32 v245, 0x600
	s_nop 15
	s_lshl_b32 s2, s40, 10
	s_add_u32 s2, s2, s38
	s_lshl_b32 s2, s2, 2
	s_add_u32 s52, s0, s2
	s_addc_u32 s53, s1, 0
	s_add_u32 s42, s10, s2
	s_addc_u32 s43, s11, 0
	v_lshrrev_b32_e32 v180, 7, v224
	v_lshlrev_b32_e32 v180, 19, v180
	v_bfe_u32 v181, v224, 5, 1
	v_lshl_or_b32 v180, v181, 14, v180
	v_bfe_u32 v181, v224, 6, 1
	v_lshl_or_b32 v180, v181, 8, v180
	v_and_b32_e32 v181, 31, v224
	v_lshl_or_b32 v180, v181, 2, v180
	s_add_u32 s2, s52, 0x0
	s_addc_u32 s3, s53, 0
	global_load_dword v130, v180, s[2:3]
	global_load_dword v131, v180, s[2:3] offset:128
	s_add_u32 s2, s52, 0x1000
	s_addc_u32 s3, s53, 0
	global_load_dword v132, v180, s[2:3]
	global_load_dword v133, v180, s[2:3] offset:128
	s_add_u32 s2, s52, 0x2000
	s_addc_u32 s3, s53, 0
	global_load_dword v134, v180, s[2:3]
	global_load_dword v135, v180, s[2:3] offset:128
	s_add_u32 s2, s52, 0x3000
	s_addc_u32 s3, s53, 0
	global_load_dword v136, v180, s[2:3]
	global_load_dword v137, v180, s[2:3] offset:128
	s_add_u32 s2, s52, 0x8000
	s_addc_u32 s3, s53, 0
	global_load_dword v138, v180, s[2:3]
	global_load_dword v139, v180, s[2:3] offset:128
	s_add_u32 s2, s52, 0x9000
	s_addc_u32 s3, s53, 0
;   __device__ __forceinline__ float* xr() const { return (float*)(ws() + OFF_xr); }
;   __device__ __forceinline__ half_t* u() const { return (half_t*)(ws() + OFF_u); }
; template <class LA, class LB, class EP>
; __device__ __forceinline__ void gemm_tile_big(int K, LA loadA, LB loadB, EP epi, char* smem) {
;     ...
; #pragma unroll
;   for (int mi = 0; mi < 4; ++mi)
; #pragma unroll
;     for (int ni = 0; ni < 2; ++ni)
; #pragma unroll
;       for (int r = 0; r < 16; ++r) {
;         const int row = wm * 128 + mi * 32 + (r & 3) + 8 * (r >> 2) + 4 * (lane >> 5);
;         const int col = wn * 64 + ni * 32 + (lane & 31);
;         epi(mi, ni, r, row, col, acc[mi][ni][r]);
; __device__ __forceinline__ void phase_outproj(const KP& p, char* smem, int* q, int xcc) {
;     ...
;         [&](int mi, int ni, int r, int row, int col, float v) {
;           const size_t xi = (size_t)(m0 + row) * DM + n0 + col;
;           ((float*)p.u())[xi] = ALPHA_F * p.xr()[xi] + v;
	global_load_dword v140, v180, s[2:3]
	global_load_dword v141, v180, s[2:3] offset:128
	s_add_u32 s2, s52, 0xa000
	s_addc_u32 s3, s53, 0
	global_load_dword v142, v180, s[2:3]
	global_load_dword v143, v180, s[2:3] offset:128
	s_add_u32 s2, s52, 0xb000
	s_addc_u32 s3, s53, 0
	global_load_dword v144, v180, s[2:3]
	global_load_dword v145, v180, s[2:3] offset:128
	s_add_u32 s2, s52, 0x10000
	s_addc_u32 s3, s53, 0
	global_load_dword v146, v180, s[2:3]
	global_load_dword v147, v180, s[2:3] offset:128
	s_add_u32 s2, s52, 0x11000
	s_addc_u32 s3, s53, 0
	global_load_dword v148, v180, s[2:3]
	global_load_dword v149, v180, s[2:3] offset:128
	s_add_u32 s2, s52, 0x12000
	s_addc_u32 s3, s53, 0
	global_load_dword v150, v180, s[2:3]
	global_load_dword v151, v180, s[2:3] offset:128
	s_add_u32 s2, s52, 0x13000
	s_addc_u32 s3, s53, 0
	global_load_dword v152, v180, s[2:3]
	global_load_dword v153, v180, s[2:3] offset:128
	s_add_u32 s2, s52, 0x18000
	s_addc_u32 s3, s53, 0
	global_load_dword v154, v180, s[2:3]
	global_load_dword v155, v180, s[2:3] offset:128
	s_add_u32 s2, s52, 0x19000
	s_addc_u32 s3, s53, 0
	global_load_dword v156, v180, s[2:3]
	global_load_dword v157, v180, s[2:3] offset:128
	s_add_u32 s2, s52, 0x1a000
	s_addc_u32 s3, s53, 0
	global_load_dword v158, v180, s[2:3]
	global_load_dword v159, v180, s[2:3] offset:128
	s_add_u32 s2, s52, 0x1b000
	s_addc_u32 s3, s53, 0
	global_load_dword v160, v180, s[2:3]
	global_load_dword v161, v180, s[2:3] offset:128
	s_add_u32 s2, s52, 0x20000
	s_addc_u32 s3, s53, 0
	global_load_dword v162, v180, s[2:3]
	global_load_dword v163, v180, s[2:3] offset:128
	s_add_u32 s2, s52, 0x21000
	s_addc_u32 s3, s53, 0
	global_load_dword v164, v180, s[2:3]
	global_load_dword v165, v180, s[2:3] offset:128
	s_add_u32 s2, s52, 0x22000
	s_addc_u32 s3, s53, 0
	global_load_dword v166, v180, s[2:3]
	global_load_dword v167, v180, s[2:3] offset:128
	s_add_u32 s2, s52, 0x23000
	s_addc_u32 s3, s53, 0
	global_load_dword v168, v180, s[2:3]
	global_load_dword v169, v180, s[2:3] offset:128
	s_add_u32 s2, s52, 0x28000
	s_addc_u32 s3, s53, 0
	global_load_dword v170, v180, s[2:3]
	global_load_dword v171, v180, s[2:3] offset:128
	s_add_u32 s2, s52, 0x29000
	s_addc_u32 s3, s53, 0
	global_load_dword v172, v180, s[2:3]
	global_load_dword v173, v180, s[2:3] offset:128
	s_add_u32 s2, s52, 0x2a000
	s_addc_u32 s3, s53, 0
	global_load_dword v174, v180, s[2:3]
	global_load_dword v175, v180, s[2:3] offset:128
	s_add_u32 s2, s52, 0x2b000
	s_addc_u32 s3, s53, 0
	global_load_dword v176, v180, s[2:3]
	global_load_dword v177, v180, s[2:3] offset:128
	s_waitcnt vmcnt(32)
	v_fmamk_f32 v114, v130, 0x3fd744fd, v114
	v_fmamk_f32 v98, v131, 0x3fd744fd, v98
	v_fmamk_f32 v115, v132, 0x3fd744fd, v115
	v_fmamk_f32 v99, v133, 0x3fd744fd, v99
	v_fmamk_f32 v116, v134, 0x3fd744fd, v116
	v_fmamk_f32 v100, v135, 0x3fd744fd, v100
	v_fmamk_f32 v117, v136, 0x3fd744fd, v117
	v_fmamk_f32 v101, v137, 0x3fd744fd, v101
	v_fmamk_f32 v118, v138, 0x3fd744fd, v118
	v_fmamk_f32 v102, v139, 0x3fd744fd, v102
	v_fmamk_f32 v119, v140, 0x3fd744fd, v119
	v_fmamk_f32 v103, v141, 0x3fd744fd, v103
	v_fmamk_f32 v120, v142, 0x3fd744fd, v120
	v_fmamk_f32 v104, v143, 0x3fd744fd, v104
	v_fmamk_f32 v121, v144, 0x3fd744fd, v121
	v_fmamk_f32 v105, v145, 0x3fd744fd, v105
	s_add_u32 s2, s52, 0x30000
	s_addc_u32 s3, s53, 0
	global_load_dword v130, v180, s[2:3]
	global_load_dword v131, v180, s[2:3] offset:128
	s_add_u32 s2, s52, 0x31000
	s_addc_u32 s3, s53, 0
	global_load_dword v132, v180, s[2:3]
	global_load_dword v133, v180, s[2:3] offset:128
	s_add_u32 s2, s52, 0x32000
	s_addc_u32 s3, s53, 0
	global_load_dword v134, v180, s[2:3]
	global_load_dword v135, v180, s[2:3] offset:128
	s_add_u32 s2, s52, 0x33000
	s_addc_u32 s3, s53, 0
	global_load_dword v136, v180, s[2:3]
	global_load_dword v137, v180, s[2:3] offset:128
	s_add_u32 s2, s52, 0x38000
	s_addc_u32 s3, s53, 0
	global_load_dword v138, v180, s[2:3]
	global_load_dword v139, v180, s[2:3] offset:128
	s_add_u32 s2, s52, 0x39000
	s_addc_u32 s3, s53, 0
	global_load_dword v140, v180, s[2:3]
	global_load_dword v141, v180, s[2:3] offset:128
	s_add_u32 s2, s52, 0x3a000
	s_addc_u32 s3, s53, 0
	global_load_dword v142, v180, s[2:3]
	global_load_dword v143, v180, s[2:3] offset:128
	s_add_u32 s2, s52, 0x3b000
	s_addc_u32 s3, s53, 0
	global_load_dword v144, v180, s[2:3]
	global_load_dword v145, v180, s[2:3] offset:128
	s_waitcnt vmcnt(32)
	v_fmamk_f32 v122, v146, 0x3fd744fd, v122
	v_fmamk_f32 v106, v147, 0x3fd744fd, v106
	v_fmamk_f32 v123, v148, 0x3fd744fd, v123
	v_fmamk_f32 v107, v149, 0x3fd744fd, v107
	v_fmamk_f32 v124, v150, 0x3fd744fd, v124
	v_fmamk_f32 v108, v151, 0x3fd744fd, v108
	v_fmamk_f32 v125, v152, 0x3fd744fd, v125
	v_fmamk_f32 v109, v153, 0x3fd744fd, v109
	v_fmamk_f32 v126, v154, 0x3fd744fd, v126
	v_fmamk_f32 v110, v155, 0x3fd744fd, v110
	v_fmamk_f32 v127, v156, 0x3fd744fd, v127
	v_fmamk_f32 v111, v157, 0x3fd744fd, v111
	v_fmamk_f32 v128, v158, 0x3fd744fd, v128
	v_fmamk_f32 v112, v159, 0x3fd744fd, v112
	v_fmamk_f32 v129, v160, 0x3fd744fd, v129
	v_fmamk_f32 v113, v161, 0x3fd744fd, v113
	s_add_u32 s2, s52, 0x40000
	s_addc_u32 s3, s53, 0
	global_load_dword v146, v180, s[2:3]
	global_load_dword v147, v180, s[2:3] offset:128
	s_add_u32 s2, s52, 0x41000
	s_addc_u32 s3, s53, 0
	global_load_dword v148, v180, s[2:3]
	global_load_dword v149, v180, s[2:3] offset:128
	s_add_u32 s2, s52, 0x42000
	s_addc_u32 s3, s53, 0
	global_load_dword v150, v180, s[2:3]
	global_load_dword v151, v180, s[2:3] offset:128
	s_add_u32 s2, s52, 0x43000
	s_addc_u32 s3, s53, 0
	global_load_dword v152, v180, s[2:3]
	global_load_dword v153, v180, s[2:3] offset:128
	s_add_u32 s2, s52, 0x48000
	s_addc_u32 s3, s53, 0
	global_load_dword v154, v180, s[2:3]
	global_load_dword v155, v180, s[2:3] offset:128
	s_add_u32 s2, s52, 0x49000
	s_addc_u32 s3, s53, 0
	global_load_dword v156, v180, s[2:3]
	global_load_dword v157, v180, s[2:3] offset:128
	s_add_u32 s2, s52, 0x4a000
	s_addc_u32 s3, s53, 0
	global_load_dword v158, v180, s[2:3]
	global_load_dword v159, v180, s[2:3] offset:128
	s_add_u32 s2, s52, 0x4b000
	s_addc_u32 s3, s53, 0
	global_load_dword v160, v180, s[2:3]
	global_load_dword v161, v180, s[2:3] offset:128
	s_waitcnt vmcnt(32)
;   __device__ __forceinline__ float* xr() const { return (float*)(ws() + OFF_xr); }
;   __device__ __forceinline__ half_t* u() const { return (half_t*)(ws() + OFF_u); }
; template <class LA, class LB, class EP>
; __device__ __forceinline__ void gemm_tile_big(int K, LA loadA, LB loadB, EP epi, char* smem) {
;     ...
; #pragma unroll
;   for (int mi = 0; mi < 4; ++mi)
; #pragma unroll
;     for (int ni = 0; ni < 2; ++ni)
; #pragma unroll
;       for (int r = 0; r < 16; ++r) {
;         const int row = wm * 128 + mi * 32 + (r & 3) + 8 * (r >> 2) + 4 * (lane >> 5);
;         const int col = wn * 64 + ni * 32 + (lane & 31);
;         epi(mi, ni, r, row, col, acc[mi][ni][r]);
; __device__ __forceinline__ void phase_outproj(const KP& p, char* smem, int* q, int xcc) {
;     ...
;         [&](int mi, int ni, int r, int row, int col, float v) {
;           const size_t xi = (size_t)(m0 + row) * DM + n0 + col;
;           ((float*)p.u())[xi] = ALPHA_F * p.xr()[xi] + v;
	v_fmamk_f32 v82, v162, 0x3fd744fd, v82
	v_fmamk_f32 v66, v163, 0x3fd744fd, v66
	v_fmamk_f32 v83, v164, 0x3fd744fd, v83
	v_fmamk_f32 v67, v165, 0x3fd744fd, v67
	v_fmamk_f32 v84, v166, 0x3fd744fd, v84
	v_fmamk_f32 v68, v167, 0x3fd744fd, v68
	v_fmamk_f32 v85, v168, 0x3fd744fd, v85
	v_fmamk_f32 v69, v169, 0x3fd744fd, v69
	v_fmamk_f32 v86, v170, 0x3fd744fd, v86
	v_fmamk_f32 v70, v171, 0x3fd744fd, v70
	v_fmamk_f32 v87, v172, 0x3fd744fd, v87
	v_fmamk_f32 v71, v173, 0x3fd744fd, v71
	v_fmamk_f32 v88, v174, 0x3fd744fd, v88
	v_fmamk_f32 v72, v175, 0x3fd744fd, v72
	v_fmamk_f32 v89, v176, 0x3fd744fd, v89
	v_fmamk_f32 v73, v177, 0x3fd744fd, v73
	s_add_u32 s2, s52, 0x50000
	s_addc_u32 s3, s53, 0
	global_load_dword v162, v180, s[2:3]
	global_load_dword v163, v180, s[2:3] offset:128
	s_add_u32 s2, s52, 0x51000
	s_addc_u32 s3, s53, 0
	global_load_dword v164, v180, s[2:3]
	global_load_dword v165, v180, s[2:3] offset:128
	s_add_u32 s2, s52, 0x52000
	s_addc_u32 s3, s53, 0
	global_load_dword v166, v180, s[2:3]
	global_load_dword v167, v180, s[2:3] offset:128
	s_add_u32 s2, s52, 0x53000
	s_addc_u32 s3, s53, 0
	global_load_dword v168, v180, s[2:3]
	global_load_dword v169, v180, s[2:3] offset:128
	s_add_u32 s2, s52, 0x58000
	s_addc_u32 s3, s53, 0
	global_load_dword v170, v180, s[2:3]
	global_load_dword v171, v180, s[2:3] offset:128
	s_add_u32 s2, s52, 0x59000
	s_addc_u32 s3, s53, 0
	global_load_dword v172, v180, s[2:3]
	global_load_dword v173, v180, s[2:3] offset:128
	s_add_u32 s2, s52, 0x5a000
	s_addc_u32 s3, s53, 0
	global_load_dword v174, v180, s[2:3]
	global_load_dword v175, v180, s[2:3] offset:128
	s_add_u32 s2, s52, 0x5b000
	s_addc_u32 s3, s53, 0
	global_load_dword v176, v180, s[2:3]
	global_load_dword v177, v180, s[2:3] offset:128
	s_waitcnt vmcnt(32)
	v_fmamk_f32 v90, v130, 0x3fd744fd, v90
	v_fmamk_f32 v74, v131, 0x3fd744fd, v74
	v_fmamk_f32 v91, v132, 0x3fd744fd, v91
	v_fmamk_f32 v75, v133, 0x3fd744fd, v75
	v_fmamk_f32 v92, v134, 0x3fd744fd, v92
	v_fmamk_f32 v76, v135, 0x3fd744fd, v76
	v_fmamk_f32 v93, v136, 0x3fd744fd, v93
	v_fmamk_f32 v77, v137, 0x3fd744fd, v77
	v_fmamk_f32 v94, v138, 0x3fd744fd, v94
	v_fmamk_f32 v78, v139, 0x3fd744fd, v78
	v_fmamk_f32 v95, v140, 0x3fd744fd, v95
	v_fmamk_f32 v79, v141, 0x3fd744fd, v79
	v_fmamk_f32 v96, v142, 0x3fd744fd, v96
	v_fmamk_f32 v80, v143, 0x3fd744fd, v80
	v_fmamk_f32 v97, v144, 0x3fd744fd, v97
	v_fmamk_f32 v81, v145, 0x3fd744fd, v81
	s_add_u32 s2, s52, 0x60000
	s_addc_u32 s3, s53, 0
	global_load_dword v130, v180, s[2:3]
	global_load_dword v131, v180, s[2:3] offset:128
	s_add_u32 s2, s52, 0x61000
	s_addc_u32 s3, s53, 0
	global_load_dword v132, v180, s[2:3]
	global_load_dword v133, v180, s[2:3] offset:128
	s_add_u32 s2, s52, 0x62000
	s_addc_u32 s3, s53, 0
	global_load_dword v134, v180, s[2:3]
	global_load_dword v135, v180, s[2:3] offset:128
	s_add_u32 s2, s52, 0x63000
	s_addc_u32 s3, s53, 0
	global_load_dword v136, v180, s[2:3]
	global_load_dword v137, v180, s[2:3] offset:128
	s_add_u32 s2, s52, 0x68000
	s_addc_u32 s3, s53, 0
	global_load_dword v138, v180, s[2:3]
	global_load_dword v139, v180, s[2:3] offset:128
	s_add_u32 s2, s52, 0x69000
	s_addc_u32 s3, s53, 0
	global_load_dword v140, v180, s[2:3]
	global_load_dword v141, v180, s[2:3] offset:128
	s_add_u32 s2, s52, 0x6a000
	s_addc_u32 s3, s53, 0
	global_load_dword v142, v180, s[2:3]
	global_load_dword v143, v180, s[2:3] offset:128
	s_add_u32 s2, s52, 0x6b000
	s_addc_u32 s3, s53, 0
	global_load_dword v144, v180, s[2:3]
	global_load_dword v145, v180, s[2:3] offset:128
	s_waitcnt vmcnt(32)
	v_fmamk_f32 v50, v146, 0x3fd744fd, v50
	v_fmamk_f32 v34, v147, 0x3fd744fd, v34
	v_fmamk_f32 v51, v148, 0x3fd744fd, v51
	v_fmamk_f32 v35, v149, 0x3fd744fd, v35
	v_fmamk_f32 v52, v150, 0x3fd744fd, v52
	v_fmamk_f32 v36, v151, 0x3fd744fd, v36
	v_fmamk_f32 v53, v152, 0x3fd744fd, v53
	v_fmamk_f32 v37, v153, 0x3fd744fd, v37
	v_fmamk_f32 v54, v154, 0x3fd744fd, v54
	v_fmamk_f32 v38, v155, 0x3fd744fd, v38
	v_fmamk_f32 v55, v156, 0x3fd744fd, v55
	v_fmamk_f32 v39, v157, 0x3fd744fd, v39
	v_fmamk_f32 v56, v158, 0x3fd744fd, v56
	v_fmamk_f32 v40, v159, 0x3fd744fd, v40
	v_fmamk_f32 v57, v160, 0x3fd744fd, v57
	v_fmamk_f32 v41, v161, 0x3fd744fd, v41
	s_add_u32 s2, s52, 0x70000
	s_addc_u32 s3, s53, 0
	global_load_dword v146, v180, s[2:3]
	global_load_dword v147, v180, s[2:3] offset:128
	s_add_u32 s2, s52, 0x71000
	s_addc_u32 s3, s53, 0
	global_load_dword v148, v180, s[2:3]
	global_load_dword v149, v180, s[2:3] offset:128
	s_add_u32 s2, s52, 0x72000
	s_addc_u32 s3, s53, 0
	global_load_dword v150, v180, s[2:3]
	global_load_dword v151, v180, s[2:3] offset:128
	s_add_u32 s2, s52, 0x73000
	s_addc_u32 s3, s53, 0
	global_load_dword v152, v180, s[2:3]
	global_load_dword v153, v180, s[2:3] offset:128
	s_add_u32 s2, s52, 0x78000
	s_addc_u32 s3, s53, 0
	global_load_dword v154, v180, s[2:3]
	global_load_dword v155, v180, s[2:3] offset:128
	s_add_u32 s2, s52, 0x79000
	s_addc_u32 s3, s53, 0
	global_load_dword v156, v180, s[2:3]
	global_load_dword v157, v180, s[2:3] offset:128
	s_add_u32 s2, s52, 0x7a000
	s_addc_u32 s3, s53, 0
	global_load_dword v158, v180, s[2:3]
	global_load_dword v159, v180, s[2:3] offset:128
	s_add_u32 s2, s52, 0x7b000
	s_addc_u32 s3, s53, 0
	global_load_dword v160, v180, s[2:3]
	global_load_dword v161, v180, s[2:3] offset:128
	s_waitcnt vmcnt(32)
	v_fmamk_f32 v58, v162, 0x3fd744fd, v58
	v_fmamk_f32 v42, v163, 0x3fd744fd, v42
	v_fmamk_f32 v59, v164, 0x3fd744fd, v59
	v_fmamk_f32 v43, v165, 0x3fd744fd, v43
	v_fmamk_f32 v60, v166, 0x3fd744fd, v60
	v_fmamk_f32 v44, v167, 0x3fd744fd, v44
	v_fmamk_f32 v61, v168, 0x3fd744fd, v61
	v_fmamk_f32 v45, v169, 0x3fd744fd, v45
	v_fmamk_f32 v62, v170, 0x3fd744fd, v62
	v_fmamk_f32 v46, v171, 0x3fd744fd, v46
	v_fmamk_f32 v63, v172, 0x3fd744fd, v63
	v_fmamk_f32 v47, v173, 0x3fd744fd, v47
	v_fmamk_f32 v64, v174, 0x3fd744fd, v64
	v_fmamk_f32 v48, v175, 0x3fd744fd, v48
	v_fmamk_f32 v65, v176, 0x3fd744fd, v65
	v_fmamk_f32 v49, v177, 0x3fd744fd, v49
	s_waitcnt vmcnt(16)
;   __device__ __forceinline__ float* xr() const { return (float*)(ws() + OFF_xr); }
;   __device__ __forceinline__ half_t* u() const { return (half_t*)(ws() + OFF_u); }
; template <class LA, class LB, class EP>
; __device__ __forceinline__ void gemm_tile_big(int K, LA loadA, LB loadB, EP epi, char* smem) {
;     ...
; #pragma unroll
;   for (int mi = 0; mi < 4; ++mi)
; #pragma unroll
;     for (int ni = 0; ni < 2; ++ni)
; #pragma unroll
;       for (int r = 0; r < 16; ++r) {
;         const int row = wm * 128 + mi * 32 + (r & 3) + 8 * (r >> 2) + 4 * (lane >> 5);
;         const int col = wn * 64 + ni * 32 + (lane & 31);
;         epi(mi, ni, r, row, col, acc[mi][ni][r]);
; __device__ __forceinline__ void phase_outproj(const KP& p, char* smem, int* q, int xcc) {
;     ...
;         [&](int mi, int ni, int r, int row, int col, float v) {
;           const size_t xi = (size_t)(m0 + row) * DM + n0 + col;
;           ((float*)p.u())[xi] = ALPHA_F * p.xr()[xi] + v;
	v_fmamk_f32 v18, v130, 0x3fd744fd, v18
	v_fmamk_f32 v2, v131, 0x3fd744fd, v2
	v_fmamk_f32 v19, v132, 0x3fd744fd, v19
	v_fmamk_f32 v3, v133, 0x3fd744fd, v3
	v_fmamk_f32 v20, v134, 0x3fd744fd, v20
	v_fmamk_f32 v4, v135, 0x3fd744fd, v4
	v_fmamk_f32 v21, v136, 0x3fd744fd, v21
	v_fmamk_f32 v5, v137, 0x3fd744fd, v5
	v_fmamk_f32 v22, v138, 0x3fd744fd, v22
	v_fmamk_f32 v6, v139, 0x3fd744fd, v6
	v_fmamk_f32 v23, v140, 0x3fd744fd, v23
	v_fmamk_f32 v7, v141, 0x3fd744fd, v7
	v_fmamk_f32 v24, v142, 0x3fd744fd, v24
	v_fmamk_f32 v8, v143, 0x3fd744fd, v8
	v_fmamk_f32 v25, v144, 0x3fd744fd, v25
	v_fmamk_f32 v9, v145, 0x3fd744fd, v9
	s_waitcnt vmcnt(0)
	v_fmamk_f32 v26, v146, 0x3fd744fd, v26
	v_fmamk_f32 v10, v147, 0x3fd744fd, v10
	v_fmamk_f32 v27, v148, 0x3fd744fd, v27
	v_fmamk_f32 v11, v149, 0x3fd744fd, v11
	v_fmamk_f32 v28, v150, 0x3fd744fd, v28
	v_fmamk_f32 v12, v151, 0x3fd744fd, v12
	v_fmamk_f32 v29, v152, 0x3fd744fd, v29
	v_fmamk_f32 v13, v153, 0x3fd744fd, v13
	v_fmamk_f32 v30, v154, 0x3fd744fd, v30
	v_fmamk_f32 v14, v155, 0x3fd744fd, v14
	v_fmamk_f32 v31, v156, 0x3fd744fd, v31
	v_fmamk_f32 v15, v157, 0x3fd744fd, v15
	v_fmamk_f32 v32, v158, 0x3fd744fd, v32
	v_fmamk_f32 v16, v159, 0x3fd744fd, v16
	v_fmamk_f32 v33, v160, 0x3fd744fd, v33
	v_fmamk_f32 v17, v161, 0x3fd744fd, v17
	s_add_u32 s2, s42, 0x0
	s_addc_u32 s3, s43, 0
	global_store_dword v180, v114, s[2:3]
	global_store_dword v180, v98, s[2:3] offset:128
	s_add_u32 s2, s42, 0x1000
	s_addc_u32 s3, s43, 0
	global_store_dword v180, v115, s[2:3]
	global_store_dword v180, v99, s[2:3] offset:128
	s_add_u32 s2, s42, 0x2000
	s_addc_u32 s3, s43, 0
	global_store_dword v180, v116, s[2:3]
	global_store_dword v180, v100, s[2:3] offset:128
	s_add_u32 s2, s42, 0x3000
	s_addc_u32 s3, s43, 0
	global_store_dword v180, v117, s[2:3]
	global_store_dword v180, v101, s[2:3] offset:128
	s_add_u32 s2, s42, 0x8000
	s_addc_u32 s3, s43, 0
	global_store_dword v180, v118, s[2:3]
	global_store_dword v180, v102, s[2:3] offset:128
	s_add_u32 s2, s42, 0x9000
	s_addc_u32 s3, s43, 0
	global_store_dword v180, v119, s[2:3]
	global_store_dword v180, v103, s[2:3] offset:128
	s_add_u32 s2, s42, 0xa000
	s_addc_u32 s3, s43, 0
	global_store_dword v180, v120, s[2:3]
	global_store_dword v180, v104, s[2:3] offset:128
	s_add_u32 s2, s42, 0xb000
	s_addc_u32 s3, s43, 0
	global_store_dword v180, v121, s[2:3]
	global_store_dword v180, v105, s[2:3] offset:128
	s_add_u32 s2, s42, 0x10000
	s_addc_u32 s3, s43, 0
	global_store_dword v180, v122, s[2:3]
	global_store_dword v180, v106, s[2:3] offset:128
	s_add_u32 s2, s42, 0x11000
	s_addc_u32 s3, s43, 0
	global_store_dword v180, v123, s[2:3]
	global_store_dword v180, v107, s[2:3] offset:128
	s_add_u32 s2, s42, 0x12000
	s_addc_u32 s3, s43, 0
	global_store_dword v180, v124, s[2:3]
	global_store_dword v180, v108, s[2:3] offset:128
	s_add_u32 s2, s42, 0x13000
	s_addc_u32 s3, s43, 0
	global_store_dword v180, v125, s[2:3]
	global_store_dword v180, v109, s[2:3] offset:128
	s_add_u32 s2, s42, 0x18000
	s_addc_u32 s3, s43, 0
	global_store_dword v180, v126, s[2:3]
	global_store_dword v180, v110, s[2:3] offset:128
	s_add_u32 s2, s42, 0x19000
	s_addc_u32 s3, s43, 0
	global_store_dword v180, v127, s[2:3]
	global_store_dword v180, v111, s[2:3] offset:128
	s_add_u32 s2, s42, 0x1a000
	s_addc_u32 s3, s43, 0
	global_store_dword v180, v128, s[2:3]
	global_store_dword v180, v112, s[2:3] offset:128
	s_add_u32 s2, s42, 0x1b000
	s_addc_u32 s3, s43, 0
	global_store_dword v180, v129, s[2:3]
	global_store_dword v180, v113, s[2:3] offset:128
	s_add_u32 s2, s42, 0x20000
	s_addc_u32 s3, s43, 0
	global_store_dword v180, v82, s[2:3]
	global_store_dword v180, v66, s[2:3] offset:128
	s_add_u32 s2, s42, 0x21000
	s_addc_u32 s3, s43, 0
	global_store_dword v180, v83, s[2:3]
	global_store_dword v180, v67, s[2:3] offset:128
	s_add_u32 s2, s42, 0x22000
	s_addc_u32 s3, s43, 0
	global_store_dword v180, v84, s[2:3]
	global_store_dword v180, v68, s[2:3] offset:128
	s_add_u32 s2, s42, 0x23000
	s_addc_u32 s3, s43, 0
	global_store_dword v180, v85, s[2:3]
	global_store_dword v180, v69, s[2:3] offset:128
	s_add_u32 s2, s42, 0x28000
	s_addc_u32 s3, s43, 0
	global_store_dword v180, v86, s[2:3]
	global_store_dword v180, v70, s[2:3] offset:128
	s_add_u32 s2, s42, 0x29000
	s_addc_u32 s3, s43, 0
	global_store_dword v180, v87, s[2:3]
	global_store_dword v180, v71, s[2:3] offset:128
	s_add_u32 s2, s42, 0x2a000
	s_addc_u32 s3, s43, 0
	global_store_dword v180, v88, s[2:3]
	global_store_dword v180, v72, s[2:3] offset:128
	s_add_u32 s2, s42, 0x2b000
	s_addc_u32 s3, s43, 0
	global_store_dword v180, v89, s[2:3]
	global_store_dword v180, v73, s[2:3] offset:128
	s_add_u32 s2, s42, 0x30000
	s_addc_u32 s3, s43, 0
	global_store_dword v180, v90, s[2:3]
	global_store_dword v180, v74, s[2:3] offset:128
	s_add_u32 s2, s42, 0x31000
	s_addc_u32 s3, s43, 0
	global_store_dword v180, v91, s[2:3]
	global_store_dword v180, v75, s[2:3] offset:128
	s_add_u32 s2, s42, 0x32000
	s_addc_u32 s3, s43, 0
	global_store_dword v180, v92, s[2:3]
	global_store_dword v180, v76, s[2:3] offset:128
	s_add_u32 s2, s42, 0x33000
	s_addc_u32 s3, s43, 0
;   __device__ __forceinline__ float* xr() const { return (float*)(ws() + OFF_xr); }
;   __device__ __forceinline__ half_t* u() const { return (half_t*)(ws() + OFF_u); }
; __device__ __forceinline__ void phase_outproj(const KP& p, char* smem, int* q, int xcc) {
;     ...
;         [&](int mi, int ni, int r, int row, int col, float v) {
;           const size_t xi = (size_t)(m0 + row) * DM + n0 + col;
;           ((float*)p.u())[xi] = ALPHA_F * p.xr()[xi] + v;
	global_store_dword v180, v93, s[2:3]
	global_store_dword v180, v77, s[2:3] offset:128
	s_add_u32 s2, s42, 0x38000
	s_addc_u32 s3, s43, 0
	global_store_dword v180, v94, s[2:3]
	global_store_dword v180, v78, s[2:3] offset:128
	s_add_u32 s2, s42, 0x39000
	s_addc_u32 s3, s43, 0
	global_store_dword v180, v95, s[2:3]
	global_store_dword v180, v79, s[2:3] offset:128
	s_add_u32 s2, s42, 0x3a000
	s_addc_u32 s3, s43, 0
	global_store_dword v180, v96, s[2:3]
	global_store_dword v180, v80, s[2:3] offset:128
	s_add_u32 s2, s42, 0x3b000
	s_addc_u32 s3, s43, 0
	global_store_dword v180, v97, s[2:3]
	global_store_dword v180, v81, s[2:3] offset:128
	s_add_u32 s2, s42, 0x40000
	s_addc_u32 s3, s43, 0
	global_store_dword v180, v50, s[2:3]
	global_store_dword v180, v34, s[2:3] offset:128
	s_add_u32 s2, s42, 0x41000
	s_addc_u32 s3, s43, 0
	global_store_dword v180, v51, s[2:3]
	global_store_dword v180, v35, s[2:3] offset:128
	s_add_u32 s2, s42, 0x42000
	s_addc_u32 s3, s43, 0
	global_store_dword v180, v52, s[2:3]
	global_store_dword v180, v36, s[2:3] offset:128
	s_add_u32 s2, s42, 0x43000
	s_addc_u32 s3, s43, 0
	global_store_dword v180, v53, s[2:3]
	global_store_dword v180, v37, s[2:3] offset:128
	s_add_u32 s2, s42, 0x48000
	s_addc_u32 s3, s43, 0
	global_store_dword v180, v54, s[2:3]
	global_store_dword v180, v38, s[2:3] offset:128
	s_add_u32 s2, s42, 0x49000
	s_addc_u32 s3, s43, 0
	global_store_dword v180, v55, s[2:3]
	global_store_dword v180, v39, s[2:3] offset:128
	s_add_u32 s2, s42, 0x4a000
	s_addc_u32 s3, s43, 0
	global_store_dword v180, v56, s[2:3]
	global_store_dword v180, v40, s[2:3] offset:128
	s_add_u32 s2, s42, 0x4b000
	s_addc_u32 s3, s43, 0
	global_store_dword v180, v57, s[2:3]
	global_store_dword v180, v41, s[2:3] offset:128
	s_add_u32 s2, s42, 0x50000
	s_addc_u32 s3, s43, 0
	global_store_dword v180, v58, s[2:3]
	global_store_dword v180, v42, s[2:3] offset:128
	s_add_u32 s2, s42, 0x51000
	s_addc_u32 s3, s43, 0
	global_store_dword v180, v59, s[2:3]
	global_store_dword v180, v43, s[2:3] offset:128
	s_add_u32 s2, s42, 0x52000
	s_addc_u32 s3, s43, 0
	global_store_dword v180, v60, s[2:3]
	global_store_dword v180, v44, s[2:3] offset:128
	s_add_u32 s2, s42, 0x53000
	s_addc_u32 s3, s43, 0
	global_store_dword v180, v61, s[2:3]
	global_store_dword v180, v45, s[2:3] offset:128
	s_add_u32 s2, s42, 0x58000
	s_addc_u32 s3, s43, 0
	global_store_dword v180, v62, s[2:3]
	global_store_dword v180, v46, s[2:3] offset:128
	s_add_u32 s2, s42, 0x59000
	s_addc_u32 s3, s43, 0
	global_store_dword v180, v63, s[2:3]
	global_store_dword v180, v47, s[2:3] offset:128
	s_add_u32 s2, s42, 0x5a000
	s_addc_u32 s3, s43, 0
	global_store_dword v180, v64, s[2:3]
	global_store_dword v180, v48, s[2:3] offset:128
	s_add_u32 s2, s42, 0x5b000
	s_addc_u32 s3, s43, 0
	global_store_dword v180, v65, s[2:3]
	global_store_dword v180, v49, s[2:3] offset:128
	s_add_u32 s2, s42, 0x60000
	s_addc_u32 s3, s43, 0
	global_store_dword v180, v18, s[2:3]
	global_store_dword v180, v2, s[2:3] offset:128
	s_add_u32 s2, s42, 0x61000
	s_addc_u32 s3, s43, 0
	global_store_dword v180, v19, s[2:3]
	global_store_dword v180, v3, s[2:3] offset:128
	s_add_u32 s2, s42, 0x62000
	s_addc_u32 s3, s43, 0
	global_store_dword v180, v20, s[2:3]
	global_store_dword v180, v4, s[2:3] offset:128
	s_add_u32 s2, s42, 0x63000
	s_addc_u32 s3, s43, 0
	global_store_dword v180, v21, s[2:3]
	global_store_dword v180, v5, s[2:3] offset:128
	s_add_u32 s2, s42, 0x68000
	s_addc_u32 s3, s43, 0
	global_store_dword v180, v22, s[2:3]
	global_store_dword v180, v6, s[2:3] offset:128
	s_add_u32 s2, s42, 0x69000
	s_addc_u32 s3, s43, 0
	global_store_dword v180, v23, s[2:3]
	global_store_dword v180, v7, s[2:3] offset:128
	s_add_u32 s2, s42, 0x6a000
	s_addc_u32 s3, s43, 0
	global_store_dword v180, v24, s[2:3]
	global_store_dword v180, v8, s[2:3] offset:128
	s_add_u32 s2, s42, 0x6b000
	s_addc_u32 s3, s43, 0
	global_store_dword v180, v25, s[2:3]
	global_store_dword v180, v9, s[2:3] offset:128
	s_add_u32 s2, s42, 0x70000
	s_addc_u32 s3, s43, 0
	global_store_dword v180, v26, s[2:3]
	global_store_dword v180, v10, s[2:3] offset:128
	s_add_u32 s2, s42, 0x71000
	s_addc_u32 s3, s43, 0
	global_store_dword v180, v27, s[2:3]
	global_store_dword v180, v11, s[2:3] offset:128
	s_add_u32 s2, s42, 0x72000
	s_addc_u32 s3, s43, 0
	global_store_dword v180, v28, s[2:3]
	global_store_dword v180, v12, s[2:3] offset:128
	s_add_u32 s2, s42, 0x73000
	s_addc_u32 s3, s43, 0
	global_store_dword v180, v29, s[2:3]
	global_store_dword v180, v13, s[2:3] offset:128
	s_add_u32 s2, s42, 0x78000
	s_addc_u32 s3, s43, 0
	global_store_dword v180, v30, s[2:3]
	global_store_dword v180, v14, s[2:3] offset:128
	s_add_u32 s2, s42, 0x79000
	s_addc_u32 s3, s43, 0
	global_store_dword v180, v31, s[2:3]
	global_store_dword v180, v15, s[2:3] offset:128
	s_add_u32 s2, s42, 0x7a000
	s_addc_u32 s3, s43, 0
	global_store_dword v180, v32, s[2:3]
	global_store_dword v180, v16, s[2:3] offset:128
	s_add_u32 s2, s42, 0x7b000
	s_addc_u32 s3, s43, 0
	global_store_dword v180, v33, s[2:3]
	global_store_dword v180, v17, s[2:3] offset:128
	s_branch .LBB0_1805
